# GEMM K-loops: LDS-DMA loads use SGPR-base + 32-bit VGPR offset form; 12-16 of 16 per-iteration 64-bit VALU address adds removed (scalar adds instead)
# speedup vs baseline: 1.0040x; 1.0040x over previous
; #define PG8_STAGE(bufoff, gbase, voff) do { _Pragma("unroll") for (int _i = 0; _i < 2; ++_i) \
;         __builtin_amdgcn_global_load_lds((const unsigned*)((const char*)(gbase) + (voff)[_i]), (PG8_LAS unsigned*)(lds + (bufoff) + ldsw + _i * 8192), 16, 0, 0); } while (0)
; #define PG8_LDA(dst, b, h) do { _Pragma("unroll") for (int m = 0; m < 4; ++m) _Pragma("unroll") for (int k = 0; k < 2; ++k) dst[m][k] = *(const PG8_LAS bf16x8*)(lds + PG8_SA(b, h) + aoff + m * 2048 + k * 1024); } while (0)
; #define PG8_LDB(dst, b, h) do { _Pragma("unroll") for (int n = 0; n < 2; ++n) _Pragma("unroll") for (int k = 0; k < 2; ++k) dst[n][k] = *(const PG8_LAS bf16x8*)(lds + PG8_SB(b, h) + boff + n * 2048 + k * 1024); } while (0)
; #define PG8_WAIT_V(n) asm volatile("s_waitcnt vmcnt(" #n ")" ::: "memory")
; #define PG8_WAIT_L(n) asm volatile("s_waitcnt lgkmcnt(" #n ")" ::: "memory")
; #define PG8_BAR __builtin_amdgcn_s_barrier()
; #define PG8_SCHED __builtin_amdgcn_sched_barrier(0)
; template <class Epi, bool ALIGN_EPI = true>
; __device__ __forceinline__ void gemm_phase(PG8_LAS unsigned char* lds, const Gemm g, const StaticOrder& S, const Epi& E) {
;     ...
;             PG8_LDB(B0, 0, 0); PG8_LDB(B1, 0, 1); PG8_SCHED; PG8_LDA(At, 0, 0); PG8_STAGE(PG8_SA(1, 1), a1 + hstepA, voffA);
;             PG8_WAIT_V(8); PG8_WAIT_L(0); PG8_BAR; PG8_MMA(0, 0, At, B0); PG8_MMA(0, 1, At, B1); PG8_BAR; PG8_SCHED;
;             PG8_LDA(At, 0, 1); PG8_STAGE(PG8_SB(0, 0), b2, voffB); PG8_STAGE(PG8_SB(0, 1), b2 + hstepB, voffB); PG8_STAGE(PG8_SA(0, 0), a2, voffA);
;             PG8_WAIT_V(8); PG8_WAIT_L(0); PG8_BAR; PG8_MMA(1, 0, At, B0); PG8_MMA(1, 1, At, B1); PG8_BAR; PG8_SCHED;
.LBB0_439:
	s_add_u32 s28, s8, 0xfffc0080
	s_addc_u32 s29, s9, -1
	s_add_i32 s53, 0, 0x10000
	s_cmp_eq_u32 s52, 12
	s_cselect_b32 s31, s3, s29
	s_cselect_b32 s30, s7, s28
	v_add_u32_e32 v32, s53, v164
	s_cselect_b32 s29, s21, s51
	s_cselect_b32 s28, s23, s50
	s_add_i32 s56, 0, 0x14000
	ds_read_b128 v[142:145], v32
	ds_read_b128 v[148:151], v32 offset:1024
	ds_read_b128 v[158:161], v32 offset:2048
	ds_read_b128 v[168:171], v32 offset:3072
	v_add_u32_e32 v32, s56, v164
	ds_read_b128 v[172:175], v32
	ds_read_b128 v[176:179], v32 offset:1024
	ds_read_b128 v[180:183], v32 offset:2048
	ds_read_b128 v[184:187], v32 offset:3072
	s_add_i32 m0, s41, 0xc000
	ds_read_b128 v[188:191], v166
	ds_read_b128 v[192:195], v166 offset:1024
	ds_read_b128 v[196:199], v166 offset:2048
	ds_read_b128 v[208:211], v166 offset:3072
	ds_read_b128 v[216:219], v166 offset:4096
	ds_read_b128 v[220:223], v166 offset:5120
	ds_read_b128 v[224:227], v166 offset:6144
	ds_read_b128 v[228:231], v166 offset:7168
	global_load_lds_dwordx4 v138, s[8:9]
	s_add_i32 m0, s41, 0xe000
	s_nop 0
	global_load_lds_dwordx4 v140, s[8:9]
	s_waitcnt vmcnt(8)
	s_waitcnt lgkmcnt(0)
	s_barrier
	s_setprio 1
	s_waitcnt lgkmcnt(0)
	v_mfma_f32_16x16x32_bf16 v[126:129], v[142:145], v[188:191], 0
	v_mfma_f32_16x16x32_bf16 v[122:125], v[158:161], v[188:191], 0
	v_mfma_f32_16x16x32_bf16 v[110:113], v[142:145], v[196:199], 0
	v_mfma_f32_16x16x32_bf16 v[106:109], v[158:161], v[196:199], 0
	v_mfma_f32_16x16x32_bf16 v[94:97], v[142:145], v[216:219], 0
	v_mfma_f32_16x16x32_bf16 v[90:93], v[158:161], v[216:219], 0
	v_mfma_f32_16x16x32_bf16 v[78:81], v[142:145], v[224:227], 0
	v_mfma_f32_16x16x32_bf16 v[74:77], v[158:161], v[224:227], 0
	v_mfma_f32_16x16x32_bf16 v[126:129], v[148:151], v[192:195], v[126:129]
	v_mfma_f32_16x16x32_bf16 v[122:125], v[168:171], v[192:195], v[122:125]
	v_mfma_f32_16x16x32_bf16 v[110:113], v[148:151], v[208:211], v[110:113]
	v_mfma_f32_16x16x32_bf16 v[106:109], v[168:171], v[208:211], v[106:109]
	v_mfma_f32_16x16x32_bf16 v[94:97], v[148:151], v[220:223], v[94:97]
	v_mfma_f32_16x16x32_bf16 v[90:93], v[168:171], v[220:223], v[90:93]
	v_mfma_f32_16x16x32_bf16 v[78:81], v[148:151], v[228:231], v[78:81]
	v_mfma_f32_16x16x32_bf16 v[74:77], v[168:171], v[228:231], v[74:77]
	v_mfma_f32_16x16x32_bf16 v[118:121], v[172:175], v[188:191], 0
	v_mfma_f32_16x16x32_bf16 v[114:117], v[180:183], v[188:191], 0
	v_mfma_f32_16x16x32_bf16 v[102:105], v[172:175], v[196:199], 0
	v_mfma_f32_16x16x32_bf16 v[98:101], v[180:183], v[196:199], 0
	v_mfma_f32_16x16x32_bf16 v[86:89], v[172:175], v[216:219], 0
	v_mfma_f32_16x16x32_bf16 v[82:85], v[180:183], v[216:219], 0
	v_mfma_f32_16x16x32_bf16 v[70:73], v[172:175], v[224:227], 0
	v_mfma_f32_16x16x32_bf16 v[66:69], v[180:183], v[224:227], 0
	v_mfma_f32_16x16x32_bf16 v[118:121], v[176:179], v[192:195], v[118:121]
	v_mfma_f32_16x16x32_bf16 v[114:117], v[184:187], v[192:195], v[114:117]
	v_mfma_f32_16x16x32_bf16 v[102:105], v[176:179], v[208:211], v[102:105]
	v_mfma_f32_16x16x32_bf16 v[98:101], v[184:187], v[208:211], v[98:101]
	v_mfma_f32_16x16x32_bf16 v[86:89], v[176:179], v[220:223], v[86:89]
	v_mfma_f32_16x16x32_bf16 v[82:85], v[184:187], v[220:223], v[82:85]
	v_mfma_f32_16x16x32_bf16 v[70:73], v[176:179], v[228:231], v[70:73]
	v_mfma_f32_16x16x32_bf16 v[66:69], v[184:187], v[228:231], v[66:69]
	s_setprio 0
	s_barrier
	s_add_i32 s53, s53, s40
	s_mov_b32 m0, s53
	ds_read_b128 v[188:191], v166 offset:16384
	ds_read_b128 v[192:195], v166 offset:17408
	ds_read_b128 v[196:199], v166 offset:18432
	ds_read_b128 v[208:211], v166 offset:19456
	ds_read_b128 v[216:219], v166 offset:20480
	ds_read_b128 v[220:223], v166 offset:21504
	ds_read_b128 v[224:227], v166 offset:22528
	ds_read_b128 v[228:231], v166 offset:23552
	global_load_lds_dwordx4 v132, s[28:29]
	s_add_i32 m0, s53, 0x2000
	s_add_u32 s58, s28, 0x40000
	s_addc_u32 s59, s29, 0
	s_add_i32 s53, s56, s40
	global_load_lds_dwordx4 v136, s[28:29]
	s_mov_b32 m0, s53
	v_lshl_add_u64 v[206:207], s[30:31], 0, v[134:135]
	global_load_lds_dwordx4 v132, s[58:59]
	s_add_i32 m0, s53, 0x2000
	s_nop 0
	global_load_lds_dwordx4 v136, s[58:59]
	v_lshl_add_u64 v[204:205], s[30:31], 0, v[130:131]
	s_mov_b32 m0, s41
	s_nop 0
	global_load_lds_dwordx4 v130, s[30:31]
	s_mov_b32 m0, s42
	s_nop 0
	global_load_lds_dwordx4 v134, s[30:31]
	s_waitcnt vmcnt(8)
	s_waitcnt lgkmcnt(0)
	s_barrier
	s_setprio 1
	s_waitcnt lgkmcnt(0)
	v_mfma_f32_16x16x32_bf16 v[62:65], v[142:145], v[188:191], 0
	v_mfma_f32_16x16x32_bf16 v[58:61], v[158:161], v[188:191], 0
	v_mfma_f32_16x16x32_bf16 v[46:49], v[142:145], v[196:199], 0
	v_mfma_f32_16x16x32_bf16 v[42:45], v[158:161], v[196:199], 0
	v_mfma_f32_16x16x32_bf16 v[28:31], v[142:145], v[216:219], 0
	v_mfma_f32_16x16x32_bf16 v[24:27], v[158:161], v[216:219], 0
	v_mfma_f32_16x16x32_bf16 v[12:15], v[142:145], v[224:227], 0
	v_mfma_f32_16x16x32_bf16 v[8:11], v[158:161], v[224:227], 0
	v_mfma_f32_16x16x32_bf16 v[62:65], v[148:151], v[192:195], v[62:65]
	v_mfma_f32_16x16x32_bf16 v[58:61], v[168:171], v[192:195], v[58:61]
	v_mfma_f32_16x16x32_bf16 v[46:49], v[148:151], v[208:211], v[46:49]
	v_mfma_f32_16x16x32_bf16 v[42:45], v[168:171], v[208:211], v[42:45]
	v_mfma_f32_16x16x32_bf16 v[28:31], v[148:151], v[220:223], v[28:31]
	v_mfma_f32_16x16x32_bf16 v[24:27], v[168:171], v[220:223], v[24:27]
	v_mfma_f32_16x16x32_bf16 v[12:15], v[148:151], v[228:231], v[12:15]
	v_mfma_f32_16x16x32_bf16 v[8:11], v[168:171], v[228:231], v[8:11]
	v_mfma_f32_16x16x32_bf16 v[54:57], v[172:175], v[188:191], 0
	v_mfma_f32_16x16x32_bf16 v[50:53], v[180:183], v[188:191], 0
	v_mfma_f32_16x16x32_bf16 v[38:41], v[172:175], v[196:199], 0
	v_mfma_f32_16x16x32_bf16 v[34:37], v[180:183], v[196:199], 0
	v_mfma_f32_16x16x32_bf16 v[20:23], v[172:175], v[216:219], 0
	v_mfma_f32_16x16x32_bf16 v[16:19], v[180:183], v[216:219], 0
	v_mfma_f32_16x16x32_bf16 v[4:7], v[172:175], v[224:227], 0
	v_mfma_f32_16x16x32_bf16 v[0:3], v[180:183], v[224:227], 0
	v_mfma_f32_16x16x32_bf16 v[54:57], v[176:179], v[192:195], v[54:57]
	v_mfma_f32_16x16x32_bf16 v[50:53], v[184:187], v[192:195], v[50:53]
	v_mfma_f32_16x16x32_bf16 v[38:41], v[176:179], v[208:211], v[38:41]
	v_mfma_f32_16x16x32_bf16 v[34:37], v[184:187], v[208:211], v[34:37]
	v_mfma_f32_16x16x32_bf16 v[20:23], v[176:179], v[220:223], v[20:23]
	v_mfma_f32_16x16x32_bf16 v[16:19], v[184:187], v[220:223], v[16:19]
	v_mfma_f32_16x16x32_bf16 v[4:7], v[176:179], v[228:231], v[4:7]
	v_mfma_f32_16x16x32_bf16 v[0:3], v[184:187], v[228:231], v[0:3]
	s_setprio 0
	s_barrier
	s_branch .Lp3_439
; #define PG8_STAGE(bufoff, gbase, voff) do { _Pragma("unroll") for (int _i = 0; _i < 2; ++_i) \
;         __builtin_amdgcn_global_load_lds((const unsigned*)((const char*)(gbase) + (voff)[_i]), (PG8_LAS unsigned*)(lds + (bufoff) + ldsw + _i * 8192), 16, 0, 0); } while (0)
; #define PG8_LDA(dst, b, h) do { _Pragma("unroll") for (int m = 0; m < 4; ++m) _Pragma("unroll") for (int k = 0; k < 2; ++k) dst[m][k] = *(const PG8_LAS bf16x8*)(lds + PG8_SA(b, h) + aoff + m * 2048 + k * 1024); } while (0)
; #define PG8_LDB(dst, b, h) do { _Pragma("unroll") for (int n = 0; n < 2; ++n) _Pragma("unroll") for (int k = 0; k < 2; ++k) dst[n][k] = *(const PG8_LAS bf16x8*)(lds + PG8_SB(b, h) + boff + n * 2048 + k * 1024); } while (0)
; #define PG8_WAIT_V(n) asm volatile("s_waitcnt vmcnt(" #n ")" ::: "memory")
; #define PG8_WAIT_L(n) asm volatile("s_waitcnt lgkmcnt(" #n ")" ::: "memory")
; #define PG8_BAR __builtin_amdgcn_s_barrier()
; #define PG8_SCHED __builtin_amdgcn_sched_barrier(0)
; template <class Epi, bool ALIGN_EPI = true>
; __device__ __forceinline__ void gemm_phase(PG8_LAS unsigned char* lds, const Gemm g, const StaticOrder& S, const Epi& E) {
;     ...
;             PG8_LDB(B0, 0, 0); PG8_LDB(B1, 0, 1); PG8_SCHED; PG8_LDA(At, 0, 0); PG8_STAGE(PG8_SA(1, 1), a1 + hstepA, voffA);
;             PG8_WAIT_V(8); PG8_WAIT_L(0); PG8_BAR; PG8_MMA(0, 0, At, B0); PG8_MMA(0, 1, At, B1); PG8_BAR; PG8_SCHED;
;             PG8_LDA(At, 0, 1); PG8_STAGE(PG8_SB(0, 0), b2, voffB); PG8_STAGE(PG8_SB(0, 1), b2 + hstepB, voffB); PG8_STAGE(PG8_SA(0, 0), a2, voffA);
;             PG8_WAIT_V(8); PG8_WAIT_L(0); PG8_BAR; PG8_MMA(1, 0, At, B0); PG8_MMA(1, 1, At, B1); PG8_BAR; PG8_SCHED;
.Lrot_439:
	ds_read_b128 v[142:145], v32
	ds_read_b128 v[148:151], v32 offset:1024
	ds_read_b128 v[158:161], v32 offset:2048
	ds_read_b128 v[168:171], v32 offset:3072
	v_add_u32_e32 v32, s56, v164
	ds_read_b128 v[172:175], v32
	ds_read_b128 v[176:179], v32 offset:1024
	ds_read_b128 v[180:183], v32 offset:2048
	ds_read_b128 v[184:187], v32 offset:3072
	s_add_i32 m0, s41, 0xc000
	ds_read_b128 v[188:191], v166
	ds_read_b128 v[192:195], v166 offset:1024
	ds_read_b128 v[196:199], v166 offset:2048
	ds_read_b128 v[208:211], v166 offset:3072
	ds_read_b128 v[216:219], v166 offset:4096
	ds_read_b128 v[220:223], v166 offset:5120
	ds_read_b128 v[224:227], v166 offset:6144
	ds_read_b128 v[228:231], v166 offset:7168
	global_load_lds_dwordx4 v138, s[8:9]
	s_add_i32 m0, s41, 0xe000
	s_nop 0
	global_load_lds_dwordx4 v140, s[8:9]
	s_waitcnt vmcnt(8)
	s_waitcnt lgkmcnt(0)
	s_barrier
	s_setprio 1
	s_waitcnt lgkmcnt(0)
	v_mfma_f32_16x16x32_bf16 v[126:129], v[142:145], v[188:191], v[126:129]
	v_mfma_f32_16x16x32_bf16 v[122:125], v[158:161], v[188:191], v[122:125]
	v_mfma_f32_16x16x32_bf16 v[110:113], v[142:145], v[196:199], v[110:113]
	v_mfma_f32_16x16x32_bf16 v[106:109], v[158:161], v[196:199], v[106:109]
	v_mfma_f32_16x16x32_bf16 v[94:97], v[142:145], v[216:219], v[94:97]
	v_mfma_f32_16x16x32_bf16 v[90:93], v[158:161], v[216:219], v[90:93]
	v_mfma_f32_16x16x32_bf16 v[78:81], v[142:145], v[224:227], v[78:81]
	v_mfma_f32_16x16x32_bf16 v[74:77], v[158:161], v[224:227], v[74:77]
	v_mfma_f32_16x16x32_bf16 v[126:129], v[148:151], v[192:195], v[126:129]
	v_mfma_f32_16x16x32_bf16 v[122:125], v[168:171], v[192:195], v[122:125]
	v_mfma_f32_16x16x32_bf16 v[110:113], v[148:151], v[208:211], v[110:113]
	v_mfma_f32_16x16x32_bf16 v[106:109], v[168:171], v[208:211], v[106:109]
	v_mfma_f32_16x16x32_bf16 v[94:97], v[148:151], v[220:223], v[94:97]
	v_mfma_f32_16x16x32_bf16 v[90:93], v[168:171], v[220:223], v[90:93]
	v_mfma_f32_16x16x32_bf16 v[78:81], v[148:151], v[228:231], v[78:81]
	v_mfma_f32_16x16x32_bf16 v[74:77], v[168:171], v[228:231], v[74:77]
	v_mfma_f32_16x16x32_bf16 v[118:121], v[172:175], v[188:191], v[118:121]
	v_mfma_f32_16x16x32_bf16 v[114:117], v[180:183], v[188:191], v[114:117]
	v_mfma_f32_16x16x32_bf16 v[102:105], v[172:175], v[196:199], v[102:105]
	v_mfma_f32_16x16x32_bf16 v[98:101], v[180:183], v[196:199], v[98:101]
	v_mfma_f32_16x16x32_bf16 v[86:89], v[172:175], v[216:219], v[86:89]
	v_mfma_f32_16x16x32_bf16 v[82:85], v[180:183], v[216:219], v[82:85]
	v_mfma_f32_16x16x32_bf16 v[70:73], v[172:175], v[224:227], v[70:73]
	v_mfma_f32_16x16x32_bf16 v[66:69], v[180:183], v[224:227], v[66:69]
	v_mfma_f32_16x16x32_bf16 v[118:121], v[176:179], v[192:195], v[118:121]
	v_mfma_f32_16x16x32_bf16 v[114:117], v[184:187], v[192:195], v[114:117]
	v_mfma_f32_16x16x32_bf16 v[102:105], v[176:179], v[208:211], v[102:105]
	v_mfma_f32_16x16x32_bf16 v[98:101], v[184:187], v[208:211], v[98:101]
	v_mfma_f32_16x16x32_bf16 v[86:89], v[176:179], v[220:223], v[86:89]
	v_mfma_f32_16x16x32_bf16 v[82:85], v[184:187], v[220:223], v[82:85]
	v_mfma_f32_16x16x32_bf16 v[70:73], v[176:179], v[228:231], v[70:73]
	v_mfma_f32_16x16x32_bf16 v[66:69], v[184:187], v[228:231], v[66:69]
	s_setprio 0
	s_barrier
	s_add_i32 s53, s53, s40
	s_mov_b32 m0, s53
	ds_read_b128 v[188:191], v166 offset:16384
	ds_read_b128 v[192:195], v166 offset:17408
	ds_read_b128 v[196:199], v166 offset:18432
	ds_read_b128 v[208:211], v166 offset:19456
	ds_read_b128 v[216:219], v166 offset:20480
	ds_read_b128 v[220:223], v166 offset:21504
	ds_read_b128 v[224:227], v166 offset:22528
	ds_read_b128 v[228:231], v166 offset:23552
	global_load_lds_dwordx4 v132, s[28:29]
	s_add_i32 m0, s53, 0x2000
	s_add_u32 s58, s28, 0x40000
	s_addc_u32 s59, s29, 0
	s_add_i32 s53, s56, s40
	global_load_lds_dwordx4 v136, s[28:29]
	s_mov_b32 m0, s53
	v_lshl_add_u64 v[206:207], s[30:31], 0, v[134:135]
	global_load_lds_dwordx4 v132, s[58:59]
	s_add_i32 m0, s53, 0x2000
	s_nop 0
	global_load_lds_dwordx4 v136, s[58:59]
	v_lshl_add_u64 v[204:205], s[30:31], 0, v[130:131]
	s_mov_b32 m0, s41
	s_nop 0
	global_load_lds_dwordx4 v130, s[30:31]
	s_mov_b32 m0, s42
	s_nop 0
	global_load_lds_dwordx4 v134, s[30:31]
	s_waitcnt vmcnt(8)
	s_waitcnt lgkmcnt(0)
	s_barrier
	s_setprio 1
	s_waitcnt lgkmcnt(0)
	v_mfma_f32_16x16x32_bf16 v[62:65], v[142:145], v[188:191], v[62:65]
	v_mfma_f32_16x16x32_bf16 v[58:61], v[158:161], v[188:191], v[58:61]
	v_mfma_f32_16x16x32_bf16 v[46:49], v[142:145], v[196:199], v[46:49]
	v_mfma_f32_16x16x32_bf16 v[42:45], v[158:161], v[196:199], v[42:45]
	v_mfma_f32_16x16x32_bf16 v[28:31], v[142:145], v[216:219], v[28:31]
	v_mfma_f32_16x16x32_bf16 v[24:27], v[158:161], v[216:219], v[24:27]
	v_mfma_f32_16x16x32_bf16 v[12:15], v[142:145], v[224:227], v[12:15]
	v_mfma_f32_16x16x32_bf16 v[8:11], v[158:161], v[224:227], v[8:11]
	v_mfma_f32_16x16x32_bf16 v[62:65], v[148:151], v[192:195], v[62:65]
	v_mfma_f32_16x16x32_bf16 v[58:61], v[168:171], v[192:195], v[58:61]
	v_mfma_f32_16x16x32_bf16 v[46:49], v[148:151], v[208:211], v[46:49]
	v_mfma_f32_16x16x32_bf16 v[42:45], v[168:171], v[208:211], v[42:45]
	v_mfma_f32_16x16x32_bf16 v[28:31], v[148:151], v[220:223], v[28:31]
	v_mfma_f32_16x16x32_bf16 v[24:27], v[168:171], v[220:223], v[24:27]
	v_mfma_f32_16x16x32_bf16 v[12:15], v[148:151], v[228:231], v[12:15]
	v_mfma_f32_16x16x32_bf16 v[8:11], v[168:171], v[228:231], v[8:11]
	v_mfma_f32_16x16x32_bf16 v[54:57], v[172:175], v[188:191], v[54:57]
	v_mfma_f32_16x16x32_bf16 v[50:53], v[180:183], v[188:191], v[50:53]
	v_mfma_f32_16x16x32_bf16 v[38:41], v[172:175], v[196:199], v[38:41]
	v_mfma_f32_16x16x32_bf16 v[34:37], v[180:183], v[196:199], v[34:37]
	v_mfma_f32_16x16x32_bf16 v[20:23], v[172:175], v[216:219], v[20:23]
	v_mfma_f32_16x16x32_bf16 v[16:19], v[180:183], v[216:219], v[16:19]
	v_mfma_f32_16x16x32_bf16 v[4:7], v[172:175], v[224:227], v[4:7]
	v_mfma_f32_16x16x32_bf16 v[0:3], v[180:183], v[224:227], v[0:3]
	v_mfma_f32_16x16x32_bf16 v[54:57], v[176:179], v[192:195], v[54:57]
	v_mfma_f32_16x16x32_bf16 v[50:53], v[184:187], v[192:195], v[50:53]
	v_mfma_f32_16x16x32_bf16 v[38:41], v[176:179], v[208:211], v[38:41]
	v_mfma_f32_16x16x32_bf16 v[34:37], v[184:187], v[208:211], v[34:37]
	v_mfma_f32_16x16x32_bf16 v[20:23], v[176:179], v[220:223], v[20:23]
	v_mfma_f32_16x16x32_bf16 v[16:19], v[184:187], v[220:223], v[16:19]
	v_mfma_f32_16x16x32_bf16 v[4:7], v[176:179], v[228:231], v[4:7]
	v_mfma_f32_16x16x32_bf16 v[0:3], v[184:187], v[228:231], v[0:3]
	s_setprio 0
	s_barrier
; #define PG8_STAGE(bufoff, gbase, voff) do { _Pragma("unroll") for (int _i = 0; _i < 2; ++_i) \
;         __builtin_amdgcn_global_load_lds((const unsigned*)((const char*)(gbase) + (voff)[_i]), (PG8_LAS unsigned*)(lds + (bufoff) + ldsw + _i * 8192), 16, 0, 0); } while (0)
; #define PG8_LDA(dst, b, h) do { _Pragma("unroll") for (int m = 0; m < 4; ++m) _Pragma("unroll") for (int k = 0; k < 2; ++k) dst[m][k] = *(const PG8_LAS bf16x8*)(lds + PG8_SA(b, h) + aoff + m * 2048 + k * 1024); } while (0)
; #define PG8_LDB(dst, b, h) do { _Pragma("unroll") for (int n = 0; n < 2; ++n) _Pragma("unroll") for (int k = 0; k < 2; ++k) dst[n][k] = *(const PG8_LAS bf16x8*)(lds + PG8_SB(b, h) + boff + n * 2048 + k * 1024); } while (0)
; #define PG8_WAIT_V(n) asm volatile("s_waitcnt vmcnt(" #n ")" ::: "memory")
; #define PG8_WAIT_L(n) asm volatile("s_waitcnt lgkmcnt(" #n ")" ::: "memory")
; #define PG8_BAR __builtin_amdgcn_s_barrier()
; #define PG8_SCHED __builtin_amdgcn_sched_barrier(0)
; template <class Epi, bool ALIGN_EPI = true>
; __device__ __forceinline__ void gemm_phase(PG8_LAS unsigned char* lds, const Gemm g, const StaticOrder& S, const Epi& E) {
;     ...
;             PG8_LDB(B0, 1, 0); PG8_LDB(B1, 1, 1); PG8_SCHED; PG8_LDA(At, 1, 0); PG8_STAGE(PG8_SA(0, 1), a2 + hstepA, voffA);
;             PG8_WAIT_V(8); PG8_WAIT_L(0); PG8_BAR; PG8_MMA(0, 0, At, B0); PG8_MMA(0, 1, At, B1); PG8_BAR; PG8_SCHED;
.Lp3_439:
	s_add_i32 s53, 0, 0x18000
	v_add_u32_e32 v32, s53, v164
	s_add_i32 s56, 0, 0x1c000
	ds_read_b128 v[142:145], v32
	ds_read_b128 v[148:151], v32 offset:1024
	ds_read_b128 v[158:161], v32 offset:2048
	ds_read_b128 v[168:171], v32 offset:3072
	v_add_u32_e32 v32, s56, v164
	ds_read_b128 v[172:175], v32
	ds_read_b128 v[176:179], v32 offset:1024
	ds_read_b128 v[180:183], v32 offset:2048
	ds_read_b128 v[184:187], v32 offset:3072
	s_add_u32 s30, s30, 0x40000
	s_addc_u32 s31, s31, 0
	s_mov_b32 m0, s43
	ds_read_b128 v[188:191], v166 offset:32768
	ds_read_b128 v[192:195], v166 offset:33792
	ds_read_b128 v[196:199], v166 offset:34816
	ds_read_b128 v[208:211], v166 offset:35840
	ds_read_b128 v[216:219], v166 offset:36864
	ds_read_b128 v[220:223], v166 offset:37888
	ds_read_b128 v[224:227], v166 offset:38912
	ds_read_b128 v[228:231], v166 offset:39936
	global_load_lds_dwordx4 v130, s[30:31]
	s_mov_b32 m0, s44
	s_nop 0
	global_load_lds_dwordx4 v134, s[30:31]
	s_waitcnt vmcnt(8)
	s_waitcnt lgkmcnt(0)
	s_barrier
	s_setprio 1
	s_waitcnt lgkmcnt(0)
	v_mfma_f32_16x16x32_bf16 v[126:129], v[142:145], v[188:191], v[126:129]
	v_mfma_f32_16x16x32_bf16 v[122:125], v[158:161], v[188:191], v[122:125]
	v_mfma_f32_16x16x32_bf16 v[110:113], v[142:145], v[196:199], v[110:113]
	v_mfma_f32_16x16x32_bf16 v[106:109], v[158:161], v[196:199], v[106:109]
	v_mfma_f32_16x16x32_bf16 v[94:97], v[142:145], v[216:219], v[94:97]
	v_mfma_f32_16x16x32_bf16 v[90:93], v[158:161], v[216:219], v[90:93]
	v_mfma_f32_16x16x32_bf16 v[78:81], v[142:145], v[224:227], v[78:81]
	v_mfma_f32_16x16x32_bf16 v[74:77], v[158:161], v[224:227], v[74:77]
	v_mfma_f32_16x16x32_bf16 v[126:129], v[148:151], v[192:195], v[126:129]
	v_mfma_f32_16x16x32_bf16 v[122:125], v[168:171], v[192:195], v[122:125]
	v_mfma_f32_16x16x32_bf16 v[110:113], v[148:151], v[208:211], v[110:113]
	v_mfma_f32_16x16x32_bf16 v[106:109], v[168:171], v[208:211], v[106:109]
	v_mfma_f32_16x16x32_bf16 v[94:97], v[148:151], v[220:223], v[94:97]
	v_mfma_f32_16x16x32_bf16 v[90:93], v[168:171], v[220:223], v[90:93]
	v_mfma_f32_16x16x32_bf16 v[78:81], v[148:151], v[228:231], v[78:81]
	v_mfma_f32_16x16x32_bf16 v[74:77], v[168:171], v[228:231], v[74:77]
	v_mfma_f32_16x16x32_bf16 v[118:121], v[172:175], v[188:191], v[118:121]
	v_mfma_f32_16x16x32_bf16 v[114:117], v[180:183], v[188:191], v[114:117]
	v_mfma_f32_16x16x32_bf16 v[102:105], v[172:175], v[196:199], v[102:105]
	v_mfma_f32_16x16x32_bf16 v[98:101], v[180:183], v[196:199], v[98:101]
	v_mfma_f32_16x16x32_bf16 v[86:89], v[172:175], v[216:219], v[86:89]
	v_mfma_f32_16x16x32_bf16 v[82:85], v[180:183], v[216:219], v[82:85]
	v_mfma_f32_16x16x32_bf16 v[70:73], v[172:175], v[224:227], v[70:73]
	v_mfma_f32_16x16x32_bf16 v[66:69], v[180:183], v[224:227], v[66:69]
	v_mfma_f32_16x16x32_bf16 v[118:121], v[176:179], v[192:195], v[118:121]
	v_mfma_f32_16x16x32_bf16 v[114:117], v[184:187], v[192:195], v[114:117]
	v_mfma_f32_16x16x32_bf16 v[102:105], v[176:179], v[208:211], v[102:105]
	v_mfma_f32_16x16x32_bf16 v[98:101], v[184:187], v[208:211], v[98:101]
	v_mfma_f32_16x16x32_bf16 v[86:89], v[176:179], v[220:223], v[86:89]
	v_mfma_f32_16x16x32_bf16 v[82:85], v[184:187], v[220:223], v[82:85]
	v_mfma_f32_16x16x32_bf16 v[70:73], v[176:179], v[228:231], v[70:73]
	v_mfma_f32_16x16x32_bf16 v[66:69], v[184:187], v[228:231], v[66:69]
	s_setprio 0
	s_barrier
; #define PG8_STAGE(bufoff, gbase, voff) do { _Pragma("unroll") for (int _i = 0; _i < 2; ++_i) \
;         __builtin_amdgcn_global_load_lds((const unsigned*)((const char*)(gbase) + (voff)[_i]), (PG8_LAS unsigned*)(lds + (bufoff) + ldsw + _i * 8192), 16, 0, 0); } while (0)
; #define PG8_LDA(dst, b, h) do { _Pragma("unroll") for (int m = 0; m < 4; ++m) _Pragma("unroll") for (int k = 0; k < 2; ++k) dst[m][k] = *(const PG8_LAS bf16x8*)(lds + PG8_SA(b, h) + aoff + m * 2048 + k * 1024); } while (0)
; #define PG8_WAIT_V(n) asm volatile("s_waitcnt vmcnt(" #n ")" ::: "memory")
; #define PG8_WAIT_L(n) asm volatile("s_waitcnt lgkmcnt(" #n ")" ::: "memory")
; #define PG8_BAR __builtin_amdgcn_s_barrier()
; #define PG8_SCHED __builtin_amdgcn_sched_barrier(0)
; template <class Epi, bool ALIGN_EPI = true>
; __device__ __forceinline__ void gemm_phase(PG8_LAS unsigned char* lds, const Gemm g, const StaticOrder& S, const Epi& E) {
;     ...
;         for (int t = 0; t < nt; t += 2) {
;             const bool last = (t == nt - 2);
;             const char* a1 = cA + (size_t)(t + 1) * kstep;
;             const char* a2 = last ? nA : cA + (size_t)(t + 2) * kstep; const char* b2 = last ? nB : cB + (size_t)(t + 2) * kstep;
;     ...
;             PG8_LDA(At, 1, 1); PG8_STAGE(PG8_SB(1, 0), b3, voffB); PG8_STAGE(PG8_SB(1, 1), b3 + hstepB, voffB); PG8_STAGE(PG8_SA(1, 0), a3, voffA);
;             PG8_WAIT_V(8); PG8_WAIT_L(0); PG8_BAR; PG8_MMA(1, 0, At, B0); PG8_MMA(1, 1, At, B1); PG8_BAR; PG8_SCHED;
	s_add_i32 s30, s53, s40
	s_mov_b32 m0, s30
	ds_read_b128 v[188:191], v166 offset:49152
	ds_read_b128 v[192:195], v166 offset:50176
	ds_read_b128 v[196:199], v166 offset:51200
	ds_read_b128 v[208:211], v166 offset:52224
	ds_read_b128 v[216:219], v166 offset:53248
	ds_read_b128 v[220:223], v166 offset:54272
	ds_read_b128 v[224:227], v166 offset:55296
	ds_read_b128 v[228:231], v166 offset:56320
	s_add_u32 s98, s28, s60
	s_addc_u32 s99, s29, s61
	global_load_lds_dwordx4 v132, s[98:99]
	s_add_i32 m0, s30, 0x2000
	s_add_u32 s28, s28, 0x40080
	s_addc_u32 s29, s29, 0
	s_add_i32 s30, s56, s40
	s_add_u32 s98, s28, s60
	s_addc_u32 s99, s29, s61
	s_add_u32 s98, s98, 0xfffbff80
	s_addc_u32 s99, s99, -1
	global_load_lds_dwordx4 v136, s[98:99]
	s_mov_b32 m0, s30
	s_nop 0
	global_load_lds_dwordx4 v132, s[28:29]
	s_add_i32 m0, s30, 0x2000
	s_nop 0
	global_load_lds_dwordx4 v136, s[28:29]
	v_lshl_add_u64 v[146:147], v[204:205], 0, s[60:61]
	s_mov_b32 m0, s45
	s_nop 0
	global_load_lds_dwordx4 v[146:147], off
	v_lshl_add_u64 v[146:147], v[206:207], 0, s[60:61]
	s_mov_b32 m0, s46
	s_nop 0
	global_load_lds_dwordx4 v[146:147], off
	s_add_i32 s52, s52, 2
	s_add_u32 s8, s8, 0x100
	s_addc_u32 s9, s9, 0
	s_add_u32 s50, s50, 0x100
	s_addc_u32 s51, s51, 0
	s_add_u32 s28, s8, 0xfffc0080
	s_addc_u32 s29, s9, -1
	s_add_i32 s53, 0, 0x10000
	s_cmp_eq_u32 s52, 12
	s_cselect_b32 s31, s3, s29
	s_cselect_b32 s30, s7, s28
	v_add_u32_e32 v32, s53, v164
	s_cselect_b32 s29, s21, s51
	s_cselect_b32 s28, s23, s50
	s_add_i32 s56, 0, 0x14000
	s_cmp_gt_u32 s52, 13
	s_waitcnt vmcnt(8)
	s_waitcnt lgkmcnt(0)
	s_barrier
	s_setprio 1
	s_waitcnt lgkmcnt(0)
	v_mfma_f32_16x16x32_bf16 v[62:65], v[142:145], v[188:191], v[62:65]
	v_mfma_f32_16x16x32_bf16 v[58:61], v[158:161], v[188:191], v[58:61]
	v_mfma_f32_16x16x32_bf16 v[46:49], v[142:145], v[196:199], v[46:49]
	v_mfma_f32_16x16x32_bf16 v[42:45], v[158:161], v[196:199], v[42:45]
	v_mfma_f32_16x16x32_bf16 v[28:31], v[142:145], v[216:219], v[28:31]
	v_mfma_f32_16x16x32_bf16 v[24:27], v[158:161], v[216:219], v[24:27]
	v_mfma_f32_16x16x32_bf16 v[12:15], v[142:145], v[224:227], v[12:15]
	v_mfma_f32_16x16x32_bf16 v[8:11], v[158:161], v[224:227], v[8:11]
	v_mfma_f32_16x16x32_bf16 v[62:65], v[148:151], v[192:195], v[62:65]
	v_mfma_f32_16x16x32_bf16 v[58:61], v[168:171], v[192:195], v[58:61]
	v_mfma_f32_16x16x32_bf16 v[46:49], v[148:151], v[208:211], v[46:49]
	v_mfma_f32_16x16x32_bf16 v[42:45], v[168:171], v[208:211], v[42:45]
	v_mfma_f32_16x16x32_bf16 v[28:31], v[148:151], v[220:223], v[28:31]
	v_mfma_f32_16x16x32_bf16 v[24:27], v[168:171], v[220:223], v[24:27]
	v_mfma_f32_16x16x32_bf16 v[12:15], v[148:151], v[228:231], v[12:15]
	v_mfma_f32_16x16x32_bf16 v[8:11], v[168:171], v[228:231], v[8:11]
	v_mfma_f32_16x16x32_bf16 v[54:57], v[172:175], v[188:191], v[54:57]
	v_mfma_f32_16x16x32_bf16 v[50:53], v[180:183], v[188:191], v[50:53]
	v_mfma_f32_16x16x32_bf16 v[38:41], v[172:175], v[196:199], v[38:41]
	v_mfma_f32_16x16x32_bf16 v[34:37], v[180:183], v[196:199], v[34:37]
	v_mfma_f32_16x16x32_bf16 v[20:23], v[172:175], v[216:219], v[20:23]
	v_mfma_f32_16x16x32_bf16 v[16:19], v[180:183], v[216:219], v[16:19]
	v_mfma_f32_16x16x32_bf16 v[4:7], v[172:175], v[224:227], v[4:7]
	v_mfma_f32_16x16x32_bf16 v[0:3], v[180:183], v[224:227], v[0:3]
	v_mfma_f32_16x16x32_bf16 v[54:57], v[176:179], v[192:195], v[54:57]
	v_mfma_f32_16x16x32_bf16 v[50:53], v[184:187], v[192:195], v[50:53]
	v_mfma_f32_16x16x32_bf16 v[38:41], v[176:179], v[208:211], v[38:41]
	v_mfma_f32_16x16x32_bf16 v[34:37], v[184:187], v[208:211], v[34:37]
	v_mfma_f32_16x16x32_bf16 v[20:23], v[176:179], v[220:223], v[20:23]
	v_mfma_f32_16x16x32_bf16 v[16:19], v[184:187], v[220:223], v[16:19]
	v_mfma_f32_16x16x32_bf16 v[4:7], v[176:179], v[228:231], v[4:7]
	v_mfma_f32_16x16x32_bf16 v[0:3], v[184:187], v[228:231], v[0:3]
	s_setprio 0
	s_barrier
	s_cbranch_scc0 .Lrot_439
	s_and_b64 vcc, exec, s[18:19]
	s_cbranch_vccz .LBB0_442
	s_barrier

; #define PG8_STAGE(bufoff, gbase, voff) do { _Pragma("unroll") for (int _i = 0; _i < 2; ++_i) \
;         __builtin_amdgcn_global_load_lds((const unsigned*)((const char*)(gbase) + (voff)[_i]), (PG8_LAS unsigned*)(lds + (bufoff) + ldsw + _i * 8192), 16, 0, 0); } while (0)
; #define PG8_LDA(dst, b, h) do { _Pragma("unroll") for (int m = 0; m < 4; ++m) _Pragma("unroll") for (int k = 0; k < 2; ++k) dst[m][k] = *(const PG8_LAS bf16x8*)(lds + PG8_SA(b, h) + aoff + m * 2048 + k * 1024); } while (0)
; #define PG8_LDB(dst, b, h) do { _Pragma("unroll") for (int n = 0; n < 2; ++n) _Pragma("unroll") for (int k = 0; k < 2; ++k) dst[n][k] = *(const PG8_LAS bf16x8*)(lds + PG8_SB(b, h) + boff + n * 2048 + k * 1024); } while (0)
; #define PG8_WAIT_V(n) asm volatile("s_waitcnt vmcnt(" #n ")" ::: "memory")
; #define PG8_WAIT_L(n) asm volatile("s_waitcnt lgkmcnt(" #n ")" ::: "memory")
; #define PG8_BAR __builtin_amdgcn_s_barrier()
; #define PG8_SCHED __builtin_amdgcn_sched_barrier(0)
; template <class Epi, bool ALIGN_EPI = true>
; __device__ __forceinline__ void gemm_phase(PG8_LAS unsigned char* lds, const Gemm g, const StaticOrder& S, const Epi& E) {
;     ...
;             PG8_LDB(B0, 0, 0); PG8_LDB(B1, 0, 1); PG8_SCHED; PG8_LDA(At, 0, 0); PG8_STAGE(PG8_SA(1, 1), a1 + hstepA, voffA);
;             PG8_WAIT_V(8); PG8_WAIT_L(0); PG8_BAR; PG8_MMA(0, 0, At, B0); PG8_MMA(0, 1, At, B1); PG8_BAR; PG8_SCHED;
;             PG8_LDA(At, 0, 1); PG8_STAGE(PG8_SB(0, 0), b2, voffB); PG8_STAGE(PG8_SB(0, 1), b2 + hstepB, voffB); PG8_STAGE(PG8_SA(0, 0), a2, voffA);
;             PG8_WAIT_V(8); PG8_WAIT_L(0); PG8_BAR; PG8_MMA(1, 0, At, B0); PG8_MMA(1, 1, At, B1); PG8_BAR; PG8_SCHED;
.LBB0_795:
	s_add_u32 s43, s6, 0xfffc0080
	s_addc_u32 s44, s7, -1
	s_add_i32 s75, 0, 0x10000
	s_cmp_eq_u32 s37, 12
	s_cselect_b32 s47, s39, s44
	s_cselect_b32 s46, s38, s43
	v_add_u32_e32 v32, s75, v165
	s_cselect_b32 s45, s41, s35
	s_cselect_b32 s44, s40, s9
	s_add_i32 s43, 0, 0x14000
	ds_read_b128 v[142:145], v32
	ds_read_b128 v[148:151], v32 offset:1024
	ds_read_b128 v[158:161], v32 offset:2048
	ds_read_b128 v[168:171], v32 offset:3072
	v_add_u32_e32 v32, s43, v165
	ds_read_b128 v[172:175], v32
	ds_read_b128 v[176:179], v32 offset:1024
	ds_read_b128 v[180:183], v32 offset:2048
	ds_read_b128 v[184:187], v32 offset:3072
	s_add_i32 m0, s59, 0xc000
	ds_read_b128 v[188:191], v167
	ds_read_b128 v[192:195], v167 offset:1024
	ds_read_b128 v[196:199], v167 offset:2048
	ds_read_b128 v[208:211], v167 offset:3072
	ds_read_b128 v[216:219], v167 offset:4096
	ds_read_b128 v[220:223], v167 offset:5120
	ds_read_b128 v[224:227], v167 offset:6144
	ds_read_b128 v[228:231], v167 offset:7168
	global_load_lds_dwordx4 v138, s[6:7]
	s_add_i32 m0, s59, 0xe000
	s_nop 0
	global_load_lds_dwordx4 v140, s[6:7]
	s_waitcnt vmcnt(8)
	s_waitcnt lgkmcnt(0)
	s_barrier
	s_setprio 1
	s_waitcnt lgkmcnt(0)
	v_mfma_f32_16x16x32_bf16 v[126:129], v[142:145], v[188:191], 0
	v_mfma_f32_16x16x32_bf16 v[122:125], v[158:161], v[188:191], 0
	v_mfma_f32_16x16x32_bf16 v[110:113], v[142:145], v[196:199], 0
	v_mfma_f32_16x16x32_bf16 v[106:109], v[158:161], v[196:199], 0
	v_mfma_f32_16x16x32_bf16 v[94:97], v[142:145], v[216:219], 0
	v_mfma_f32_16x16x32_bf16 v[90:93], v[158:161], v[216:219], 0
	v_mfma_f32_16x16x32_bf16 v[78:81], v[142:145], v[224:227], 0
	v_mfma_f32_16x16x32_bf16 v[74:77], v[158:161], v[224:227], 0
	v_mfma_f32_16x16x32_bf16 v[126:129], v[148:151], v[192:195], v[126:129]
	v_mfma_f32_16x16x32_bf16 v[122:125], v[168:171], v[192:195], v[122:125]
	v_mfma_f32_16x16x32_bf16 v[110:113], v[148:151], v[208:211], v[110:113]
	v_mfma_f32_16x16x32_bf16 v[106:109], v[168:171], v[208:211], v[106:109]
	v_mfma_f32_16x16x32_bf16 v[94:97], v[148:151], v[220:223], v[94:97]
	v_mfma_f32_16x16x32_bf16 v[90:93], v[168:171], v[220:223], v[90:93]
	v_mfma_f32_16x16x32_bf16 v[78:81], v[148:151], v[228:231], v[78:81]
	v_mfma_f32_16x16x32_bf16 v[74:77], v[168:171], v[228:231], v[74:77]
	v_mfma_f32_16x16x32_bf16 v[118:121], v[172:175], v[188:191], 0
	v_mfma_f32_16x16x32_bf16 v[114:117], v[180:183], v[188:191], 0
	v_mfma_f32_16x16x32_bf16 v[102:105], v[172:175], v[196:199], 0
	v_mfma_f32_16x16x32_bf16 v[98:101], v[180:183], v[196:199], 0
	v_mfma_f32_16x16x32_bf16 v[86:89], v[172:175], v[216:219], 0
	v_mfma_f32_16x16x32_bf16 v[82:85], v[180:183], v[216:219], 0
	v_mfma_f32_16x16x32_bf16 v[70:73], v[172:175], v[224:227], 0
	v_mfma_f32_16x16x32_bf16 v[66:69], v[180:183], v[224:227], 0
	v_mfma_f32_16x16x32_bf16 v[118:121], v[176:179], v[192:195], v[118:121]
	v_mfma_f32_16x16x32_bf16 v[114:117], v[184:187], v[192:195], v[114:117]
	v_mfma_f32_16x16x32_bf16 v[102:105], v[176:179], v[208:211], v[102:105]
	v_mfma_f32_16x16x32_bf16 v[98:101], v[184:187], v[208:211], v[98:101]
	v_mfma_f32_16x16x32_bf16 v[86:89], v[176:179], v[220:223], v[86:89]
	v_mfma_f32_16x16x32_bf16 v[82:85], v[184:187], v[220:223], v[82:85]
	v_mfma_f32_16x16x32_bf16 v[70:73], v[176:179], v[228:231], v[70:73]
	v_mfma_f32_16x16x32_bf16 v[66:69], v[184:187], v[228:231], v[66:69]
	s_setprio 0
	s_barrier
	s_add_i32 s75, s75, s51
	s_mov_b32 m0, s75
	ds_read_b128 v[188:191], v167 offset:16384
	ds_read_b128 v[192:195], v167 offset:17408
	ds_read_b128 v[196:199], v167 offset:18432
	ds_read_b128 v[208:211], v167 offset:19456
	ds_read_b128 v[216:219], v167 offset:20480
	ds_read_b128 v[220:223], v167 offset:21504
	ds_read_b128 v[224:227], v167 offset:22528
	ds_read_b128 v[228:231], v167 offset:23552
	global_load_lds_dwordx4 v132, s[44:45]
	s_add_i32 m0, s75, 0x2000
	s_add_u32 s76, s44, 0x40000
	s_addc_u32 s77, s45, 0
	s_add_i32 s43, s43, s51
	global_load_lds_dwordx4 v136, s[44:45]
	s_mov_b32 m0, s43
	s_nop 0
	global_load_lds_dwordx4 v132, s[76:77]
	s_add_i32 m0, s43, 0x2000
	s_nop 0
	global_load_lds_dwordx4 v136, s[76:77]
	s_mov_b32 m0, s59
	s_nop 0
	global_load_lds_dwordx4 v130, s[46:47]
	s_mov_b32 m0, s62
	s_nop 0
	global_load_lds_dwordx4 v134, s[46:47]
	s_waitcnt vmcnt(8)
	s_waitcnt lgkmcnt(0)
	s_barrier
	s_setprio 1
	s_waitcnt lgkmcnt(0)
	v_mfma_f32_16x16x32_bf16 v[62:65], v[142:145], v[188:191], 0
	v_mfma_f32_16x16x32_bf16 v[58:61], v[158:161], v[188:191], 0
	v_mfma_f32_16x16x32_bf16 v[46:49], v[142:145], v[196:199], 0
	v_mfma_f32_16x16x32_bf16 v[42:45], v[158:161], v[196:199], 0
	v_mfma_f32_16x16x32_bf16 v[28:31], v[142:145], v[216:219], 0
	v_mfma_f32_16x16x32_bf16 v[24:27], v[158:161], v[216:219], 0
	v_mfma_f32_16x16x32_bf16 v[12:15], v[142:145], v[224:227], 0
	v_mfma_f32_16x16x32_bf16 v[8:11], v[158:161], v[224:227], 0
	v_mfma_f32_16x16x32_bf16 v[62:65], v[148:151], v[192:195], v[62:65]
	v_mfma_f32_16x16x32_bf16 v[58:61], v[168:171], v[192:195], v[58:61]
	v_mfma_f32_16x16x32_bf16 v[46:49], v[148:151], v[208:211], v[46:49]
	v_mfma_f32_16x16x32_bf16 v[42:45], v[168:171], v[208:211], v[42:45]
	v_mfma_f32_16x16x32_bf16 v[28:31], v[148:151], v[220:223], v[28:31]
	v_mfma_f32_16x16x32_bf16 v[24:27], v[168:171], v[220:223], v[24:27]
	v_mfma_f32_16x16x32_bf16 v[12:15], v[148:151], v[228:231], v[12:15]
	v_mfma_f32_16x16x32_bf16 v[8:11], v[168:171], v[228:231], v[8:11]
	v_mfma_f32_16x16x32_bf16 v[54:57], v[172:175], v[188:191], 0
	v_mfma_f32_16x16x32_bf16 v[50:53], v[180:183], v[188:191], 0
	v_mfma_f32_16x16x32_bf16 v[38:41], v[172:175], v[196:199], 0
	v_mfma_f32_16x16x32_bf16 v[34:37], v[180:183], v[196:199], 0
	v_mfma_f32_16x16x32_bf16 v[20:23], v[172:175], v[216:219], 0
	v_mfma_f32_16x16x32_bf16 v[16:19], v[180:183], v[216:219], 0
	v_mfma_f32_16x16x32_bf16 v[4:7], v[172:175], v[224:227], 0
	v_mfma_f32_16x16x32_bf16 v[0:3], v[180:183], v[224:227], 0
	v_mfma_f32_16x16x32_bf16 v[54:57], v[176:179], v[192:195], v[54:57]
	v_mfma_f32_16x16x32_bf16 v[50:53], v[184:187], v[192:195], v[50:53]
	v_mfma_f32_16x16x32_bf16 v[38:41], v[176:179], v[208:211], v[38:41]
	v_mfma_f32_16x16x32_bf16 v[34:37], v[184:187], v[208:211], v[34:37]
	v_mfma_f32_16x16x32_bf16 v[20:23], v[176:179], v[220:223], v[20:23]
	v_mfma_f32_16x16x32_bf16 v[16:19], v[184:187], v[220:223], v[16:19]
	v_mfma_f32_16x16x32_bf16 v[4:7], v[176:179], v[228:231], v[4:7]
	v_mfma_f32_16x16x32_bf16 v[0:3], v[184:187], v[228:231], v[0:3]
	s_setprio 0
	s_barrier
	s_branch .Lp3_795
; #define PG8_STAGE(bufoff, gbase, voff) do { _Pragma("unroll") for (int _i = 0; _i < 2; ++_i) \
;         __builtin_amdgcn_global_load_lds((const unsigned*)((const char*)(gbase) + (voff)[_i]), (PG8_LAS unsigned*)(lds + (bufoff) + ldsw + _i * 8192), 16, 0, 0); } while (0)
; #define PG8_LDA(dst, b, h) do { _Pragma("unroll") for (int m = 0; m < 4; ++m) _Pragma("unroll") for (int k = 0; k < 2; ++k) dst[m][k] = *(const PG8_LAS bf16x8*)(lds + PG8_SA(b, h) + aoff + m * 2048 + k * 1024); } while (0)
; #define PG8_LDB(dst, b, h) do { _Pragma("unroll") for (int n = 0; n < 2; ++n) _Pragma("unroll") for (int k = 0; k < 2; ++k) dst[n][k] = *(const PG8_LAS bf16x8*)(lds + PG8_SB(b, h) + boff + n * 2048 + k * 1024); } while (0)
; #define PG8_WAIT_V(n) asm volatile("s_waitcnt vmcnt(" #n ")" ::: "memory")
; #define PG8_WAIT_L(n) asm volatile("s_waitcnt lgkmcnt(" #n ")" ::: "memory")
; #define PG8_BAR __builtin_amdgcn_s_barrier()
; #define PG8_SCHED __builtin_amdgcn_sched_barrier(0)
; template <class Epi, bool ALIGN_EPI = true>
; __device__ __forceinline__ void gemm_phase(PG8_LAS unsigned char* lds, const Gemm g, const StaticOrder& S, const Epi& E) {
;     ...
;             PG8_LDB(B0, 0, 0); PG8_LDB(B1, 0, 1); PG8_SCHED; PG8_LDA(At, 0, 0); PG8_STAGE(PG8_SA(1, 1), a1 + hstepA, voffA);
;             PG8_WAIT_V(8); PG8_WAIT_L(0); PG8_BAR; PG8_MMA(0, 0, At, B0); PG8_MMA(0, 1, At, B1); PG8_BAR; PG8_SCHED;
;             PG8_LDA(At, 0, 1); PG8_STAGE(PG8_SB(0, 0), b2, voffB); PG8_STAGE(PG8_SB(0, 1), b2 + hstepB, voffB); PG8_STAGE(PG8_SA(0, 0), a2, voffA);
;             PG8_WAIT_V(8); PG8_WAIT_L(0); PG8_BAR; PG8_MMA(1, 0, At, B0); PG8_MMA(1, 1, At, B1); PG8_BAR; PG8_SCHED;
.Lrot_795:
	ds_read_b128 v[142:145], v32
	ds_read_b128 v[148:151], v32 offset:1024
	ds_read_b128 v[158:161], v32 offset:2048
	ds_read_b128 v[168:171], v32 offset:3072
	v_add_u32_e32 v32, s43, v165
	ds_read_b128 v[172:175], v32
	ds_read_b128 v[176:179], v32 offset:1024
	ds_read_b128 v[180:183], v32 offset:2048
	ds_read_b128 v[184:187], v32 offset:3072
	s_add_i32 m0, s59, 0xc000
	ds_read_b128 v[188:191], v167
	ds_read_b128 v[192:195], v167 offset:1024
	ds_read_b128 v[196:199], v167 offset:2048
	ds_read_b128 v[208:211], v167 offset:3072
	ds_read_b128 v[216:219], v167 offset:4096
	ds_read_b128 v[220:223], v167 offset:5120
	ds_read_b128 v[224:227], v167 offset:6144
	ds_read_b128 v[228:231], v167 offset:7168
	global_load_lds_dwordx4 v138, s[6:7]
	s_add_i32 m0, s59, 0xe000
	s_nop 0
	global_load_lds_dwordx4 v140, s[6:7]
	s_waitcnt vmcnt(8)
	s_waitcnt lgkmcnt(0)
	s_barrier
	s_setprio 1
	s_waitcnt lgkmcnt(0)
	v_mfma_f32_16x16x32_bf16 v[126:129], v[142:145], v[188:191], v[126:129]
	v_mfma_f32_16x16x32_bf16 v[122:125], v[158:161], v[188:191], v[122:125]
	v_mfma_f32_16x16x32_bf16 v[110:113], v[142:145], v[196:199], v[110:113]
	v_mfma_f32_16x16x32_bf16 v[106:109], v[158:161], v[196:199], v[106:109]
	v_mfma_f32_16x16x32_bf16 v[94:97], v[142:145], v[216:219], v[94:97]
	v_mfma_f32_16x16x32_bf16 v[90:93], v[158:161], v[216:219], v[90:93]
	v_mfma_f32_16x16x32_bf16 v[78:81], v[142:145], v[224:227], v[78:81]
	v_mfma_f32_16x16x32_bf16 v[74:77], v[158:161], v[224:227], v[74:77]
	v_mfma_f32_16x16x32_bf16 v[126:129], v[148:151], v[192:195], v[126:129]
	v_mfma_f32_16x16x32_bf16 v[122:125], v[168:171], v[192:195], v[122:125]
	v_mfma_f32_16x16x32_bf16 v[110:113], v[148:151], v[208:211], v[110:113]
	v_mfma_f32_16x16x32_bf16 v[106:109], v[168:171], v[208:211], v[106:109]
	v_mfma_f32_16x16x32_bf16 v[94:97], v[148:151], v[220:223], v[94:97]
	v_mfma_f32_16x16x32_bf16 v[90:93], v[168:171], v[220:223], v[90:93]
	v_mfma_f32_16x16x32_bf16 v[78:81], v[148:151], v[228:231], v[78:81]
	v_mfma_f32_16x16x32_bf16 v[74:77], v[168:171], v[228:231], v[74:77]
	v_mfma_f32_16x16x32_bf16 v[118:121], v[172:175], v[188:191], v[118:121]
	v_mfma_f32_16x16x32_bf16 v[114:117], v[180:183], v[188:191], v[114:117]
	v_mfma_f32_16x16x32_bf16 v[102:105], v[172:175], v[196:199], v[102:105]
	v_mfma_f32_16x16x32_bf16 v[98:101], v[180:183], v[196:199], v[98:101]
	v_mfma_f32_16x16x32_bf16 v[86:89], v[172:175], v[216:219], v[86:89]
	v_mfma_f32_16x16x32_bf16 v[82:85], v[180:183], v[216:219], v[82:85]
	v_mfma_f32_16x16x32_bf16 v[70:73], v[172:175], v[224:227], v[70:73]
	v_mfma_f32_16x16x32_bf16 v[66:69], v[180:183], v[224:227], v[66:69]
	v_mfma_f32_16x16x32_bf16 v[118:121], v[176:179], v[192:195], v[118:121]
	v_mfma_f32_16x16x32_bf16 v[114:117], v[184:187], v[192:195], v[114:117]
	v_mfma_f32_16x16x32_bf16 v[102:105], v[176:179], v[208:211], v[102:105]
	v_mfma_f32_16x16x32_bf16 v[98:101], v[184:187], v[208:211], v[98:101]
	v_mfma_f32_16x16x32_bf16 v[86:89], v[176:179], v[220:223], v[86:89]
	v_mfma_f32_16x16x32_bf16 v[82:85], v[184:187], v[220:223], v[82:85]
	v_mfma_f32_16x16x32_bf16 v[70:73], v[176:179], v[228:231], v[70:73]
	v_mfma_f32_16x16x32_bf16 v[66:69], v[184:187], v[228:231], v[66:69]
	s_setprio 0
	s_barrier
	s_add_i32 s75, s75, s51
	s_mov_b32 m0, s75
	ds_read_b128 v[188:191], v167 offset:16384
	ds_read_b128 v[192:195], v167 offset:17408
	ds_read_b128 v[196:199], v167 offset:18432
	ds_read_b128 v[208:211], v167 offset:19456
	ds_read_b128 v[216:219], v167 offset:20480
	ds_read_b128 v[220:223], v167 offset:21504
	ds_read_b128 v[224:227], v167 offset:22528
	ds_read_b128 v[228:231], v167 offset:23552
	global_load_lds_dwordx4 v132, s[44:45]
	s_add_i32 m0, s75, 0x2000
	s_add_u32 s76, s44, 0x40000
	s_addc_u32 s77, s45, 0
	s_add_i32 s43, s43, s51
	global_load_lds_dwordx4 v136, s[44:45]
	s_mov_b32 m0, s43
	s_nop 0
	global_load_lds_dwordx4 v132, s[76:77]
	s_add_i32 m0, s43, 0x2000
	s_nop 0
	global_load_lds_dwordx4 v136, s[76:77]
	s_mov_b32 m0, s59
	s_nop 0
	global_load_lds_dwordx4 v130, s[46:47]
	s_mov_b32 m0, s62
	s_nop 0
	global_load_lds_dwordx4 v134, s[46:47]
	s_waitcnt vmcnt(8)
	s_waitcnt lgkmcnt(0)
	s_barrier
	s_setprio 1
	s_waitcnt lgkmcnt(0)
	v_mfma_f32_16x16x32_bf16 v[62:65], v[142:145], v[188:191], v[62:65]
	v_mfma_f32_16x16x32_bf16 v[58:61], v[158:161], v[188:191], v[58:61]
	v_mfma_f32_16x16x32_bf16 v[46:49], v[142:145], v[196:199], v[46:49]
	v_mfma_f32_16x16x32_bf16 v[42:45], v[158:161], v[196:199], v[42:45]
	v_mfma_f32_16x16x32_bf16 v[28:31], v[142:145], v[216:219], v[28:31]
	v_mfma_f32_16x16x32_bf16 v[24:27], v[158:161], v[216:219], v[24:27]
	v_mfma_f32_16x16x32_bf16 v[12:15], v[142:145], v[224:227], v[12:15]
	v_mfma_f32_16x16x32_bf16 v[8:11], v[158:161], v[224:227], v[8:11]
	v_mfma_f32_16x16x32_bf16 v[62:65], v[148:151], v[192:195], v[62:65]
	v_mfma_f32_16x16x32_bf16 v[58:61], v[168:171], v[192:195], v[58:61]
	v_mfma_f32_16x16x32_bf16 v[46:49], v[148:151], v[208:211], v[46:49]
	v_mfma_f32_16x16x32_bf16 v[42:45], v[168:171], v[208:211], v[42:45]
	v_mfma_f32_16x16x32_bf16 v[28:31], v[148:151], v[220:223], v[28:31]
	v_mfma_f32_16x16x32_bf16 v[24:27], v[168:171], v[220:223], v[24:27]
	v_mfma_f32_16x16x32_bf16 v[12:15], v[148:151], v[228:231], v[12:15]
	v_mfma_f32_16x16x32_bf16 v[8:11], v[168:171], v[228:231], v[8:11]
	v_mfma_f32_16x16x32_bf16 v[54:57], v[172:175], v[188:191], v[54:57]
	v_mfma_f32_16x16x32_bf16 v[50:53], v[180:183], v[188:191], v[50:53]
	v_mfma_f32_16x16x32_bf16 v[38:41], v[172:175], v[196:199], v[38:41]
	v_mfma_f32_16x16x32_bf16 v[34:37], v[180:183], v[196:199], v[34:37]
	v_mfma_f32_16x16x32_bf16 v[20:23], v[172:175], v[216:219], v[20:23]
	v_mfma_f32_16x16x32_bf16 v[16:19], v[180:183], v[216:219], v[16:19]
	v_mfma_f32_16x16x32_bf16 v[4:7], v[172:175], v[224:227], v[4:7]
	v_mfma_f32_16x16x32_bf16 v[0:3], v[180:183], v[224:227], v[0:3]
	v_mfma_f32_16x16x32_bf16 v[54:57], v[176:179], v[192:195], v[54:57]
	v_mfma_f32_16x16x32_bf16 v[50:53], v[184:187], v[192:195], v[50:53]
	v_mfma_f32_16x16x32_bf16 v[38:41], v[176:179], v[208:211], v[38:41]
	v_mfma_f32_16x16x32_bf16 v[34:37], v[184:187], v[208:211], v[34:37]
	v_mfma_f32_16x16x32_bf16 v[20:23], v[176:179], v[220:223], v[20:23]
	v_mfma_f32_16x16x32_bf16 v[16:19], v[184:187], v[220:223], v[16:19]
	v_mfma_f32_16x16x32_bf16 v[4:7], v[176:179], v[228:231], v[4:7]
	v_mfma_f32_16x16x32_bf16 v[0:3], v[184:187], v[228:231], v[0:3]
	s_setprio 0
	s_barrier
; #define PG8_STAGE(bufoff, gbase, voff) do { _Pragma("unroll") for (int _i = 0; _i < 2; ++_i) \
;         __builtin_amdgcn_global_load_lds((const unsigned*)((const char*)(gbase) + (voff)[_i]), (PG8_LAS unsigned*)(lds + (bufoff) + ldsw + _i * 8192), 16, 0, 0); } while (0)
; #define PG8_LDA(dst, b, h) do { _Pragma("unroll") for (int m = 0; m < 4; ++m) _Pragma("unroll") for (int k = 0; k < 2; ++k) dst[m][k] = *(const PG8_LAS bf16x8*)(lds + PG8_SA(b, h) + aoff + m * 2048 + k * 1024); } while (0)
; #define PG8_LDB(dst, b, h) do { _Pragma("unroll") for (int n = 0; n < 2; ++n) _Pragma("unroll") for (int k = 0; k < 2; ++k) dst[n][k] = *(const PG8_LAS bf16x8*)(lds + PG8_SB(b, h) + boff + n * 2048 + k * 1024); } while (0)
; #define PG8_WAIT_V(n) asm volatile("s_waitcnt vmcnt(" #n ")" ::: "memory")
; #define PG8_WAIT_L(n) asm volatile("s_waitcnt lgkmcnt(" #n ")" ::: "memory")
; #define PG8_BAR __builtin_amdgcn_s_barrier()
; #define PG8_SCHED __builtin_amdgcn_sched_barrier(0)
; template <class Epi, bool ALIGN_EPI = true>
; __device__ __forceinline__ void gemm_phase(PG8_LAS unsigned char* lds, const Gemm g, const StaticOrder& S, const Epi& E) {
;     ...
;             PG8_LDB(B0, 1, 0); PG8_LDB(B1, 1, 1); PG8_SCHED; PG8_LDA(At, 1, 0); PG8_STAGE(PG8_SA(0, 1), a2 + hstepA, voffA);
;             PG8_WAIT_V(8); PG8_WAIT_L(0); PG8_BAR; PG8_MMA(0, 0, At, B0); PG8_MMA(0, 1, At, B1); PG8_BAR; PG8_SCHED;
.Lp3_795:
	s_add_i32 s43, 0, 0x18000
	v_add_u32_e32 v32, s43, v165
	s_add_i32 s75, 0, 0x1c000
	ds_read_b128 v[142:145], v32
	ds_read_b128 v[148:151], v32 offset:1024
	ds_read_b128 v[158:161], v32 offset:2048
	ds_read_b128 v[168:171], v32 offset:3072
	v_add_u32_e32 v32, s75, v165
	ds_read_b128 v[172:175], v32
	ds_read_b128 v[176:179], v32 offset:1024
	ds_read_b128 v[180:183], v32 offset:2048
	ds_read_b128 v[184:187], v32 offset:3072
	s_add_u32 s46, s46, 0x40000
	s_addc_u32 s47, s47, 0
	s_mov_b32 m0, s63
	ds_read_b128 v[188:191], v167 offset:32768
	ds_read_b128 v[192:195], v167 offset:33792
	ds_read_b128 v[196:199], v167 offset:34816
	ds_read_b128 v[208:211], v167 offset:35840
	ds_read_b128 v[216:219], v167 offset:36864
	ds_read_b128 v[220:223], v167 offset:37888
	ds_read_b128 v[224:227], v167 offset:38912
	ds_read_b128 v[228:231], v167 offset:39936
	global_load_lds_dwordx4 v130, s[46:47]
	s_mov_b32 m0, s66
	s_nop 0
	global_load_lds_dwordx4 v134, s[46:47]
	s_waitcnt vmcnt(8)
	s_waitcnt lgkmcnt(0)
	s_barrier
	s_setprio 1
	s_waitcnt lgkmcnt(0)
	v_mfma_f32_16x16x32_bf16 v[126:129], v[142:145], v[188:191], v[126:129]
	v_mfma_f32_16x16x32_bf16 v[122:125], v[158:161], v[188:191], v[122:125]
	v_mfma_f32_16x16x32_bf16 v[110:113], v[142:145], v[196:199], v[110:113]
	v_mfma_f32_16x16x32_bf16 v[106:109], v[158:161], v[196:199], v[106:109]
	v_mfma_f32_16x16x32_bf16 v[94:97], v[142:145], v[216:219], v[94:97]
	v_mfma_f32_16x16x32_bf16 v[90:93], v[158:161], v[216:219], v[90:93]
	v_mfma_f32_16x16x32_bf16 v[78:81], v[142:145], v[224:227], v[78:81]
	v_mfma_f32_16x16x32_bf16 v[74:77], v[158:161], v[224:227], v[74:77]
	v_mfma_f32_16x16x32_bf16 v[126:129], v[148:151], v[192:195], v[126:129]
	v_mfma_f32_16x16x32_bf16 v[122:125], v[168:171], v[192:195], v[122:125]
	v_mfma_f32_16x16x32_bf16 v[110:113], v[148:151], v[208:211], v[110:113]
	v_mfma_f32_16x16x32_bf16 v[106:109], v[168:171], v[208:211], v[106:109]
	v_mfma_f32_16x16x32_bf16 v[94:97], v[148:151], v[220:223], v[94:97]
	v_mfma_f32_16x16x32_bf16 v[90:93], v[168:171], v[220:223], v[90:93]
	v_mfma_f32_16x16x32_bf16 v[78:81], v[148:151], v[228:231], v[78:81]
	v_mfma_f32_16x16x32_bf16 v[74:77], v[168:171], v[228:231], v[74:77]
	v_mfma_f32_16x16x32_bf16 v[118:121], v[172:175], v[188:191], v[118:121]
	v_mfma_f32_16x16x32_bf16 v[114:117], v[180:183], v[188:191], v[114:117]
	v_mfma_f32_16x16x32_bf16 v[102:105], v[172:175], v[196:199], v[102:105]
	v_mfma_f32_16x16x32_bf16 v[98:101], v[180:183], v[196:199], v[98:101]
	v_mfma_f32_16x16x32_bf16 v[86:89], v[172:175], v[216:219], v[86:89]
	v_mfma_f32_16x16x32_bf16 v[82:85], v[180:183], v[216:219], v[82:85]
	v_mfma_f32_16x16x32_bf16 v[70:73], v[172:175], v[224:227], v[70:73]
	v_mfma_f32_16x16x32_bf16 v[66:69], v[180:183], v[224:227], v[66:69]
	v_mfma_f32_16x16x32_bf16 v[118:121], v[176:179], v[192:195], v[118:121]
	v_mfma_f32_16x16x32_bf16 v[114:117], v[184:187], v[192:195], v[114:117]
	v_mfma_f32_16x16x32_bf16 v[102:105], v[176:179], v[208:211], v[102:105]
	v_mfma_f32_16x16x32_bf16 v[98:101], v[184:187], v[208:211], v[98:101]
	v_mfma_f32_16x16x32_bf16 v[86:89], v[176:179], v[220:223], v[86:89]
	v_mfma_f32_16x16x32_bf16 v[82:85], v[184:187], v[220:223], v[82:85]
	v_mfma_f32_16x16x32_bf16 v[70:73], v[176:179], v[228:231], v[70:73]
	v_mfma_f32_16x16x32_bf16 v[66:69], v[184:187], v[228:231], v[66:69]
	s_setprio 0
	s_barrier
; #define PG8_STAGE(bufoff, gbase, voff) do { _Pragma("unroll") for (int _i = 0; _i < 2; ++_i) \
;         __builtin_amdgcn_global_load_lds((const unsigned*)((const char*)(gbase) + (voff)[_i]), (PG8_LAS unsigned*)(lds + (bufoff) + ldsw + _i * 8192), 16, 0, 0); } while (0)
; #define PG8_LDA(dst, b, h) do { _Pragma("unroll") for (int m = 0; m < 4; ++m) _Pragma("unroll") for (int k = 0; k < 2; ++k) dst[m][k] = *(const PG8_LAS bf16x8*)(lds + PG8_SA(b, h) + aoff + m * 2048 + k * 1024); } while (0)
; #define PG8_WAIT_V(n) asm volatile("s_waitcnt vmcnt(" #n ")" ::: "memory")
; #define PG8_WAIT_L(n) asm volatile("s_waitcnt lgkmcnt(" #n ")" ::: "memory")
; #define PG8_BAR __builtin_amdgcn_s_barrier()
; #define PG8_SCHED __builtin_amdgcn_sched_barrier(0)
; template <class Epi, bool ALIGN_EPI = true>
; __device__ __forceinline__ void gemm_phase(PG8_LAS unsigned char* lds, const Gemm g, const StaticOrder& S, const Epi& E) {
;     ...
;         for (int t = 0; t < nt; t += 2) {
;             const bool last = (t == nt - 2);
;             const char* a1 = cA + (size_t)(t + 1) * kstep;
;             const char* a2 = last ? nA : cA + (size_t)(t + 2) * kstep; const char* b2 = last ? nB : cB + (size_t)(t + 2) * kstep;
;     ...
;             PG8_LDA(At, 1, 1); PG8_STAGE(PG8_SB(1, 0), b3, voffB); PG8_STAGE(PG8_SB(1, 1), b3 + hstepB, voffB); PG8_STAGE(PG8_SA(1, 0), a3, voffA);
;             PG8_WAIT_V(8); PG8_WAIT_L(0); PG8_BAR; PG8_MMA(1, 0, At, B0); PG8_MMA(1, 1, At, B1); PG8_BAR; PG8_SCHED;
	s_add_i32 s43, s43, s51
	s_mov_b32 m0, s43
	ds_read_b128 v[188:191], v167 offset:49152
	ds_read_b128 v[192:195], v167 offset:50176
	ds_read_b128 v[196:199], v167 offset:51200
	ds_read_b128 v[208:211], v167 offset:52224
	ds_read_b128 v[216:219], v167 offset:53248
	ds_read_b128 v[220:223], v167 offset:54272
	ds_read_b128 v[224:227], v167 offset:55296
	ds_read_b128 v[228:231], v167 offset:56320
	s_add_u32 s98, s44, s60
	s_addc_u32 s99, s45, s61
	global_load_lds_dwordx4 v132, s[98:99]
	s_add_i32 m0, s43, 0x2000
	s_add_u32 s44, s44, 0x40080
	s_addc_u32 s45, s45, 0
	s_add_i32 s43, s75, s51
	s_add_u32 s98, s44, s60
	s_addc_u32 s99, s45, s61
	s_add_u32 s98, s98, 0xfffbff80
	s_addc_u32 s99, s99, -1
	global_load_lds_dwordx4 v136, s[98:99]
	s_mov_b32 m0, s43
	s_nop 0
	global_load_lds_dwordx4 v132, s[44:45]
	s_add_i32 m0, s43, 0x2000
	s_nop 0
	global_load_lds_dwordx4 v136, s[44:45]
	s_mov_b32 m0, s70
	s_nop 0
	s_add_u32 s98, s46, s60
	s_addc_u32 s99, s47, s61
	s_add_u32 s98, s98, 0xfffc0000
	s_addc_u32 s99, s99, -1
	global_load_lds_dwordx4 v130, s[98:99]
	s_mov_b32 m0, s71
	s_nop 0
	s_add_u32 s98, s46, s60
	s_addc_u32 s99, s47, s61
	s_add_u32 s98, s98, 0xfffc0000
	s_addc_u32 s99, s99, -1
	global_load_lds_dwordx4 v134, s[98:99]
	s_add_i32 s37, s37, 2
	s_add_u32 s6, s6, 0x100
	s_addc_u32 s7, s7, 0
	s_add_u32 s9, s9, 0x100
	s_addc_u32 s35, s35, 0
	s_add_u32 s43, s6, 0xfffc0080
	s_addc_u32 s44, s7, -1
	s_add_i32 s75, 0, 0x10000
	s_cmp_eq_u32 s37, 12
	s_cselect_b32 s47, s39, s44
	s_cselect_b32 s46, s38, s43
	v_add_u32_e32 v32, s75, v165
	s_cselect_b32 s45, s41, s35
	s_cselect_b32 s44, s40, s9
	s_add_i32 s43, 0, 0x14000
	s_cmp_gt_u32 s37, 13
	s_waitcnt vmcnt(8)
	s_waitcnt lgkmcnt(0)
	s_barrier
	s_setprio 1
	s_waitcnt lgkmcnt(0)
	v_mfma_f32_16x16x32_bf16 v[62:65], v[142:145], v[188:191], v[62:65]
	v_mfma_f32_16x16x32_bf16 v[58:61], v[158:161], v[188:191], v[58:61]
	v_mfma_f32_16x16x32_bf16 v[46:49], v[142:145], v[196:199], v[46:49]
	v_mfma_f32_16x16x32_bf16 v[42:45], v[158:161], v[196:199], v[42:45]
	v_mfma_f32_16x16x32_bf16 v[28:31], v[142:145], v[216:219], v[28:31]
	v_mfma_f32_16x16x32_bf16 v[24:27], v[158:161], v[216:219], v[24:27]
	v_mfma_f32_16x16x32_bf16 v[12:15], v[142:145], v[224:227], v[12:15]
	v_mfma_f32_16x16x32_bf16 v[8:11], v[158:161], v[224:227], v[8:11]
	v_mfma_f32_16x16x32_bf16 v[62:65], v[148:151], v[192:195], v[62:65]
	v_mfma_f32_16x16x32_bf16 v[58:61], v[168:171], v[192:195], v[58:61]
	v_mfma_f32_16x16x32_bf16 v[46:49], v[148:151], v[208:211], v[46:49]
	v_mfma_f32_16x16x32_bf16 v[42:45], v[168:171], v[208:211], v[42:45]
	v_mfma_f32_16x16x32_bf16 v[28:31], v[148:151], v[220:223], v[28:31]
	v_mfma_f32_16x16x32_bf16 v[24:27], v[168:171], v[220:223], v[24:27]
	v_mfma_f32_16x16x32_bf16 v[12:15], v[148:151], v[228:231], v[12:15]
	v_mfma_f32_16x16x32_bf16 v[8:11], v[168:171], v[228:231], v[8:11]
	v_mfma_f32_16x16x32_bf16 v[54:57], v[172:175], v[188:191], v[54:57]
	v_mfma_f32_16x16x32_bf16 v[50:53], v[180:183], v[188:191], v[50:53]
	v_mfma_f32_16x16x32_bf16 v[38:41], v[172:175], v[196:199], v[38:41]
	v_mfma_f32_16x16x32_bf16 v[34:37], v[180:183], v[196:199], v[34:37]
	v_mfma_f32_16x16x32_bf16 v[20:23], v[172:175], v[216:219], v[20:23]
	v_mfma_f32_16x16x32_bf16 v[16:19], v[180:183], v[216:219], v[16:19]
	v_mfma_f32_16x16x32_bf16 v[4:7], v[172:175], v[224:227], v[4:7]
	v_mfma_f32_16x16x32_bf16 v[0:3], v[180:183], v[224:227], v[0:3]
	v_mfma_f32_16x16x32_bf16 v[54:57], v[176:179], v[192:195], v[54:57]
	v_mfma_f32_16x16x32_bf16 v[50:53], v[184:187], v[192:195], v[50:53]
	v_mfma_f32_16x16x32_bf16 v[38:41], v[176:179], v[208:211], v[38:41]
	v_mfma_f32_16x16x32_bf16 v[34:37], v[184:187], v[208:211], v[34:37]
	v_mfma_f32_16x16x32_bf16 v[20:23], v[176:179], v[220:223], v[20:23]
	v_mfma_f32_16x16x32_bf16 v[16:19], v[184:187], v[220:223], v[16:19]
	v_mfma_f32_16x16x32_bf16 v[4:7], v[176:179], v[228:231], v[4:7]
	v_mfma_f32_16x16x32_bf16 v[0:3], v[184:187], v[228:231], v[0:3]
	s_setprio 0
	s_barrier
	s_cbranch_scc0 .Lrot_795
	s_and_b64 vcc, exec, s[26:27]
	s_cbranch_vccz .LBB0_798
	s_barrier

; #define PG8_STAGE(bufoff, gbase, voff) do { _Pragma("unroll") for (int _i = 0; _i < 2; ++_i) \
;         __builtin_amdgcn_global_load_lds((const unsigned*)((const char*)(gbase) + (voff)[_i]), (PG8_LAS unsigned*)(lds + (bufoff) + ldsw + _i * 8192), 16, 0, 0); } while (0)
; #define PG8_LDA(dst, b, h) do { _Pragma("unroll") for (int m = 0; m < 4; ++m) _Pragma("unroll") for (int k = 0; k < 2; ++k) dst[m][k] = *(const PG8_LAS bf16x8*)(lds + PG8_SA(b, h) + aoff + m * 2048 + k * 1024); } while (0)
; #define PG8_LDB(dst, b, h) do { _Pragma("unroll") for (int n = 0; n < 2; ++n) _Pragma("unroll") for (int k = 0; k < 2; ++k) dst[n][k] = *(const PG8_LAS bf16x8*)(lds + PG8_SB(b, h) + boff + n * 2048 + k * 1024); } while (0)
; #define PG8_WAIT_V(n) asm volatile("s_waitcnt vmcnt(" #n ")" ::: "memory")
; #define PG8_WAIT_L(n) asm volatile("s_waitcnt lgkmcnt(" #n ")" ::: "memory")
; #define PG8_BAR __builtin_amdgcn_s_barrier()
; #define PG8_SCHED __builtin_amdgcn_sched_barrier(0)
; template <class Epi, bool ALIGN_EPI = true>
; __device__ __forceinline__ void gemm_phase(PG8_LAS unsigned char* lds, const Gemm g, const StaticOrder& S, const Epi& E) {
;     ...
;         for (int t = 0; t < nt; t += 2) {
;             const bool last = (t == nt - 2);
;             const char* a1 = cA + (size_t)(t + 1) * kstep;
;             const char* a2 = last ? nA : cA + (size_t)(t + 2) * kstep; const char* b2 = last ? nB : cB + (size_t)(t + 2) * kstep;
;             const char* a3 = a2 + kstep; const char* b3 = b2 + kstep;
;             PG8_LDB(B0, 0, 0); PG8_LDB(B1, 0, 1); PG8_SCHED; PG8_LDA(At, 0, 0); PG8_STAGE(PG8_SA(1, 1), a1 + hstepA, voffA);
;             PG8_WAIT_V(8); PG8_WAIT_L(0); PG8_BAR; PG8_MMA(0, 0, At, B0); PG8_MMA(0, 1, At, B1); PG8_BAR; PG8_SCHED;
;             PG8_LDA(At, 0, 1); PG8_STAGE(PG8_SB(0, 0), b2, voffB); PG8_STAGE(PG8_SB(0, 1), b2 + hstepB, voffB); PG8_STAGE(PG8_SA(0, 0), a2, voffA);
;             PG8_WAIT_V(8); PG8_WAIT_L(0); PG8_BAR; PG8_MMA(1, 0, At, B0); PG8_MMA(1, 1, At, B1); PG8_BAR; PG8_SCHED;
.LBB0_1004:
	s_add_u32 s22, s20, 0xfffc0080
	s_addc_u32 s23, s21, -1
	s_add_i32 s50, 0, 0x10000
	s_cmp_eq_u32 s49, 12
	s_cselect_b32 s25, s11, s23
	s_cselect_b32 s24, s17, s22
	v_add_u32_e32 v32, s50, v143
	s_cselect_b32 s23, s9, s48
	s_cselect_b32 s22, s19, s47
	s_add_i32 s52, 0, 0x14000
	ds_read_b128 v[130:133], v32
	ds_read_b128 v[134:137], v32 offset:1024
	ds_read_b128 v[164:167], v32 offset:2048
	ds_read_b128 v[168:171], v32 offset:3072
	v_add_u32_e32 v32, s52, v143
	ds_read_b128 v[172:175], v32
	ds_read_b128 v[176:179], v32 offset:1024
	ds_read_b128 v[180:183], v32 offset:2048
	ds_read_b128 v[184:187], v32 offset:3072
	s_add_i32 m0, s35, 0xc000
	ds_read_b128 v[188:191], v163
	ds_read_b128 v[192:195], v163 offset:1024
	ds_read_b128 v[196:199], v163 offset:2048
	ds_read_b128 v[216:219], v163 offset:3072
	ds_read_b128 v[220:223], v163 offset:4096
	ds_read_b128 v[224:227], v163 offset:5120
	ds_read_b128 v[228:231], v163 offset:6144
	ds_read_b128 v[232:235], v163 offset:7168
	global_load_lds_dwordx4 v158, s[20:21]
	s_add_i32 m0, s35, 0xe000
	s_nop 0
	global_load_lds_dwordx4 v160, s[20:21]
	s_waitcnt vmcnt(8)
	s_waitcnt lgkmcnt(0)
	s_barrier
	s_setprio 1
	s_waitcnt lgkmcnt(0)
	v_mfma_f32_16x16x32_bf16 v[126:129], v[188:191], v[130:133], 0
	v_mfma_f32_16x16x32_bf16 v[122:125], v[188:191], v[164:167], 0
	v_mfma_f32_16x16x32_bf16 v[110:113], v[196:199], v[130:133], 0
	v_mfma_f32_16x16x32_bf16 v[106:109], v[196:199], v[164:167], 0
	v_mfma_f32_16x16x32_bf16 v[94:97], v[220:223], v[130:133], 0
	v_mfma_f32_16x16x32_bf16 v[90:93], v[220:223], v[164:167], 0
	v_mfma_f32_16x16x32_bf16 v[78:81], v[228:231], v[130:133], 0
	v_mfma_f32_16x16x32_bf16 v[74:77], v[228:231], v[164:167], 0
	v_mfma_f32_16x16x32_bf16 v[126:129], v[192:195], v[134:137], v[126:129]
	v_mfma_f32_16x16x32_bf16 v[122:125], v[192:195], v[168:171], v[122:125]
	v_mfma_f32_16x16x32_bf16 v[110:113], v[216:219], v[134:137], v[110:113]
	v_mfma_f32_16x16x32_bf16 v[106:109], v[216:219], v[168:171], v[106:109]
	v_mfma_f32_16x16x32_bf16 v[94:97], v[224:227], v[134:137], v[94:97]
	v_mfma_f32_16x16x32_bf16 v[90:93], v[224:227], v[168:171], v[90:93]
	v_mfma_f32_16x16x32_bf16 v[78:81], v[232:235], v[134:137], v[78:81]
	v_mfma_f32_16x16x32_bf16 v[74:77], v[232:235], v[168:171], v[74:77]
	v_mfma_f32_16x16x32_bf16 v[118:121], v[188:191], v[172:175], 0
	v_mfma_f32_16x16x32_bf16 v[114:117], v[188:191], v[180:183], 0
	v_mfma_f32_16x16x32_bf16 v[102:105], v[196:199], v[172:175], 0
	v_mfma_f32_16x16x32_bf16 v[98:101], v[196:199], v[180:183], 0
	v_mfma_f32_16x16x32_bf16 v[86:89], v[220:223], v[172:175], 0
	v_mfma_f32_16x16x32_bf16 v[82:85], v[220:223], v[180:183], 0
	v_mfma_f32_16x16x32_bf16 v[70:73], v[228:231], v[172:175], 0
	v_mfma_f32_16x16x32_bf16 v[66:69], v[228:231], v[180:183], 0
	v_mfma_f32_16x16x32_bf16 v[118:121], v[192:195], v[176:179], v[118:121]
	v_mfma_f32_16x16x32_bf16 v[114:117], v[192:195], v[184:187], v[114:117]
	v_mfma_f32_16x16x32_bf16 v[102:105], v[216:219], v[176:179], v[102:105]
	v_mfma_f32_16x16x32_bf16 v[98:101], v[216:219], v[184:187], v[98:101]
	v_mfma_f32_16x16x32_bf16 v[86:89], v[224:227], v[176:179], v[86:89]
	v_mfma_f32_16x16x32_bf16 v[82:85], v[224:227], v[184:187], v[82:85]
	v_mfma_f32_16x16x32_bf16 v[70:73], v[232:235], v[176:179], v[70:73]
	v_mfma_f32_16x16x32_bf16 v[66:69], v[232:235], v[184:187], v[66:69]
	s_setprio 0
	s_barrier
	s_add_i32 s50, s50, s34
	s_mov_b32 m0, s50
	ds_read_b128 v[188:191], v163 offset:16384
	ds_read_b128 v[192:195], v163 offset:17408
	ds_read_b128 v[196:199], v163 offset:18432
	ds_read_b128 v[216:219], v163 offset:19456
	ds_read_b128 v[220:223], v163 offset:20480
	ds_read_b128 v[224:227], v163 offset:21504
	ds_read_b128 v[228:231], v163 offset:22528
	ds_read_b128 v[232:235], v163 offset:23552
	global_load_lds_dwordx4 v138, s[22:23]
	s_add_i32 m0, s50, 0x2000
	s_add_u32 s50, s22, 0x40000
	s_addc_u32 s51, s23, 0
	s_add_i32 s52, s52, s34
	global_load_lds_dwordx4 v140, s[22:23]
	s_mov_b32 m0, s52
	v_lshl_add_u64 v[200:201], s[24:25], 0, v[140:141]
	global_load_lds_dwordx4 v138, s[50:51]
	s_add_i32 m0, s52, 0x2000
	s_nop 0
	global_load_lds_dwordx4 v140, s[50:51]
	v_lshl_add_u64 v[150:151], s[24:25], 0, v[138:139]
	s_mov_b32 m0, s35
	s_nop 0
	global_load_lds_dwordx4 v138, s[24:25]
	s_mov_b32 m0, s36
	s_nop 0
	global_load_lds_dwordx4 v140, s[24:25]
	s_waitcnt vmcnt(8)
	s_waitcnt lgkmcnt(0)
	s_barrier
	s_setprio 1
	s_waitcnt lgkmcnt(0)
	v_mfma_f32_16x16x32_bf16 v[62:65], v[188:191], v[130:133], 0
	v_mfma_f32_16x16x32_bf16 v[58:61], v[188:191], v[164:167], 0
	v_mfma_f32_16x16x32_bf16 v[46:49], v[196:199], v[130:133], 0
	v_mfma_f32_16x16x32_bf16 v[42:45], v[196:199], v[164:167], 0
	v_mfma_f32_16x16x32_bf16 v[28:31], v[220:223], v[130:133], 0
	v_mfma_f32_16x16x32_bf16 v[24:27], v[220:223], v[164:167], 0
	v_mfma_f32_16x16x32_bf16 v[12:15], v[228:231], v[130:133], 0
	v_mfma_f32_16x16x32_bf16 v[8:11], v[228:231], v[164:167], 0
	v_mfma_f32_16x16x32_bf16 v[62:65], v[192:195], v[134:137], v[62:65]
	v_mfma_f32_16x16x32_bf16 v[58:61], v[192:195], v[168:171], v[58:61]
	v_mfma_f32_16x16x32_bf16 v[46:49], v[216:219], v[134:137], v[46:49]
	v_mfma_f32_16x16x32_bf16 v[42:45], v[216:219], v[168:171], v[42:45]
	v_mfma_f32_16x16x32_bf16 v[28:31], v[224:227], v[134:137], v[28:31]
	v_mfma_f32_16x16x32_bf16 v[24:27], v[224:227], v[168:171], v[24:27]
	v_mfma_f32_16x16x32_bf16 v[12:15], v[232:235], v[134:137], v[12:15]
	v_mfma_f32_16x16x32_bf16 v[8:11], v[232:235], v[168:171], v[8:11]
	v_mfma_f32_16x16x32_bf16 v[54:57], v[188:191], v[172:175], 0
	v_mfma_f32_16x16x32_bf16 v[50:53], v[188:191], v[180:183], 0
	v_mfma_f32_16x16x32_bf16 v[38:41], v[196:199], v[172:175], 0
	v_mfma_f32_16x16x32_bf16 v[34:37], v[196:199], v[180:183], 0
	v_mfma_f32_16x16x32_bf16 v[20:23], v[220:223], v[172:175], 0
	v_mfma_f32_16x16x32_bf16 v[16:19], v[220:223], v[180:183], 0
	v_mfma_f32_16x16x32_bf16 v[4:7], v[228:231], v[172:175], 0
	v_mfma_f32_16x16x32_bf16 v[0:3], v[228:231], v[180:183], 0
	v_mfma_f32_16x16x32_bf16 v[54:57], v[192:195], v[176:179], v[54:57]
	v_mfma_f32_16x16x32_bf16 v[50:53], v[192:195], v[184:187], v[50:53]
	v_mfma_f32_16x16x32_bf16 v[38:41], v[216:219], v[176:179], v[38:41]
	v_mfma_f32_16x16x32_bf16 v[34:37], v[216:219], v[184:187], v[34:37]
	v_mfma_f32_16x16x32_bf16 v[20:23], v[224:227], v[176:179], v[20:23]
	v_mfma_f32_16x16x32_bf16 v[16:19], v[224:227], v[184:187], v[16:19]
	v_mfma_f32_16x16x32_bf16 v[4:7], v[232:235], v[176:179], v[4:7]
	v_mfma_f32_16x16x32_bf16 v[0:3], v[232:235], v[184:187], v[0:3]
	s_setprio 0
	s_barrier
	s_branch .Lp3_1004
; #define PG8_STAGE(bufoff, gbase, voff) do { _Pragma("unroll") for (int _i = 0; _i < 2; ++_i) \
;         __builtin_amdgcn_global_load_lds((const unsigned*)((const char*)(gbase) + (voff)[_i]), (PG8_LAS unsigned*)(lds + (bufoff) + ldsw + _i * 8192), 16, 0, 0); } while (0)
; #define PG8_LDA(dst, b, h) do { _Pragma("unroll") for (int m = 0; m < 4; ++m) _Pragma("unroll") for (int k = 0; k < 2; ++k) dst[m][k] = *(const PG8_LAS bf16x8*)(lds + PG8_SA(b, h) + aoff + m * 2048 + k * 1024); } while (0)
; #define PG8_LDB(dst, b, h) do { _Pragma("unroll") for (int n = 0; n < 2; ++n) _Pragma("unroll") for (int k = 0; k < 2; ++k) dst[n][k] = *(const PG8_LAS bf16x8*)(lds + PG8_SB(b, h) + boff + n * 2048 + k * 1024); } while (0)
; #define PG8_WAIT_V(n) asm volatile("s_waitcnt vmcnt(" #n ")" ::: "memory")
; #define PG8_WAIT_L(n) asm volatile("s_waitcnt lgkmcnt(" #n ")" ::: "memory")
; #define PG8_BAR __builtin_amdgcn_s_barrier()
; #define PG8_SCHED __builtin_amdgcn_sched_barrier(0)
; template <class Epi, bool ALIGN_EPI = true>
; __device__ __forceinline__ void gemm_phase(PG8_LAS unsigned char* lds, const Gemm g, const StaticOrder& S, const Epi& E) {
;     ...
;         for (int t = 0; t < nt; t += 2) {
;             const bool last = (t == nt - 2);
;             const char* a1 = cA + (size_t)(t + 1) * kstep;
;             const char* a2 = last ? nA : cA + (size_t)(t + 2) * kstep; const char* b2 = last ? nB : cB + (size_t)(t + 2) * kstep;
;             const char* a3 = a2 + kstep; const char* b3 = b2 + kstep;
;             PG8_LDB(B0, 0, 0); PG8_LDB(B1, 0, 1); PG8_SCHED; PG8_LDA(At, 0, 0); PG8_STAGE(PG8_SA(1, 1), a1 + hstepA, voffA);
;             PG8_WAIT_V(8); PG8_WAIT_L(0); PG8_BAR; PG8_MMA(0, 0, At, B0); PG8_MMA(0, 1, At, B1); PG8_BAR; PG8_SCHED;
;             PG8_LDA(At, 0, 1); PG8_STAGE(PG8_SB(0, 0), b2, voffB); PG8_STAGE(PG8_SB(0, 1), b2 + hstepB, voffB); PG8_STAGE(PG8_SA(0, 0), a2, voffA);
;             PG8_WAIT_V(8); PG8_WAIT_L(0); PG8_BAR; PG8_MMA(1, 0, At, B0); PG8_MMA(1, 1, At, B1); PG8_BAR; PG8_SCHED;
.Lrot_1004:
	ds_read_b128 v[130:133], v32
	ds_read_b128 v[134:137], v32 offset:1024
	ds_read_b128 v[164:167], v32 offset:2048
	ds_read_b128 v[168:171], v32 offset:3072
	v_add_u32_e32 v32, s52, v143
	ds_read_b128 v[172:175], v32
	ds_read_b128 v[176:179], v32 offset:1024
	ds_read_b128 v[180:183], v32 offset:2048
	ds_read_b128 v[184:187], v32 offset:3072
	s_add_i32 m0, s35, 0xc000
	ds_read_b128 v[188:191], v163
	ds_read_b128 v[192:195], v163 offset:1024
	ds_read_b128 v[196:199], v163 offset:2048
	ds_read_b128 v[216:219], v163 offset:3072
	ds_read_b128 v[220:223], v163 offset:4096
	ds_read_b128 v[224:227], v163 offset:5120
	ds_read_b128 v[228:231], v163 offset:6144
	ds_read_b128 v[232:235], v163 offset:7168
	global_load_lds_dwordx4 v158, s[20:21]
	s_add_i32 m0, s35, 0xe000
	s_nop 0
	global_load_lds_dwordx4 v160, s[20:21]
	s_waitcnt vmcnt(8)
	s_waitcnt lgkmcnt(0)
	s_barrier
	s_setprio 1
	s_waitcnt lgkmcnt(0)
	v_mfma_f32_16x16x32_bf16 v[126:129], v[188:191], v[130:133], v[126:129]
	v_mfma_f32_16x16x32_bf16 v[122:125], v[188:191], v[164:167], v[122:125]
	v_mfma_f32_16x16x32_bf16 v[110:113], v[196:199], v[130:133], v[110:113]
	v_mfma_f32_16x16x32_bf16 v[106:109], v[196:199], v[164:167], v[106:109]
	v_mfma_f32_16x16x32_bf16 v[94:97], v[220:223], v[130:133], v[94:97]
	v_mfma_f32_16x16x32_bf16 v[90:93], v[220:223], v[164:167], v[90:93]
	v_mfma_f32_16x16x32_bf16 v[78:81], v[228:231], v[130:133], v[78:81]
	v_mfma_f32_16x16x32_bf16 v[74:77], v[228:231], v[164:167], v[74:77]
	v_mfma_f32_16x16x32_bf16 v[126:129], v[192:195], v[134:137], v[126:129]
	v_mfma_f32_16x16x32_bf16 v[122:125], v[192:195], v[168:171], v[122:125]
	v_mfma_f32_16x16x32_bf16 v[110:113], v[216:219], v[134:137], v[110:113]
	v_mfma_f32_16x16x32_bf16 v[106:109], v[216:219], v[168:171], v[106:109]
	v_mfma_f32_16x16x32_bf16 v[94:97], v[224:227], v[134:137], v[94:97]
	v_mfma_f32_16x16x32_bf16 v[90:93], v[224:227], v[168:171], v[90:93]
	v_mfma_f32_16x16x32_bf16 v[78:81], v[232:235], v[134:137], v[78:81]
	v_mfma_f32_16x16x32_bf16 v[74:77], v[232:235], v[168:171], v[74:77]
	v_mfma_f32_16x16x32_bf16 v[118:121], v[188:191], v[172:175], v[118:121]
	v_mfma_f32_16x16x32_bf16 v[114:117], v[188:191], v[180:183], v[114:117]
	v_mfma_f32_16x16x32_bf16 v[102:105], v[196:199], v[172:175], v[102:105]
	v_mfma_f32_16x16x32_bf16 v[98:101], v[196:199], v[180:183], v[98:101]
	v_mfma_f32_16x16x32_bf16 v[86:89], v[220:223], v[172:175], v[86:89]
	v_mfma_f32_16x16x32_bf16 v[82:85], v[220:223], v[180:183], v[82:85]
	v_mfma_f32_16x16x32_bf16 v[70:73], v[228:231], v[172:175], v[70:73]
	v_mfma_f32_16x16x32_bf16 v[66:69], v[228:231], v[180:183], v[66:69]
	v_mfma_f32_16x16x32_bf16 v[118:121], v[192:195], v[176:179], v[118:121]
	v_mfma_f32_16x16x32_bf16 v[114:117], v[192:195], v[184:187], v[114:117]
	v_mfma_f32_16x16x32_bf16 v[102:105], v[216:219], v[176:179], v[102:105]
	v_mfma_f32_16x16x32_bf16 v[98:101], v[216:219], v[184:187], v[98:101]
	v_mfma_f32_16x16x32_bf16 v[86:89], v[224:227], v[176:179], v[86:89]
	v_mfma_f32_16x16x32_bf16 v[82:85], v[224:227], v[184:187], v[82:85]
	v_mfma_f32_16x16x32_bf16 v[70:73], v[232:235], v[176:179], v[70:73]
	v_mfma_f32_16x16x32_bf16 v[66:69], v[232:235], v[184:187], v[66:69]
	s_setprio 0
	s_barrier
	s_add_i32 s50, s50, s34
	s_mov_b32 m0, s50
	ds_read_b128 v[188:191], v163 offset:16384
	ds_read_b128 v[192:195], v163 offset:17408
	ds_read_b128 v[196:199], v163 offset:18432
	ds_read_b128 v[216:219], v163 offset:19456
	ds_read_b128 v[220:223], v163 offset:20480
	ds_read_b128 v[224:227], v163 offset:21504
	ds_read_b128 v[228:231], v163 offset:22528
	ds_read_b128 v[232:235], v163 offset:23552
	global_load_lds_dwordx4 v138, s[22:23]
	s_add_i32 m0, s50, 0x2000
	s_add_u32 s50, s22, 0x40000
	s_addc_u32 s51, s23, 0
	s_add_i32 s52, s52, s34
	global_load_lds_dwordx4 v140, s[22:23]
	s_mov_b32 m0, s52
	v_lshl_add_u64 v[200:201], s[24:25], 0, v[140:141]
	global_load_lds_dwordx4 v138, s[50:51]
	s_add_i32 m0, s52, 0x2000
	s_nop 0
	global_load_lds_dwordx4 v140, s[50:51]
	v_lshl_add_u64 v[150:151], s[24:25], 0, v[138:139]
	s_mov_b32 m0, s35
	s_nop 0
	global_load_lds_dwordx4 v138, s[24:25]
	s_mov_b32 m0, s36
	s_nop 0
	global_load_lds_dwordx4 v140, s[24:25]
	s_waitcnt vmcnt(8)
	s_waitcnt lgkmcnt(0)
	s_barrier
	s_setprio 1
	s_waitcnt lgkmcnt(0)
	v_mfma_f32_16x16x32_bf16 v[62:65], v[188:191], v[130:133], v[62:65]
	v_mfma_f32_16x16x32_bf16 v[58:61], v[188:191], v[164:167], v[58:61]
	v_mfma_f32_16x16x32_bf16 v[46:49], v[196:199], v[130:133], v[46:49]
	v_mfma_f32_16x16x32_bf16 v[42:45], v[196:199], v[164:167], v[42:45]
	v_mfma_f32_16x16x32_bf16 v[28:31], v[220:223], v[130:133], v[28:31]
	v_mfma_f32_16x16x32_bf16 v[24:27], v[220:223], v[164:167], v[24:27]
	v_mfma_f32_16x16x32_bf16 v[12:15], v[228:231], v[130:133], v[12:15]
	v_mfma_f32_16x16x32_bf16 v[8:11], v[228:231], v[164:167], v[8:11]
	v_mfma_f32_16x16x32_bf16 v[62:65], v[192:195], v[134:137], v[62:65]
	v_mfma_f32_16x16x32_bf16 v[58:61], v[192:195], v[168:171], v[58:61]
	v_mfma_f32_16x16x32_bf16 v[46:49], v[216:219], v[134:137], v[46:49]
	v_mfma_f32_16x16x32_bf16 v[42:45], v[216:219], v[168:171], v[42:45]
	v_mfma_f32_16x16x32_bf16 v[28:31], v[224:227], v[134:137], v[28:31]
	v_mfma_f32_16x16x32_bf16 v[24:27], v[224:227], v[168:171], v[24:27]
	v_mfma_f32_16x16x32_bf16 v[12:15], v[232:235], v[134:137], v[12:15]
	v_mfma_f32_16x16x32_bf16 v[8:11], v[232:235], v[168:171], v[8:11]
	v_mfma_f32_16x16x32_bf16 v[54:57], v[188:191], v[172:175], v[54:57]
	v_mfma_f32_16x16x32_bf16 v[50:53], v[188:191], v[180:183], v[50:53]
	v_mfma_f32_16x16x32_bf16 v[38:41], v[196:199], v[172:175], v[38:41]
	v_mfma_f32_16x16x32_bf16 v[34:37], v[196:199], v[180:183], v[34:37]
	v_mfma_f32_16x16x32_bf16 v[20:23], v[220:223], v[172:175], v[20:23]
	v_mfma_f32_16x16x32_bf16 v[16:19], v[220:223], v[180:183], v[16:19]
	v_mfma_f32_16x16x32_bf16 v[4:7], v[228:231], v[172:175], v[4:7]
	v_mfma_f32_16x16x32_bf16 v[0:3], v[228:231], v[180:183], v[0:3]
	v_mfma_f32_16x16x32_bf16 v[54:57], v[192:195], v[176:179], v[54:57]
	v_mfma_f32_16x16x32_bf16 v[50:53], v[192:195], v[184:187], v[50:53]
	v_mfma_f32_16x16x32_bf16 v[38:41], v[216:219], v[176:179], v[38:41]
	v_mfma_f32_16x16x32_bf16 v[34:37], v[216:219], v[184:187], v[34:37]
	v_mfma_f32_16x16x32_bf16 v[20:23], v[224:227], v[176:179], v[20:23]
	v_mfma_f32_16x16x32_bf16 v[16:19], v[224:227], v[184:187], v[16:19]
	v_mfma_f32_16x16x32_bf16 v[4:7], v[232:235], v[176:179], v[4:7]
	v_mfma_f32_16x16x32_bf16 v[0:3], v[232:235], v[184:187], v[0:3]
	s_setprio 0
	s_barrier
; #define PG8_STAGE(bufoff, gbase, voff) do { _Pragma("unroll") for (int _i = 0; _i < 2; ++_i) \
;         __builtin_amdgcn_global_load_lds((const unsigned*)((const char*)(gbase) + (voff)[_i]), (PG8_LAS unsigned*)(lds + (bufoff) + ldsw + _i * 8192), 16, 0, 0); } while (0)
; #define PG8_LDA(dst, b, h) do { _Pragma("unroll") for (int m = 0; m < 4; ++m) _Pragma("unroll") for (int k = 0; k < 2; ++k) dst[m][k] = *(const PG8_LAS bf16x8*)(lds + PG8_SA(b, h) + aoff + m * 2048 + k * 1024); } while (0)
; #define PG8_LDB(dst, b, h) do { _Pragma("unroll") for (int n = 0; n < 2; ++n) _Pragma("unroll") for (int k = 0; k < 2; ++k) dst[n][k] = *(const PG8_LAS bf16x8*)(lds + PG8_SB(b, h) + boff + n * 2048 + k * 1024); } while (0)
; #define PG8_WAIT_V(n) asm volatile("s_waitcnt vmcnt(" #n ")" ::: "memory")
; #define PG8_WAIT_L(n) asm volatile("s_waitcnt lgkmcnt(" #n ")" ::: "memory")
; #define PG8_BAR __builtin_amdgcn_s_barrier()
; #define PG8_SCHED __builtin_amdgcn_sched_barrier(0)
; template <class Epi, bool ALIGN_EPI = true>
; __device__ __forceinline__ void gemm_phase(PG8_LAS unsigned char* lds, const Gemm g, const StaticOrder& S, const Epi& E) {
;     ...
;             PG8_LDB(B0, 1, 0); PG8_LDB(B1, 1, 1); PG8_SCHED; PG8_LDA(At, 1, 0); PG8_STAGE(PG8_SA(0, 1), a2 + hstepA, voffA);
;             PG8_WAIT_V(8); PG8_WAIT_L(0); PG8_BAR; PG8_MMA(0, 0, At, B0); PG8_MMA(0, 1, At, B1); PG8_BAR; PG8_SCHED;
.Lp3_1004:
	s_add_i32 s50, 0, 0x18000
	v_add_u32_e32 v32, s50, v143
	s_add_i32 s51, 0, 0x1c000
	ds_read_b128 v[130:133], v32
	ds_read_b128 v[134:137], v32 offset:1024
	ds_read_b128 v[164:167], v32 offset:2048
	ds_read_b128 v[168:171], v32 offset:3072
	v_add_u32_e32 v32, s51, v143
	ds_read_b128 v[172:175], v32
	ds_read_b128 v[176:179], v32 offset:1024
	ds_read_b128 v[180:183], v32 offset:2048
	ds_read_b128 v[184:187], v32 offset:3072
	s_add_u32 s24, s24, 0x40000
	s_addc_u32 s25, s25, 0
	s_mov_b32 m0, s37
	ds_read_b128 v[188:191], v163 offset:32768
	ds_read_b128 v[192:195], v163 offset:33792
	ds_read_b128 v[196:199], v163 offset:34816
	ds_read_b128 v[216:219], v163 offset:35840
	ds_read_b128 v[220:223], v163 offset:36864
	ds_read_b128 v[224:227], v163 offset:37888
	ds_read_b128 v[228:231], v163 offset:38912
	ds_read_b128 v[232:235], v163 offset:39936
	global_load_lds_dwordx4 v138, s[24:25]
	s_mov_b32 m0, s38
	s_nop 0
	global_load_lds_dwordx4 v140, s[24:25]
	s_waitcnt vmcnt(8)
	s_waitcnt lgkmcnt(0)
	s_barrier
	s_setprio 1
	s_waitcnt lgkmcnt(0)
	v_mfma_f32_16x16x32_bf16 v[126:129], v[188:191], v[130:133], v[126:129]
	v_mfma_f32_16x16x32_bf16 v[122:125], v[188:191], v[164:167], v[122:125]
	v_mfma_f32_16x16x32_bf16 v[110:113], v[196:199], v[130:133], v[110:113]
	v_mfma_f32_16x16x32_bf16 v[106:109], v[196:199], v[164:167], v[106:109]
	v_mfma_f32_16x16x32_bf16 v[94:97], v[220:223], v[130:133], v[94:97]
	v_mfma_f32_16x16x32_bf16 v[90:93], v[220:223], v[164:167], v[90:93]
	v_mfma_f32_16x16x32_bf16 v[78:81], v[228:231], v[130:133], v[78:81]
	v_mfma_f32_16x16x32_bf16 v[74:77], v[228:231], v[164:167], v[74:77]
	v_mfma_f32_16x16x32_bf16 v[126:129], v[192:195], v[134:137], v[126:129]
	v_mfma_f32_16x16x32_bf16 v[122:125], v[192:195], v[168:171], v[122:125]
	v_mfma_f32_16x16x32_bf16 v[110:113], v[216:219], v[134:137], v[110:113]
	v_mfma_f32_16x16x32_bf16 v[106:109], v[216:219], v[168:171], v[106:109]
	v_mfma_f32_16x16x32_bf16 v[94:97], v[224:227], v[134:137], v[94:97]
	v_mfma_f32_16x16x32_bf16 v[90:93], v[224:227], v[168:171], v[90:93]
	v_mfma_f32_16x16x32_bf16 v[78:81], v[232:235], v[134:137], v[78:81]
	v_mfma_f32_16x16x32_bf16 v[74:77], v[232:235], v[168:171], v[74:77]
	v_mfma_f32_16x16x32_bf16 v[118:121], v[188:191], v[172:175], v[118:121]
	v_mfma_f32_16x16x32_bf16 v[114:117], v[188:191], v[180:183], v[114:117]
	v_mfma_f32_16x16x32_bf16 v[102:105], v[196:199], v[172:175], v[102:105]
	v_mfma_f32_16x16x32_bf16 v[98:101], v[196:199], v[180:183], v[98:101]
	v_mfma_f32_16x16x32_bf16 v[86:89], v[220:223], v[172:175], v[86:89]
	v_mfma_f32_16x16x32_bf16 v[82:85], v[220:223], v[180:183], v[82:85]
	v_mfma_f32_16x16x32_bf16 v[70:73], v[228:231], v[172:175], v[70:73]
	v_mfma_f32_16x16x32_bf16 v[66:69], v[228:231], v[180:183], v[66:69]
	v_mfma_f32_16x16x32_bf16 v[118:121], v[192:195], v[176:179], v[118:121]
	v_mfma_f32_16x16x32_bf16 v[114:117], v[192:195], v[184:187], v[114:117]
	v_mfma_f32_16x16x32_bf16 v[102:105], v[216:219], v[176:179], v[102:105]
	v_mfma_f32_16x16x32_bf16 v[98:101], v[216:219], v[184:187], v[98:101]
	v_mfma_f32_16x16x32_bf16 v[86:89], v[224:227], v[176:179], v[86:89]
	v_mfma_f32_16x16x32_bf16 v[82:85], v[224:227], v[184:187], v[82:85]
	v_mfma_f32_16x16x32_bf16 v[70:73], v[232:235], v[176:179], v[70:73]
	v_mfma_f32_16x16x32_bf16 v[66:69], v[232:235], v[184:187], v[66:69]
	s_setprio 0
	s_barrier
; #define PG8_STAGE(bufoff, gbase, voff) do { _Pragma("unroll") for (int _i = 0; _i < 2; ++_i) \
;         __builtin_amdgcn_global_load_lds((const unsigned*)((const char*)(gbase) + (voff)[_i]), (PG8_LAS unsigned*)(lds + (bufoff) + ldsw + _i * 8192), 16, 0, 0); } while (0)
; #define PG8_LDA(dst, b, h) do { _Pragma("unroll") for (int m = 0; m < 4; ++m) _Pragma("unroll") for (int k = 0; k < 2; ++k) dst[m][k] = *(const PG8_LAS bf16x8*)(lds + PG8_SA(b, h) + aoff + m * 2048 + k * 1024); } while (0)
; #define PG8_WAIT_V(n) asm volatile("s_waitcnt vmcnt(" #n ")" ::: "memory")
; #define PG8_WAIT_L(n) asm volatile("s_waitcnt lgkmcnt(" #n ")" ::: "memory")
; #define PG8_BAR __builtin_amdgcn_s_barrier()
; #define PG8_SCHED __builtin_amdgcn_sched_barrier(0)
; template <class Epi, bool ALIGN_EPI = true>
; __device__ __forceinline__ void gemm_phase(PG8_LAS unsigned char* lds, const Gemm g, const StaticOrder& S, const Epi& E) {
;     ...
;         for (int t = 0; t < nt; t += 2) {
;             const bool last = (t == nt - 2);
;             const char* a1 = cA + (size_t)(t + 1) * kstep;
;             const char* a2 = last ? nA : cA + (size_t)(t + 2) * kstep; const char* b2 = last ? nB : cB + (size_t)(t + 2) * kstep;
;             const char* a3 = a2 + kstep; const char* b3 = b2 + kstep;
;     ...
;             PG8_LDA(At, 1, 1); PG8_STAGE(PG8_SB(1, 0), b3, voffB); PG8_STAGE(PG8_SB(1, 1), b3 + hstepB, voffB); PG8_STAGE(PG8_SA(1, 0), a3, voffA);
;             PG8_WAIT_V(8); PG8_WAIT_L(0); PG8_BAR; PG8_MMA(1, 0, At, B0); PG8_MMA(1, 1, At, B1); PG8_BAR; PG8_SCHED;
	s_add_i32 s24, s50, s34
	s_mov_b32 m0, s24
	ds_read_b128 v[188:191], v163 offset:49152
	ds_read_b128 v[192:195], v163 offset:50176
	ds_read_b128 v[196:199], v163 offset:51200
	ds_read_b128 v[216:219], v163 offset:52224
	ds_read_b128 v[220:223], v163 offset:53248
	ds_read_b128 v[224:227], v163 offset:54272
	ds_read_b128 v[228:231], v163 offset:55296
	ds_read_b128 v[232:235], v163 offset:56320
	s_add_u32 s98, s22, s60
	s_addc_u32 s99, s23, s61
	global_load_lds_dwordx4 v138, s[98:99]
	s_add_i32 m0, s24, 0x2000
	s_add_u32 s22, s22, 0x40080
	s_addc_u32 s23, s23, 0
	s_add_i32 s24, s51, s34
	s_add_u32 s98, s22, s60
	s_addc_u32 s99, s23, s61
	s_add_u32 s98, s98, 0xfffbff80
	s_addc_u32 s99, s99, -1
	global_load_lds_dwordx4 v140, s[98:99]
	s_mov_b32 m0, s24
	s_nop 0
	global_load_lds_dwordx4 v138, s[22:23]
	s_add_i32 m0, s24, 0x2000
	s_nop 0
	global_load_lds_dwordx4 v140, s[22:23]
	v_lshl_add_u64 v[146:147], v[150:151], 0, s[60:61]
	s_mov_b32 m0, s42
	s_nop 0
	global_load_lds_dwordx4 v[146:147], off
	v_lshl_add_u64 v[146:147], v[200:201], 0, s[60:61]
	s_mov_b32 m0, s43
	s_nop 0
	global_load_lds_dwordx4 v[146:147], off
	s_add_i32 s49, s49, 2
	s_add_u32 s20, s20, 0x100
	s_addc_u32 s21, s21, 0
	s_add_u32 s47, s47, 0x100
	s_addc_u32 s48, s48, 0
	s_add_u32 s22, s20, 0xfffc0080
	s_addc_u32 s23, s21, -1
	s_add_i32 s50, 0, 0x10000
	s_cmp_eq_u32 s49, 12
	s_cselect_b32 s25, s11, s23
	s_cselect_b32 s24, s17, s22
	v_add_u32_e32 v32, s50, v143
	s_cselect_b32 s23, s9, s48
	s_cselect_b32 s22, s19, s47
	s_add_i32 s52, 0, 0x14000
	s_cmp_gt_u32 s49, 13
	s_waitcnt vmcnt(8)
	s_waitcnt lgkmcnt(0)
	s_barrier
	s_setprio 1
	s_waitcnt lgkmcnt(0)
	v_mfma_f32_16x16x32_bf16 v[62:65], v[188:191], v[130:133], v[62:65]
	v_mfma_f32_16x16x32_bf16 v[58:61], v[188:191], v[164:167], v[58:61]
	v_mfma_f32_16x16x32_bf16 v[46:49], v[196:199], v[130:133], v[46:49]
	v_mfma_f32_16x16x32_bf16 v[42:45], v[196:199], v[164:167], v[42:45]
	v_mfma_f32_16x16x32_bf16 v[28:31], v[220:223], v[130:133], v[28:31]
	v_mfma_f32_16x16x32_bf16 v[24:27], v[220:223], v[164:167], v[24:27]
	v_mfma_f32_16x16x32_bf16 v[12:15], v[228:231], v[130:133], v[12:15]
	v_mfma_f32_16x16x32_bf16 v[8:11], v[228:231], v[164:167], v[8:11]
	v_mfma_f32_16x16x32_bf16 v[62:65], v[192:195], v[134:137], v[62:65]
	v_mfma_f32_16x16x32_bf16 v[58:61], v[192:195], v[168:171], v[58:61]
	v_mfma_f32_16x16x32_bf16 v[46:49], v[216:219], v[134:137], v[46:49]
	v_mfma_f32_16x16x32_bf16 v[42:45], v[216:219], v[168:171], v[42:45]
	v_mfma_f32_16x16x32_bf16 v[28:31], v[224:227], v[134:137], v[28:31]
	v_mfma_f32_16x16x32_bf16 v[24:27], v[224:227], v[168:171], v[24:27]
	v_mfma_f32_16x16x32_bf16 v[12:15], v[232:235], v[134:137], v[12:15]
	v_mfma_f32_16x16x32_bf16 v[8:11], v[232:235], v[168:171], v[8:11]
	v_mfma_f32_16x16x32_bf16 v[54:57], v[188:191], v[172:175], v[54:57]
	v_mfma_f32_16x16x32_bf16 v[50:53], v[188:191], v[180:183], v[50:53]
	v_mfma_f32_16x16x32_bf16 v[38:41], v[196:199], v[172:175], v[38:41]
	v_mfma_f32_16x16x32_bf16 v[34:37], v[196:199], v[180:183], v[34:37]
	v_mfma_f32_16x16x32_bf16 v[20:23], v[220:223], v[172:175], v[20:23]
	v_mfma_f32_16x16x32_bf16 v[16:19], v[220:223], v[180:183], v[16:19]
	v_mfma_f32_16x16x32_bf16 v[4:7], v[228:231], v[172:175], v[4:7]
	v_mfma_f32_16x16x32_bf16 v[0:3], v[228:231], v[180:183], v[0:3]
	v_mfma_f32_16x16x32_bf16 v[54:57], v[192:195], v[176:179], v[54:57]
	v_mfma_f32_16x16x32_bf16 v[50:53], v[192:195], v[184:187], v[50:53]
	v_mfma_f32_16x16x32_bf16 v[38:41], v[216:219], v[176:179], v[38:41]
	v_mfma_f32_16x16x32_bf16 v[34:37], v[216:219], v[184:187], v[34:37]
	v_mfma_f32_16x16x32_bf16 v[20:23], v[224:227], v[176:179], v[20:23]
	v_mfma_f32_16x16x32_bf16 v[16:19], v[224:227], v[184:187], v[16:19]
	v_mfma_f32_16x16x32_bf16 v[4:7], v[232:235], v[176:179], v[4:7]
	v_mfma_f32_16x16x32_bf16 v[0:3], v[232:235], v[184:187], v[0:3]
	s_setprio 0
	s_barrier
	s_cbranch_scc0 .Lrot_1004
	s_and_b64 vcc, exec, s[6:7]
	s_cbranch_vccz .LBB0_1007
	s_barrier

; #define PG8_STAGE(bufoff, gbase, voff) do { _Pragma("unroll") for (int _i = 0; _i < 2; ++_i) \
;         __builtin_amdgcn_global_load_lds((const unsigned*)((const char*)(gbase) + (voff)[_i]), (PG8_LAS unsigned*)(lds + (bufoff) + ldsw + _i * 8192), 16, 0, 0); } while (0)
; #define PG8_LDA(dst, b, h) do { _Pragma("unroll") for (int m = 0; m < 4; ++m) _Pragma("unroll") for (int k = 0; k < 2; ++k) dst[m][k] = *(const PG8_LAS bf16x8*)(lds + PG8_SA(b, h) + aoff + m * 2048 + k * 1024); } while (0)
; #define PG8_LDB(dst, b, h) do { _Pragma("unroll") for (int n = 0; n < 2; ++n) _Pragma("unroll") for (int k = 0; k < 2; ++k) dst[n][k] = *(const PG8_LAS bf16x8*)(lds + PG8_SB(b, h) + boff + n * 2048 + k * 1024); } while (0)
; #define PG8_WAIT_V(n) asm volatile("s_waitcnt vmcnt(" #n ")" ::: "memory")
; #define PG8_WAIT_L(n) asm volatile("s_waitcnt lgkmcnt(" #n ")" ::: "memory")
; #define PG8_BAR __builtin_amdgcn_s_barrier()
; #define PG8_SCHED __builtin_amdgcn_sched_barrier(0)
; template <class Epi, bool ALIGN_EPI = true>
; __device__ __forceinline__ void gemm_phase(PG8_LAS unsigned char* lds, const Gemm g, const StaticOrder& S, const Epi& E) {
;     ...
;         for (int t = 0; t < nt; t += 2) {
;             const bool last = (t == nt - 2);
;             const char* a1 = cA + (size_t)(t + 1) * kstep;
;             const char* a2 = last ? nA : cA + (size_t)(t + 2) * kstep; const char* b2 = last ? nB : cB + (size_t)(t + 2) * kstep;
;             const char* a3 = a2 + kstep; const char* b3 = b2 + kstep;
;             PG8_LDB(B0, 0, 0); PG8_LDB(B1, 0, 1); PG8_SCHED; PG8_LDA(At, 0, 0); PG8_STAGE(PG8_SA(1, 1), a1 + hstepA, voffA);
;             PG8_WAIT_V(8); PG8_WAIT_L(0); PG8_BAR; PG8_MMA(0, 0, At, B0); PG8_MMA(0, 1, At, B1); PG8_BAR; PG8_SCHED;
;             PG8_LDA(At, 0, 1); PG8_STAGE(PG8_SB(0, 0), b2, voffB); PG8_STAGE(PG8_SB(0, 1), b2 + hstepB, voffB); PG8_STAGE(PG8_SA(0, 0), a2, voffA);
;             PG8_WAIT_V(8); PG8_WAIT_L(0); PG8_BAR; PG8_MMA(1, 0, At, B0); PG8_MMA(1, 1, At, B1); PG8_BAR; PG8_SCHED;
.LBB0_1829:
	s_add_u32 s43, s6, 0xfffc0080
	s_addc_u32 s44, s7, -1
	s_add_i32 s75, 0, 0x10000
	s_cmp_eq_u32 s37, 12
	s_cselect_b32 s47, s39, s44
	s_cselect_b32 s46, s38, s43
	v_add_u32_e32 v32, s75, v165
	s_cselect_b32 s45, s41, s35
	s_cselect_b32 s44, s40, s9
	s_add_i32 s43, 0, 0x14000
	ds_read_b128 v[142:145], v32
	ds_read_b128 v[148:151], v32 offset:1024
	ds_read_b128 v[158:161], v32 offset:2048
	ds_read_b128 v[168:171], v32 offset:3072
	v_add_u32_e32 v32, s43, v165
	ds_read_b128 v[172:175], v32
	ds_read_b128 v[176:179], v32 offset:1024
	ds_read_b128 v[180:183], v32 offset:2048
	ds_read_b128 v[184:187], v32 offset:3072
	s_add_i32 m0, s59, 0xc000
	ds_read_b128 v[188:191], v167
	ds_read_b128 v[192:195], v167 offset:1024
	ds_read_b128 v[196:199], v167 offset:2048
	ds_read_b128 v[208:211], v167 offset:3072
	ds_read_b128 v[216:219], v167 offset:4096
	ds_read_b128 v[220:223], v167 offset:5120
	ds_read_b128 v[224:227], v167 offset:6144
	ds_read_b128 v[228:231], v167 offset:7168
	global_load_lds_dwordx4 v138, s[6:7]
	s_add_i32 m0, s59, 0xe000
	s_nop 0
	global_load_lds_dwordx4 v140, s[6:7]
	s_waitcnt vmcnt(8)
	s_waitcnt lgkmcnt(0)
	s_barrier
	s_setprio 1
	s_waitcnt lgkmcnt(0)
	v_mfma_f32_16x16x32_bf16 v[126:129], v[142:145], v[188:191], 0
	v_mfma_f32_16x16x32_bf16 v[122:125], v[158:161], v[188:191], 0
	v_mfma_f32_16x16x32_bf16 v[110:113], v[142:145], v[196:199], 0
	v_mfma_f32_16x16x32_bf16 v[106:109], v[158:161], v[196:199], 0
	v_mfma_f32_16x16x32_bf16 v[94:97], v[142:145], v[216:219], 0
	v_mfma_f32_16x16x32_bf16 v[90:93], v[158:161], v[216:219], 0
	v_mfma_f32_16x16x32_bf16 v[78:81], v[142:145], v[224:227], 0
	v_mfma_f32_16x16x32_bf16 v[74:77], v[158:161], v[224:227], 0
	v_mfma_f32_16x16x32_bf16 v[126:129], v[148:151], v[192:195], v[126:129]
	v_mfma_f32_16x16x32_bf16 v[122:125], v[168:171], v[192:195], v[122:125]
	v_mfma_f32_16x16x32_bf16 v[110:113], v[148:151], v[208:211], v[110:113]
	v_mfma_f32_16x16x32_bf16 v[106:109], v[168:171], v[208:211], v[106:109]
	v_mfma_f32_16x16x32_bf16 v[94:97], v[148:151], v[220:223], v[94:97]
	v_mfma_f32_16x16x32_bf16 v[90:93], v[168:171], v[220:223], v[90:93]
	v_mfma_f32_16x16x32_bf16 v[78:81], v[148:151], v[228:231], v[78:81]
	v_mfma_f32_16x16x32_bf16 v[74:77], v[168:171], v[228:231], v[74:77]
	v_mfma_f32_16x16x32_bf16 v[118:121], v[172:175], v[188:191], 0
	v_mfma_f32_16x16x32_bf16 v[114:117], v[180:183], v[188:191], 0
	v_mfma_f32_16x16x32_bf16 v[102:105], v[172:175], v[196:199], 0
	v_mfma_f32_16x16x32_bf16 v[98:101], v[180:183], v[196:199], 0
	v_mfma_f32_16x16x32_bf16 v[86:89], v[172:175], v[216:219], 0
	v_mfma_f32_16x16x32_bf16 v[82:85], v[180:183], v[216:219], 0
	v_mfma_f32_16x16x32_bf16 v[70:73], v[172:175], v[224:227], 0
	v_mfma_f32_16x16x32_bf16 v[66:69], v[180:183], v[224:227], 0
	v_mfma_f32_16x16x32_bf16 v[118:121], v[176:179], v[192:195], v[118:121]
	v_mfma_f32_16x16x32_bf16 v[114:117], v[184:187], v[192:195], v[114:117]
	v_mfma_f32_16x16x32_bf16 v[102:105], v[176:179], v[208:211], v[102:105]
	v_mfma_f32_16x16x32_bf16 v[98:101], v[184:187], v[208:211], v[98:101]
	v_mfma_f32_16x16x32_bf16 v[86:89], v[176:179], v[220:223], v[86:89]
	v_mfma_f32_16x16x32_bf16 v[82:85], v[184:187], v[220:223], v[82:85]
	v_mfma_f32_16x16x32_bf16 v[70:73], v[176:179], v[228:231], v[70:73]
	v_mfma_f32_16x16x32_bf16 v[66:69], v[184:187], v[228:231], v[66:69]
	s_setprio 0
	s_barrier
	s_add_i32 s75, s75, s53
	s_mov_b32 m0, s75
	ds_read_b128 v[188:191], v167 offset:16384
	ds_read_b128 v[192:195], v167 offset:17408
	ds_read_b128 v[196:199], v167 offset:18432
	ds_read_b128 v[208:211], v167 offset:19456
	ds_read_b128 v[216:219], v167 offset:20480
	ds_read_b128 v[220:223], v167 offset:21504
	ds_read_b128 v[224:227], v167 offset:22528
	ds_read_b128 v[228:231], v167 offset:23552
	global_load_lds_dwordx4 v132, s[44:45]
	s_add_i32 m0, s75, 0x2000
	s_add_u32 s76, s44, 0x40000
	s_addc_u32 s77, s45, 0
	s_add_i32 s43, s43, s53
	global_load_lds_dwordx4 v136, s[44:45]
	s_mov_b32 m0, s43
	s_nop 0
	global_load_lds_dwordx4 v132, s[76:77]
	s_add_i32 m0, s43, 0x2000
	s_nop 0
	global_load_lds_dwordx4 v136, s[76:77]
	s_mov_b32 m0, s59
	s_nop 0
	global_load_lds_dwordx4 v130, s[46:47]
	s_mov_b32 m0, s62
	s_nop 0
	global_load_lds_dwordx4 v134, s[46:47]
	s_waitcnt vmcnt(8)
	s_waitcnt lgkmcnt(0)
	s_barrier
	s_setprio 1
	s_waitcnt lgkmcnt(0)
	v_mfma_f32_16x16x32_bf16 v[62:65], v[142:145], v[188:191], 0
	v_mfma_f32_16x16x32_bf16 v[58:61], v[158:161], v[188:191], 0
	v_mfma_f32_16x16x32_bf16 v[46:49], v[142:145], v[196:199], 0
	v_mfma_f32_16x16x32_bf16 v[42:45], v[158:161], v[196:199], 0
	v_mfma_f32_16x16x32_bf16 v[28:31], v[142:145], v[216:219], 0
	v_mfma_f32_16x16x32_bf16 v[24:27], v[158:161], v[216:219], 0
	v_mfma_f32_16x16x32_bf16 v[12:15], v[142:145], v[224:227], 0
	v_mfma_f32_16x16x32_bf16 v[8:11], v[158:161], v[224:227], 0
	v_mfma_f32_16x16x32_bf16 v[62:65], v[148:151], v[192:195], v[62:65]
	v_mfma_f32_16x16x32_bf16 v[58:61], v[168:171], v[192:195], v[58:61]
	v_mfma_f32_16x16x32_bf16 v[46:49], v[148:151], v[208:211], v[46:49]
	v_mfma_f32_16x16x32_bf16 v[42:45], v[168:171], v[208:211], v[42:45]
	v_mfma_f32_16x16x32_bf16 v[28:31], v[148:151], v[220:223], v[28:31]
	v_mfma_f32_16x16x32_bf16 v[24:27], v[168:171], v[220:223], v[24:27]
	v_mfma_f32_16x16x32_bf16 v[12:15], v[148:151], v[228:231], v[12:15]
	v_mfma_f32_16x16x32_bf16 v[8:11], v[168:171], v[228:231], v[8:11]
	v_mfma_f32_16x16x32_bf16 v[54:57], v[172:175], v[188:191], 0
	v_mfma_f32_16x16x32_bf16 v[50:53], v[180:183], v[188:191], 0
	v_mfma_f32_16x16x32_bf16 v[38:41], v[172:175], v[196:199], 0
	v_mfma_f32_16x16x32_bf16 v[34:37], v[180:183], v[196:199], 0
	v_mfma_f32_16x16x32_bf16 v[20:23], v[172:175], v[216:219], 0
	v_mfma_f32_16x16x32_bf16 v[16:19], v[180:183], v[216:219], 0
	v_mfma_f32_16x16x32_bf16 v[4:7], v[172:175], v[224:227], 0
	v_mfma_f32_16x16x32_bf16 v[0:3], v[180:183], v[224:227], 0
	v_mfma_f32_16x16x32_bf16 v[54:57], v[176:179], v[192:195], v[54:57]
	v_mfma_f32_16x16x32_bf16 v[50:53], v[184:187], v[192:195], v[50:53]
	v_mfma_f32_16x16x32_bf16 v[38:41], v[176:179], v[208:211], v[38:41]
	v_mfma_f32_16x16x32_bf16 v[34:37], v[184:187], v[208:211], v[34:37]
	v_mfma_f32_16x16x32_bf16 v[20:23], v[176:179], v[220:223], v[20:23]
	v_mfma_f32_16x16x32_bf16 v[16:19], v[184:187], v[220:223], v[16:19]
	v_mfma_f32_16x16x32_bf16 v[4:7], v[176:179], v[228:231], v[4:7]
	v_mfma_f32_16x16x32_bf16 v[0:3], v[184:187], v[228:231], v[0:3]
	s_setprio 0
	s_barrier
	s_branch .Lp3_1829
; #define PG8_STAGE(bufoff, gbase, voff) do { _Pragma("unroll") for (int _i = 0; _i < 2; ++_i) \
;         __builtin_amdgcn_global_load_lds((const unsigned*)((const char*)(gbase) + (voff)[_i]), (PG8_LAS unsigned*)(lds + (bufoff) + ldsw + _i * 8192), 16, 0, 0); } while (0)
; #define PG8_LDA(dst, b, h) do { _Pragma("unroll") for (int m = 0; m < 4; ++m) _Pragma("unroll") for (int k = 0; k < 2; ++k) dst[m][k] = *(const PG8_LAS bf16x8*)(lds + PG8_SA(b, h) + aoff + m * 2048 + k * 1024); } while (0)
; #define PG8_LDB(dst, b, h) do { _Pragma("unroll") for (int n = 0; n < 2; ++n) _Pragma("unroll") for (int k = 0; k < 2; ++k) dst[n][k] = *(const PG8_LAS bf16x8*)(lds + PG8_SB(b, h) + boff + n * 2048 + k * 1024); } while (0)
; #define PG8_WAIT_V(n) asm volatile("s_waitcnt vmcnt(" #n ")" ::: "memory")
; #define PG8_WAIT_L(n) asm volatile("s_waitcnt lgkmcnt(" #n ")" ::: "memory")
; #define PG8_BAR __builtin_amdgcn_s_barrier()
; #define PG8_SCHED __builtin_amdgcn_sched_barrier(0)
; template <class Epi, bool ALIGN_EPI = true>
; __device__ __forceinline__ void gemm_phase(PG8_LAS unsigned char* lds, const Gemm g, const StaticOrder& S, const Epi& E) {
;     ...
;         for (int t = 0; t < nt; t += 2) {
;             const bool last = (t == nt - 2);
;             const char* a1 = cA + (size_t)(t + 1) * kstep;
;             const char* a2 = last ? nA : cA + (size_t)(t + 2) * kstep; const char* b2 = last ? nB : cB + (size_t)(t + 2) * kstep;
;             const char* a3 = a2 + kstep; const char* b3 = b2 + kstep;
;             PG8_LDB(B0, 0, 0); PG8_LDB(B1, 0, 1); PG8_SCHED; PG8_LDA(At, 0, 0); PG8_STAGE(PG8_SA(1, 1), a1 + hstepA, voffA);
;             PG8_WAIT_V(8); PG8_WAIT_L(0); PG8_BAR; PG8_MMA(0, 0, At, B0); PG8_MMA(0, 1, At, B1); PG8_BAR; PG8_SCHED;
;             PG8_LDA(At, 0, 1); PG8_STAGE(PG8_SB(0, 0), b2, voffB); PG8_STAGE(PG8_SB(0, 1), b2 + hstepB, voffB); PG8_STAGE(PG8_SA(0, 0), a2, voffA);
;             PG8_WAIT_V(8); PG8_WAIT_L(0); PG8_BAR; PG8_MMA(1, 0, At, B0); PG8_MMA(1, 1, At, B1); PG8_BAR; PG8_SCHED;
.Lrot_1829:
	ds_read_b128 v[142:145], v32
	ds_read_b128 v[148:151], v32 offset:1024
	ds_read_b128 v[158:161], v32 offset:2048
	ds_read_b128 v[168:171], v32 offset:3072
	v_add_u32_e32 v32, s43, v165
	ds_read_b128 v[172:175], v32
	ds_read_b128 v[176:179], v32 offset:1024
	ds_read_b128 v[180:183], v32 offset:2048
	ds_read_b128 v[184:187], v32 offset:3072
	s_add_i32 m0, s59, 0xc000
	ds_read_b128 v[188:191], v167
	ds_read_b128 v[192:195], v167 offset:1024
	ds_read_b128 v[196:199], v167 offset:2048
	ds_read_b128 v[208:211], v167 offset:3072
	ds_read_b128 v[216:219], v167 offset:4096
	ds_read_b128 v[220:223], v167 offset:5120
	ds_read_b128 v[224:227], v167 offset:6144
	ds_read_b128 v[228:231], v167 offset:7168
	global_load_lds_dwordx4 v138, s[6:7]
	s_add_i32 m0, s59, 0xe000
	s_nop 0
	global_load_lds_dwordx4 v140, s[6:7]
	s_waitcnt vmcnt(8)
	s_waitcnt lgkmcnt(0)
	s_barrier
	s_setprio 1
	s_waitcnt lgkmcnt(0)
	v_mfma_f32_16x16x32_bf16 v[126:129], v[142:145], v[188:191], v[126:129]
	v_mfma_f32_16x16x32_bf16 v[122:125], v[158:161], v[188:191], v[122:125]
	v_mfma_f32_16x16x32_bf16 v[110:113], v[142:145], v[196:199], v[110:113]
	v_mfma_f32_16x16x32_bf16 v[106:109], v[158:161], v[196:199], v[106:109]
	v_mfma_f32_16x16x32_bf16 v[94:97], v[142:145], v[216:219], v[94:97]
	v_mfma_f32_16x16x32_bf16 v[90:93], v[158:161], v[216:219], v[90:93]
	v_mfma_f32_16x16x32_bf16 v[78:81], v[142:145], v[224:227], v[78:81]
	v_mfma_f32_16x16x32_bf16 v[74:77], v[158:161], v[224:227], v[74:77]
	v_mfma_f32_16x16x32_bf16 v[126:129], v[148:151], v[192:195], v[126:129]
	v_mfma_f32_16x16x32_bf16 v[122:125], v[168:171], v[192:195], v[122:125]
	v_mfma_f32_16x16x32_bf16 v[110:113], v[148:151], v[208:211], v[110:113]
	v_mfma_f32_16x16x32_bf16 v[106:109], v[168:171], v[208:211], v[106:109]
	v_mfma_f32_16x16x32_bf16 v[94:97], v[148:151], v[220:223], v[94:97]
	v_mfma_f32_16x16x32_bf16 v[90:93], v[168:171], v[220:223], v[90:93]
	v_mfma_f32_16x16x32_bf16 v[78:81], v[148:151], v[228:231], v[78:81]
	v_mfma_f32_16x16x32_bf16 v[74:77], v[168:171], v[228:231], v[74:77]
	v_mfma_f32_16x16x32_bf16 v[118:121], v[172:175], v[188:191], v[118:121]
	v_mfma_f32_16x16x32_bf16 v[114:117], v[180:183], v[188:191], v[114:117]
	v_mfma_f32_16x16x32_bf16 v[102:105], v[172:175], v[196:199], v[102:105]
	v_mfma_f32_16x16x32_bf16 v[98:101], v[180:183], v[196:199], v[98:101]
	v_mfma_f32_16x16x32_bf16 v[86:89], v[172:175], v[216:219], v[86:89]
	v_mfma_f32_16x16x32_bf16 v[82:85], v[180:183], v[216:219], v[82:85]
	v_mfma_f32_16x16x32_bf16 v[70:73], v[172:175], v[224:227], v[70:73]
	v_mfma_f32_16x16x32_bf16 v[66:69], v[180:183], v[224:227], v[66:69]
	v_mfma_f32_16x16x32_bf16 v[118:121], v[176:179], v[192:195], v[118:121]
	v_mfma_f32_16x16x32_bf16 v[114:117], v[184:187], v[192:195], v[114:117]
	v_mfma_f32_16x16x32_bf16 v[102:105], v[176:179], v[208:211], v[102:105]
	v_mfma_f32_16x16x32_bf16 v[98:101], v[184:187], v[208:211], v[98:101]
	v_mfma_f32_16x16x32_bf16 v[86:89], v[176:179], v[220:223], v[86:89]
	v_mfma_f32_16x16x32_bf16 v[82:85], v[184:187], v[220:223], v[82:85]
	v_mfma_f32_16x16x32_bf16 v[70:73], v[176:179], v[228:231], v[70:73]
	v_mfma_f32_16x16x32_bf16 v[66:69], v[184:187], v[228:231], v[66:69]
	s_setprio 0
	s_barrier
	s_add_i32 s75, s75, s53
	s_mov_b32 m0, s75
	ds_read_b128 v[188:191], v167 offset:16384
	ds_read_b128 v[192:195], v167 offset:17408
	ds_read_b128 v[196:199], v167 offset:18432
	ds_read_b128 v[208:211], v167 offset:19456
	ds_read_b128 v[216:219], v167 offset:20480
	ds_read_b128 v[220:223], v167 offset:21504
	ds_read_b128 v[224:227], v167 offset:22528
	ds_read_b128 v[228:231], v167 offset:23552
	global_load_lds_dwordx4 v132, s[44:45]
	s_add_i32 m0, s75, 0x2000
	s_add_u32 s76, s44, 0x40000
	s_addc_u32 s77, s45, 0
	s_add_i32 s43, s43, s53
	global_load_lds_dwordx4 v136, s[44:45]
	s_mov_b32 m0, s43
	s_nop 0
	global_load_lds_dwordx4 v132, s[76:77]
	s_add_i32 m0, s43, 0x2000
	s_nop 0
	global_load_lds_dwordx4 v136, s[76:77]
	s_mov_b32 m0, s59
	s_nop 0
	global_load_lds_dwordx4 v130, s[46:47]
	s_mov_b32 m0, s62
	s_nop 0
	global_load_lds_dwordx4 v134, s[46:47]
	s_waitcnt vmcnt(8)
	s_waitcnt lgkmcnt(0)
	s_barrier
	s_setprio 1
	s_waitcnt lgkmcnt(0)
	v_mfma_f32_16x16x32_bf16 v[62:65], v[142:145], v[188:191], v[62:65]
	v_mfma_f32_16x16x32_bf16 v[58:61], v[158:161], v[188:191], v[58:61]
	v_mfma_f32_16x16x32_bf16 v[46:49], v[142:145], v[196:199], v[46:49]
	v_mfma_f32_16x16x32_bf16 v[42:45], v[158:161], v[196:199], v[42:45]
	v_mfma_f32_16x16x32_bf16 v[28:31], v[142:145], v[216:219], v[28:31]
	v_mfma_f32_16x16x32_bf16 v[24:27], v[158:161], v[216:219], v[24:27]
	v_mfma_f32_16x16x32_bf16 v[12:15], v[142:145], v[224:227], v[12:15]
	v_mfma_f32_16x16x32_bf16 v[8:11], v[158:161], v[224:227], v[8:11]
	v_mfma_f32_16x16x32_bf16 v[62:65], v[148:151], v[192:195], v[62:65]
	v_mfma_f32_16x16x32_bf16 v[58:61], v[168:171], v[192:195], v[58:61]
	v_mfma_f32_16x16x32_bf16 v[46:49], v[148:151], v[208:211], v[46:49]
	v_mfma_f32_16x16x32_bf16 v[42:45], v[168:171], v[208:211], v[42:45]
	v_mfma_f32_16x16x32_bf16 v[28:31], v[148:151], v[220:223], v[28:31]
	v_mfma_f32_16x16x32_bf16 v[24:27], v[168:171], v[220:223], v[24:27]
	v_mfma_f32_16x16x32_bf16 v[12:15], v[148:151], v[228:231], v[12:15]
	v_mfma_f32_16x16x32_bf16 v[8:11], v[168:171], v[228:231], v[8:11]
	v_mfma_f32_16x16x32_bf16 v[54:57], v[172:175], v[188:191], v[54:57]
	v_mfma_f32_16x16x32_bf16 v[50:53], v[180:183], v[188:191], v[50:53]
	v_mfma_f32_16x16x32_bf16 v[38:41], v[172:175], v[196:199], v[38:41]
	v_mfma_f32_16x16x32_bf16 v[34:37], v[180:183], v[196:199], v[34:37]
	v_mfma_f32_16x16x32_bf16 v[20:23], v[172:175], v[216:219], v[20:23]
	v_mfma_f32_16x16x32_bf16 v[16:19], v[180:183], v[216:219], v[16:19]
	v_mfma_f32_16x16x32_bf16 v[4:7], v[172:175], v[224:227], v[4:7]
	v_mfma_f32_16x16x32_bf16 v[0:3], v[180:183], v[224:227], v[0:3]
	v_mfma_f32_16x16x32_bf16 v[54:57], v[176:179], v[192:195], v[54:57]
	v_mfma_f32_16x16x32_bf16 v[50:53], v[184:187], v[192:195], v[50:53]
	v_mfma_f32_16x16x32_bf16 v[38:41], v[176:179], v[208:211], v[38:41]
	v_mfma_f32_16x16x32_bf16 v[34:37], v[184:187], v[208:211], v[34:37]
	v_mfma_f32_16x16x32_bf16 v[20:23], v[176:179], v[220:223], v[20:23]
	v_mfma_f32_16x16x32_bf16 v[16:19], v[184:187], v[220:223], v[16:19]
	v_mfma_f32_16x16x32_bf16 v[4:7], v[176:179], v[228:231], v[4:7]
	v_mfma_f32_16x16x32_bf16 v[0:3], v[184:187], v[228:231], v[0:3]
	s_setprio 0
	s_barrier
; #define PG8_STAGE(bufoff, gbase, voff) do { _Pragma("unroll") for (int _i = 0; _i < 2; ++_i) \
;         __builtin_amdgcn_global_load_lds((const unsigned*)((const char*)(gbase) + (voff)[_i]), (PG8_LAS unsigned*)(lds + (bufoff) + ldsw + _i * 8192), 16, 0, 0); } while (0)
; #define PG8_LDA(dst, b, h) do { _Pragma("unroll") for (int m = 0; m < 4; ++m) _Pragma("unroll") for (int k = 0; k < 2; ++k) dst[m][k] = *(const PG8_LAS bf16x8*)(lds + PG8_SA(b, h) + aoff + m * 2048 + k * 1024); } while (0)
; #define PG8_LDB(dst, b, h) do { _Pragma("unroll") for (int n = 0; n < 2; ++n) _Pragma("unroll") for (int k = 0; k < 2; ++k) dst[n][k] = *(const PG8_LAS bf16x8*)(lds + PG8_SB(b, h) + boff + n * 2048 + k * 1024); } while (0)
; #define PG8_WAIT_V(n) asm volatile("s_waitcnt vmcnt(" #n ")" ::: "memory")
; #define PG8_WAIT_L(n) asm volatile("s_waitcnt lgkmcnt(" #n ")" ::: "memory")
; #define PG8_BAR __builtin_amdgcn_s_barrier()
; #define PG8_SCHED __builtin_amdgcn_sched_barrier(0)
; template <class Epi, bool ALIGN_EPI = true>
; __device__ __forceinline__ void gemm_phase(PG8_LAS unsigned char* lds, const Gemm g, const StaticOrder& S, const Epi& E) {
;     ...
;             PG8_LDB(B0, 1, 0); PG8_LDB(B1, 1, 1); PG8_SCHED; PG8_LDA(At, 1, 0); PG8_STAGE(PG8_SA(0, 1), a2 + hstepA, voffA);
;             PG8_WAIT_V(8); PG8_WAIT_L(0); PG8_BAR; PG8_MMA(0, 0, At, B0); PG8_MMA(0, 1, At, B1); PG8_BAR; PG8_SCHED;
.Lp3_1829:
	s_add_i32 s43, 0, 0x18000
	v_add_u32_e32 v32, s43, v165
	s_add_i32 s75, 0, 0x1c000
	ds_read_b128 v[142:145], v32
	ds_read_b128 v[148:151], v32 offset:1024
	ds_read_b128 v[158:161], v32 offset:2048
	ds_read_b128 v[168:171], v32 offset:3072
	v_add_u32_e32 v32, s75, v165
	ds_read_b128 v[172:175], v32
	ds_read_b128 v[176:179], v32 offset:1024
	ds_read_b128 v[180:183], v32 offset:2048
	ds_read_b128 v[184:187], v32 offset:3072
	s_add_u32 s46, s46, 0x40000
	s_addc_u32 s47, s47, 0
	s_mov_b32 m0, s63
	ds_read_b128 v[188:191], v167 offset:32768
	ds_read_b128 v[192:195], v167 offset:33792
	ds_read_b128 v[196:199], v167 offset:34816
	ds_read_b128 v[208:211], v167 offset:35840
	ds_read_b128 v[216:219], v167 offset:36864
	ds_read_b128 v[220:223], v167 offset:37888
	ds_read_b128 v[224:227], v167 offset:38912
	ds_read_b128 v[228:231], v167 offset:39936
	global_load_lds_dwordx4 v130, s[46:47]
	s_mov_b32 m0, s66
	s_nop 0
	global_load_lds_dwordx4 v134, s[46:47]
	s_waitcnt vmcnt(8)
	s_waitcnt lgkmcnt(0)
	s_barrier
	s_setprio 1
	s_waitcnt lgkmcnt(0)
	v_mfma_f32_16x16x32_bf16 v[126:129], v[142:145], v[188:191], v[126:129]
	v_mfma_f32_16x16x32_bf16 v[122:125], v[158:161], v[188:191], v[122:125]
	v_mfma_f32_16x16x32_bf16 v[110:113], v[142:145], v[196:199], v[110:113]
	v_mfma_f32_16x16x32_bf16 v[106:109], v[158:161], v[196:199], v[106:109]
	v_mfma_f32_16x16x32_bf16 v[94:97], v[142:145], v[216:219], v[94:97]
	v_mfma_f32_16x16x32_bf16 v[90:93], v[158:161], v[216:219], v[90:93]
	v_mfma_f32_16x16x32_bf16 v[78:81], v[142:145], v[224:227], v[78:81]
	v_mfma_f32_16x16x32_bf16 v[74:77], v[158:161], v[224:227], v[74:77]
	v_mfma_f32_16x16x32_bf16 v[126:129], v[148:151], v[192:195], v[126:129]
	v_mfma_f32_16x16x32_bf16 v[122:125], v[168:171], v[192:195], v[122:125]
	v_mfma_f32_16x16x32_bf16 v[110:113], v[148:151], v[208:211], v[110:113]
	v_mfma_f32_16x16x32_bf16 v[106:109], v[168:171], v[208:211], v[106:109]
	v_mfma_f32_16x16x32_bf16 v[94:97], v[148:151], v[220:223], v[94:97]
	v_mfma_f32_16x16x32_bf16 v[90:93], v[168:171], v[220:223], v[90:93]
	v_mfma_f32_16x16x32_bf16 v[78:81], v[148:151], v[228:231], v[78:81]
	v_mfma_f32_16x16x32_bf16 v[74:77], v[168:171], v[228:231], v[74:77]
	v_mfma_f32_16x16x32_bf16 v[118:121], v[172:175], v[188:191], v[118:121]
	v_mfma_f32_16x16x32_bf16 v[114:117], v[180:183], v[188:191], v[114:117]
	v_mfma_f32_16x16x32_bf16 v[102:105], v[172:175], v[196:199], v[102:105]
	v_mfma_f32_16x16x32_bf16 v[98:101], v[180:183], v[196:199], v[98:101]
	v_mfma_f32_16x16x32_bf16 v[86:89], v[172:175], v[216:219], v[86:89]
	v_mfma_f32_16x16x32_bf16 v[82:85], v[180:183], v[216:219], v[82:85]
	v_mfma_f32_16x16x32_bf16 v[70:73], v[172:175], v[224:227], v[70:73]
	v_mfma_f32_16x16x32_bf16 v[66:69], v[180:183], v[224:227], v[66:69]
	v_mfma_f32_16x16x32_bf16 v[118:121], v[176:179], v[192:195], v[118:121]
	v_mfma_f32_16x16x32_bf16 v[114:117], v[184:187], v[192:195], v[114:117]
	v_mfma_f32_16x16x32_bf16 v[102:105], v[176:179], v[208:211], v[102:105]
	v_mfma_f32_16x16x32_bf16 v[98:101], v[184:187], v[208:211], v[98:101]
	v_mfma_f32_16x16x32_bf16 v[86:89], v[176:179], v[220:223], v[86:89]
	v_mfma_f32_16x16x32_bf16 v[82:85], v[184:187], v[220:223], v[82:85]
	v_mfma_f32_16x16x32_bf16 v[70:73], v[176:179], v[228:231], v[70:73]
	v_mfma_f32_16x16x32_bf16 v[66:69], v[184:187], v[228:231], v[66:69]
	s_setprio 0
	s_barrier
; #define PG8_STAGE(bufoff, gbase, voff) do { _Pragma("unroll") for (int _i = 0; _i < 2; ++_i) \
;         __builtin_amdgcn_global_load_lds((const unsigned*)((const char*)(gbase) + (voff)[_i]), (PG8_LAS unsigned*)(lds + (bufoff) + ldsw + _i * 8192), 16, 0, 0); } while (0)
; #define PG8_LDA(dst, b, h) do { _Pragma("unroll") for (int m = 0; m < 4; ++m) _Pragma("unroll") for (int k = 0; k < 2; ++k) dst[m][k] = *(const PG8_LAS bf16x8*)(lds + PG8_SA(b, h) + aoff + m * 2048 + k * 1024); } while (0)
; #define PG8_WAIT_V(n) asm volatile("s_waitcnt vmcnt(" #n ")" ::: "memory")
; #define PG8_WAIT_L(n) asm volatile("s_waitcnt lgkmcnt(" #n ")" ::: "memory")
; #define PG8_BAR __builtin_amdgcn_s_barrier()
; #define PG8_SCHED __builtin_amdgcn_sched_barrier(0)
; template <class Epi, bool ALIGN_EPI = true>
; __device__ __forceinline__ void gemm_phase(PG8_LAS unsigned char* lds, const Gemm g, const StaticOrder& S, const Epi& E) {
;     ...
;         for (int t = 0; t < nt; t += 2) {
;             const bool last = (t == nt - 2);
;             const char* a1 = cA + (size_t)(t + 1) * kstep;
;             const char* a2 = last ? nA : cA + (size_t)(t + 2) * kstep; const char* b2 = last ? nB : cB + (size_t)(t + 2) * kstep;
;             const char* a3 = a2 + kstep; const char* b3 = b2 + kstep;
;     ...
;             PG8_LDA(At, 1, 1); PG8_STAGE(PG8_SB(1, 0), b3, voffB); PG8_STAGE(PG8_SB(1, 1), b3 + hstepB, voffB); PG8_STAGE(PG8_SA(1, 0), a3, voffA);
;             PG8_WAIT_V(8); PG8_WAIT_L(0); PG8_BAR; PG8_MMA(1, 0, At, B0); PG8_MMA(1, 1, At, B1); PG8_BAR; PG8_SCHED;
	s_add_i32 s43, s43, s53
	s_mov_b32 m0, s43
	ds_read_b128 v[188:191], v167 offset:49152
	ds_read_b128 v[192:195], v167 offset:50176
	ds_read_b128 v[196:199], v167 offset:51200
	ds_read_b128 v[208:211], v167 offset:52224
	ds_read_b128 v[216:219], v167 offset:53248
	ds_read_b128 v[220:223], v167 offset:54272
	ds_read_b128 v[224:227], v167 offset:55296
	ds_read_b128 v[228:231], v167 offset:56320
	s_add_u32 s98, s44, s60
	s_addc_u32 s99, s45, s61
	global_load_lds_dwordx4 v132, s[98:99]
	s_add_i32 m0, s43, 0x2000
	s_add_u32 s44, s44, 0x40080
	s_addc_u32 s45, s45, 0
	s_add_i32 s43, s75, s53
	s_add_u32 s98, s44, s60
	s_addc_u32 s99, s45, s61
	s_add_u32 s98, s98, 0xfffbff80
	s_addc_u32 s99, s99, -1
	global_load_lds_dwordx4 v136, s[98:99]
	s_mov_b32 m0, s43
	s_nop 0
	global_load_lds_dwordx4 v132, s[44:45]
	s_add_i32 m0, s43, 0x2000
	s_nop 0
	global_load_lds_dwordx4 v136, s[44:45]
	s_mov_b32 m0, s70
	s_nop 0
	s_add_u32 s98, s46, s60
	s_addc_u32 s99, s47, s61
	s_add_u32 s98, s98, 0xfffc0000
	s_addc_u32 s99, s99, -1
	global_load_lds_dwordx4 v130, s[98:99]
	s_mov_b32 m0, s71
	s_nop 0
	s_add_u32 s98, s46, s60
	s_addc_u32 s99, s47, s61
	s_add_u32 s98, s98, 0xfffc0000
	s_addc_u32 s99, s99, -1
	global_load_lds_dwordx4 v134, s[98:99]
	s_add_i32 s37, s37, 2
	s_add_u32 s6, s6, 0x100
	s_addc_u32 s7, s7, 0
	s_add_u32 s9, s9, 0x100
	s_addc_u32 s35, s35, 0
	s_add_u32 s43, s6, 0xfffc0080
	s_addc_u32 s44, s7, -1
	s_add_i32 s75, 0, 0x10000
	s_cmp_eq_u32 s37, 12
	s_cselect_b32 s47, s39, s44
	s_cselect_b32 s46, s38, s43
	v_add_u32_e32 v32, s75, v165
	s_cselect_b32 s45, s41, s35
	s_cselect_b32 s44, s40, s9
	s_add_i32 s43, 0, 0x14000
	s_cmp_gt_u32 s37, 13
	s_waitcnt vmcnt(8)
	s_waitcnt lgkmcnt(0)
	s_barrier
	s_setprio 1
	s_waitcnt lgkmcnt(0)
	v_mfma_f32_16x16x32_bf16 v[62:65], v[142:145], v[188:191], v[62:65]
	v_mfma_f32_16x16x32_bf16 v[58:61], v[158:161], v[188:191], v[58:61]
	v_mfma_f32_16x16x32_bf16 v[46:49], v[142:145], v[196:199], v[46:49]
	v_mfma_f32_16x16x32_bf16 v[42:45], v[158:161], v[196:199], v[42:45]
	v_mfma_f32_16x16x32_bf16 v[28:31], v[142:145], v[216:219], v[28:31]
	v_mfma_f32_16x16x32_bf16 v[24:27], v[158:161], v[216:219], v[24:27]
	v_mfma_f32_16x16x32_bf16 v[12:15], v[142:145], v[224:227], v[12:15]
	v_mfma_f32_16x16x32_bf16 v[8:11], v[158:161], v[224:227], v[8:11]
	v_mfma_f32_16x16x32_bf16 v[62:65], v[148:151], v[192:195], v[62:65]
	v_mfma_f32_16x16x32_bf16 v[58:61], v[168:171], v[192:195], v[58:61]
	v_mfma_f32_16x16x32_bf16 v[46:49], v[148:151], v[208:211], v[46:49]
	v_mfma_f32_16x16x32_bf16 v[42:45], v[168:171], v[208:211], v[42:45]
	v_mfma_f32_16x16x32_bf16 v[28:31], v[148:151], v[220:223], v[28:31]
	v_mfma_f32_16x16x32_bf16 v[24:27], v[168:171], v[220:223], v[24:27]
	v_mfma_f32_16x16x32_bf16 v[12:15], v[148:151], v[228:231], v[12:15]
	v_mfma_f32_16x16x32_bf16 v[8:11], v[168:171], v[228:231], v[8:11]
	v_mfma_f32_16x16x32_bf16 v[54:57], v[172:175], v[188:191], v[54:57]
	v_mfma_f32_16x16x32_bf16 v[50:53], v[180:183], v[188:191], v[50:53]
	v_mfma_f32_16x16x32_bf16 v[38:41], v[172:175], v[196:199], v[38:41]
	v_mfma_f32_16x16x32_bf16 v[34:37], v[180:183], v[196:199], v[34:37]
	v_mfma_f32_16x16x32_bf16 v[20:23], v[172:175], v[216:219], v[20:23]
	v_mfma_f32_16x16x32_bf16 v[16:19], v[180:183], v[216:219], v[16:19]
	v_mfma_f32_16x16x32_bf16 v[4:7], v[172:175], v[224:227], v[4:7]
	v_mfma_f32_16x16x32_bf16 v[0:3], v[180:183], v[224:227], v[0:3]
	v_mfma_f32_16x16x32_bf16 v[54:57], v[176:179], v[192:195], v[54:57]
	v_mfma_f32_16x16x32_bf16 v[50:53], v[184:187], v[192:195], v[50:53]
	v_mfma_f32_16x16x32_bf16 v[38:41], v[176:179], v[208:211], v[38:41]
	v_mfma_f32_16x16x32_bf16 v[34:37], v[184:187], v[208:211], v[34:37]
	v_mfma_f32_16x16x32_bf16 v[20:23], v[176:179], v[220:223], v[20:23]
	v_mfma_f32_16x16x32_bf16 v[16:19], v[184:187], v[220:223], v[16:19]
	v_mfma_f32_16x16x32_bf16 v[4:7], v[176:179], v[228:231], v[4:7]
	v_mfma_f32_16x16x32_bf16 v[0:3], v[184:187], v[228:231], v[0:3]
	s_setprio 0
	s_barrier
	s_cbranch_scc0 .Lrot_1829
	s_and_b64 vcc, exec, s[26:27]
	s_cbranch_vccz .LBB0_1832
	s_barrier

; #define PG8_STAGE(bufoff, gbase, voff) do { _Pragma("unroll") for (int _i = 0; _i < 2; ++_i) \
;         __builtin_amdgcn_global_load_lds((const unsigned*)((const char*)(gbase) + (voff)[_i]), (PG8_LAS unsigned*)(lds + (bufoff) + ldsw + _i * 8192), 16, 0, 0); } while (0)
; #define PG8_LDA(dst, b, h) do { _Pragma("unroll") for (int m = 0; m < 4; ++m) _Pragma("unroll") for (int k = 0; k < 2; ++k) dst[m][k] = *(const PG8_LAS bf16x8*)(lds + PG8_SA(b, h) + aoff + m * 2048 + k * 1024); } while (0)
; #define PG8_LDB(dst, b, h) do { _Pragma("unroll") for (int n = 0; n < 2; ++n) _Pragma("unroll") for (int k = 0; k < 2; ++k) dst[n][k] = *(const PG8_LAS bf16x8*)(lds + PG8_SB(b, h) + boff + n * 2048 + k * 1024); } while (0)
; #define PG8_WAIT_V(n) asm volatile("s_waitcnt vmcnt(" #n ")" ::: "memory")
; #define PG8_WAIT_L(n) asm volatile("s_waitcnt lgkmcnt(" #n ")" ::: "memory")
; #define PG8_BAR __builtin_amdgcn_s_barrier()
; #define PG8_SCHED __builtin_amdgcn_sched_barrier(0)
; template <class Epi, bool ALIGN_EPI = true>
; __device__ __forceinline__ void gemm_phase(PG8_LAS unsigned char* lds, const Gemm g, const StaticOrder& S, const Epi& E) {
;     ...
;         for (int t = 0; t < nt; t += 2) {
;             const bool last = (t == nt - 2);
;             const char* a1 = cA + (size_t)(t + 1) * kstep;
;             const char* a2 = last ? nA : cA + (size_t)(t + 2) * kstep; const char* b2 = last ? nB : cB + (size_t)(t + 2) * kstep;
;             const char* a3 = a2 + kstep; const char* b3 = b2 + kstep;
;             PG8_LDB(B0, 0, 0); PG8_LDB(B1, 0, 1); PG8_SCHED; PG8_LDA(At, 0, 0); PG8_STAGE(PG8_SA(1, 1), a1 + hstepA, voffA);
;             PG8_WAIT_V(8); PG8_WAIT_L(0); PG8_BAR; PG8_MMA(0, 0, At, B0); PG8_MMA(0, 1, At, B1); PG8_BAR; PG8_SCHED;
;             PG8_LDA(At, 0, 1); PG8_STAGE(PG8_SB(0, 0), b2, voffB); PG8_STAGE(PG8_SB(0, 1), b2 + hstepB, voffB); PG8_STAGE(PG8_SA(0, 0), a2, voffA);
;             PG8_WAIT_V(8); PG8_WAIT_L(0); PG8_BAR; PG8_MMA(1, 0, At, B0); PG8_MMA(1, 1, At, B1); PG8_BAR; PG8_SCHED;
.LBB0_2032:
	s_add_u32 s42, s40, 0xfffc0080
	s_addc_u32 s43, s41, -1
	s_add_i32 s87, 0, 0x10000
	s_cmp_eq_u32 s86, 12
	s_cselect_b32 s45, s29, s43
	s_cselect_b32 s44, s37, s42
	v_add_u32_e32 v144, s87, v159
	s_cselect_b32 s43, s27, s85
	s_cselect_b32 s42, s82, s83
	s_add_i32 s90, 0, 0x14000
	ds_read_b128 v[140:143], v144
	ds_read_b128 v[148:151], v144 offset:1024
	ds_read_b128 v[162:165], v144 offset:2048
	ds_read_b128 v[166:169], v144 offset:3072
	v_add_u32_e32 v144, s90, v159
	ds_read_b128 v[170:173], v144
	ds_read_b128 v[174:177], v144 offset:1024
	ds_read_b128 v[178:181], v144 offset:2048
	ds_read_b128 v[182:185], v144 offset:3072
	s_add_i32 m0, s39, 0xc000
	ds_read_b128 v[186:189], v161
	ds_read_b128 v[190:193], v161 offset:1024
	ds_read_b128 v[194:197], v161 offset:2048
	ds_read_b128 v[198:201], v161 offset:3072
	ds_read_b128 v[208:211], v161 offset:4096
	ds_read_b128 v[216:219], v161 offset:5120
	ds_read_b128 v[220:223], v161 offset:6144
	ds_read_b128 v[224:227], v161 offset:7168
	global_load_lds_dwordx4 v136, s[40:41]
	s_add_i32 m0, s39, 0xe000
	s_nop 0
	global_load_lds_dwordx4 v138, s[40:41]
	s_waitcnt vmcnt(8)
	s_waitcnt lgkmcnt(0)
	s_barrier
	s_setprio 1
	s_waitcnt lgkmcnt(0)
	v_mfma_f32_16x16x32_bf16 v[126:129], v[140:143], v[186:189], 0
	v_mfma_f32_16x16x32_bf16 v[122:125], v[162:165], v[186:189], 0
	v_mfma_f32_16x16x32_bf16 v[110:113], v[140:143], v[194:197], 0
	v_mfma_f32_16x16x32_bf16 v[106:109], v[162:165], v[194:197], 0
	v_mfma_f32_16x16x32_bf16 v[94:97], v[140:143], v[208:211], 0
	v_mfma_f32_16x16x32_bf16 v[90:93], v[162:165], v[208:211], 0
	v_mfma_f32_16x16x32_bf16 v[78:81], v[140:143], v[220:223], 0
	v_mfma_f32_16x16x32_bf16 v[74:77], v[162:165], v[220:223], 0
	v_mfma_f32_16x16x32_bf16 v[126:129], v[148:151], v[190:193], v[126:129]
	v_mfma_f32_16x16x32_bf16 v[122:125], v[166:169], v[190:193], v[122:125]
	v_mfma_f32_16x16x32_bf16 v[110:113], v[148:151], v[198:201], v[110:113]
	v_mfma_f32_16x16x32_bf16 v[106:109], v[166:169], v[198:201], v[106:109]
	v_mfma_f32_16x16x32_bf16 v[94:97], v[148:151], v[216:219], v[94:97]
	v_mfma_f32_16x16x32_bf16 v[90:93], v[166:169], v[216:219], v[90:93]
	v_mfma_f32_16x16x32_bf16 v[78:81], v[148:151], v[224:227], v[78:81]
	v_mfma_f32_16x16x32_bf16 v[74:77], v[166:169], v[224:227], v[74:77]
	v_mfma_f32_16x16x32_bf16 v[118:121], v[170:173], v[186:189], 0
	v_mfma_f32_16x16x32_bf16 v[114:117], v[178:181], v[186:189], 0
	v_mfma_f32_16x16x32_bf16 v[102:105], v[170:173], v[194:197], 0
	v_mfma_f32_16x16x32_bf16 v[98:101], v[178:181], v[194:197], 0
	v_mfma_f32_16x16x32_bf16 v[86:89], v[170:173], v[208:211], 0
	v_mfma_f32_16x16x32_bf16 v[82:85], v[178:181], v[208:211], 0
	v_mfma_f32_16x16x32_bf16 v[70:73], v[170:173], v[220:223], 0
	v_mfma_f32_16x16x32_bf16 v[66:69], v[178:181], v[220:223], 0
	v_mfma_f32_16x16x32_bf16 v[118:121], v[174:177], v[190:193], v[118:121]
	v_mfma_f32_16x16x32_bf16 v[114:117], v[182:185], v[190:193], v[114:117]
	v_mfma_f32_16x16x32_bf16 v[102:105], v[174:177], v[198:201], v[102:105]
	v_mfma_f32_16x16x32_bf16 v[98:101], v[182:185], v[198:201], v[98:101]
	v_mfma_f32_16x16x32_bf16 v[86:89], v[174:177], v[216:219], v[86:89]
	v_mfma_f32_16x16x32_bf16 v[82:85], v[182:185], v[216:219], v[82:85]
	v_mfma_f32_16x16x32_bf16 v[70:73], v[174:177], v[224:227], v[70:73]
	v_mfma_f32_16x16x32_bf16 v[66:69], v[182:185], v[224:227], v[66:69]
	s_setprio 0
	s_barrier
	s_add_i32 s87, s87, s53
	s_mov_b32 m0, s87
	ds_read_b128 v[186:189], v161 offset:16384
	ds_read_b128 v[190:193], v161 offset:17408
	ds_read_b128 v[194:197], v161 offset:18432
	ds_read_b128 v[198:201], v161 offset:19456
	ds_read_b128 v[208:211], v161 offset:20480
	ds_read_b128 v[216:219], v161 offset:21504
	ds_read_b128 v[220:223], v161 offset:22528
	ds_read_b128 v[224:227], v161 offset:23552
	global_load_lds_dwordx4 v32, s[42:43]
	s_add_i32 m0, s87, 0x2000
	s_add_u32 s88, s42, 0x40000
	s_addc_u32 s89, s43, 0
	s_add_i32 s87, s90, s53
	global_load_lds_dwordx4 v134, s[42:43]
	s_mov_b32 m0, s87
	v_lshl_add_u64 v[206:207], s[44:45], 0, v[132:133]
	global_load_lds_dwordx4 v32, s[88:89]
	s_add_i32 m0, s87, 0x2000
	s_nop 0
	global_load_lds_dwordx4 v134, s[88:89]
	v_lshl_add_u64 v[204:205], s[44:45], 0, v[130:131]
	s_mov_b32 m0, s39
	s_nop 0
	global_load_lds_dwordx4 v130, s[44:45]
	s_mov_b32 m0, s67
	s_nop 0
	global_load_lds_dwordx4 v132, s[44:45]
	s_waitcnt vmcnt(8)
	s_waitcnt lgkmcnt(0)
	s_barrier
	s_setprio 1
	s_waitcnt lgkmcnt(0)
	v_mfma_f32_16x16x32_bf16 v[62:65], v[140:143], v[186:189], 0
	v_mfma_f32_16x16x32_bf16 v[58:61], v[162:165], v[186:189], 0
	v_mfma_f32_16x16x32_bf16 v[46:49], v[140:143], v[194:197], 0
	v_mfma_f32_16x16x32_bf16 v[42:45], v[162:165], v[194:197], 0
	v_mfma_f32_16x16x32_bf16 v[28:31], v[140:143], v[208:211], 0
	v_mfma_f32_16x16x32_bf16 v[24:27], v[162:165], v[208:211], 0
	v_mfma_f32_16x16x32_bf16 v[12:15], v[140:143], v[220:223], 0
	v_mfma_f32_16x16x32_bf16 v[8:11], v[162:165], v[220:223], 0
	v_mfma_f32_16x16x32_bf16 v[62:65], v[148:151], v[190:193], v[62:65]
	v_mfma_f32_16x16x32_bf16 v[58:61], v[166:169], v[190:193], v[58:61]
	v_mfma_f32_16x16x32_bf16 v[46:49], v[148:151], v[198:201], v[46:49]
	v_mfma_f32_16x16x32_bf16 v[42:45], v[166:169], v[198:201], v[42:45]
	v_mfma_f32_16x16x32_bf16 v[28:31], v[148:151], v[216:219], v[28:31]
	v_mfma_f32_16x16x32_bf16 v[24:27], v[166:169], v[216:219], v[24:27]
	v_mfma_f32_16x16x32_bf16 v[12:15], v[148:151], v[224:227], v[12:15]
	v_mfma_f32_16x16x32_bf16 v[8:11], v[166:169], v[224:227], v[8:11]
	v_mfma_f32_16x16x32_bf16 v[54:57], v[170:173], v[186:189], 0
	v_mfma_f32_16x16x32_bf16 v[50:53], v[178:181], v[186:189], 0
	v_mfma_f32_16x16x32_bf16 v[38:41], v[170:173], v[194:197], 0
	v_mfma_f32_16x16x32_bf16 v[34:37], v[178:181], v[194:197], 0
	v_mfma_f32_16x16x32_bf16 v[20:23], v[170:173], v[208:211], 0
	v_mfma_f32_16x16x32_bf16 v[16:19], v[178:181], v[208:211], 0
	v_mfma_f32_16x16x32_bf16 v[4:7], v[170:173], v[220:223], 0
	v_mfma_f32_16x16x32_bf16 v[0:3], v[178:181], v[220:223], 0
	v_mfma_f32_16x16x32_bf16 v[54:57], v[174:177], v[190:193], v[54:57]
	v_mfma_f32_16x16x32_bf16 v[50:53], v[182:185], v[190:193], v[50:53]
	v_mfma_f32_16x16x32_bf16 v[38:41], v[174:177], v[198:201], v[38:41]
	v_mfma_f32_16x16x32_bf16 v[34:37], v[182:185], v[198:201], v[34:37]
	v_mfma_f32_16x16x32_bf16 v[20:23], v[174:177], v[216:219], v[20:23]
	v_mfma_f32_16x16x32_bf16 v[16:19], v[182:185], v[216:219], v[16:19]
	v_mfma_f32_16x16x32_bf16 v[4:7], v[174:177], v[224:227], v[4:7]
	v_mfma_f32_16x16x32_bf16 v[0:3], v[182:185], v[224:227], v[0:3]
	s_setprio 0
	s_barrier
	s_branch .Lp3_2032
; #define PG8_STAGE(bufoff, gbase, voff) do { _Pragma("unroll") for (int _i = 0; _i < 2; ++_i) \
;         __builtin_amdgcn_global_load_lds((const unsigned*)((const char*)(gbase) + (voff)[_i]), (PG8_LAS unsigned*)(lds + (bufoff) + ldsw + _i * 8192), 16, 0, 0); } while (0)
; #define PG8_LDA(dst, b, h) do { _Pragma("unroll") for (int m = 0; m < 4; ++m) _Pragma("unroll") for (int k = 0; k < 2; ++k) dst[m][k] = *(const PG8_LAS bf16x8*)(lds + PG8_SA(b, h) + aoff + m * 2048 + k * 1024); } while (0)
; #define PG8_LDB(dst, b, h) do { _Pragma("unroll") for (int n = 0; n < 2; ++n) _Pragma("unroll") for (int k = 0; k < 2; ++k) dst[n][k] = *(const PG8_LAS bf16x8*)(lds + PG8_SB(b, h) + boff + n * 2048 + k * 1024); } while (0)
; #define PG8_WAIT_V(n) asm volatile("s_waitcnt vmcnt(" #n ")" ::: "memory")
; #define PG8_WAIT_L(n) asm volatile("s_waitcnt lgkmcnt(" #n ")" ::: "memory")
; #define PG8_BAR __builtin_amdgcn_s_barrier()
; #define PG8_SCHED __builtin_amdgcn_sched_barrier(0)
; template <class Epi, bool ALIGN_EPI = true>
; __device__ __forceinline__ void gemm_phase(PG8_LAS unsigned char* lds, const Gemm g, const StaticOrder& S, const Epi& E) {
;     ...
;         for (int t = 0; t < nt; t += 2) {
;             const bool last = (t == nt - 2);
;             const char* a1 = cA + (size_t)(t + 1) * kstep;
;             const char* a2 = last ? nA : cA + (size_t)(t + 2) * kstep; const char* b2 = last ? nB : cB + (size_t)(t + 2) * kstep;
;             const char* a3 = a2 + kstep; const char* b3 = b2 + kstep;
;             PG8_LDB(B0, 0, 0); PG8_LDB(B1, 0, 1); PG8_SCHED; PG8_LDA(At, 0, 0); PG8_STAGE(PG8_SA(1, 1), a1 + hstepA, voffA);
;             PG8_WAIT_V(8); PG8_WAIT_L(0); PG8_BAR; PG8_MMA(0, 0, At, B0); PG8_MMA(0, 1, At, B1); PG8_BAR; PG8_SCHED;
;             PG8_LDA(At, 0, 1); PG8_STAGE(PG8_SB(0, 0), b2, voffB); PG8_STAGE(PG8_SB(0, 1), b2 + hstepB, voffB); PG8_STAGE(PG8_SA(0, 0), a2, voffA);
;             PG8_WAIT_V(8); PG8_WAIT_L(0); PG8_BAR; PG8_MMA(1, 0, At, B0); PG8_MMA(1, 1, At, B1); PG8_BAR; PG8_SCHED;
.Lrot_2032:
	ds_read_b128 v[140:143], v144
	ds_read_b128 v[148:151], v144 offset:1024
	ds_read_b128 v[162:165], v144 offset:2048
	ds_read_b128 v[166:169], v144 offset:3072
	v_add_u32_e32 v144, s90, v159
	ds_read_b128 v[170:173], v144
	ds_read_b128 v[174:177], v144 offset:1024
	ds_read_b128 v[178:181], v144 offset:2048
	ds_read_b128 v[182:185], v144 offset:3072
	s_add_i32 m0, s39, 0xc000
	ds_read_b128 v[186:189], v161
	ds_read_b128 v[190:193], v161 offset:1024
	ds_read_b128 v[194:197], v161 offset:2048
	ds_read_b128 v[198:201], v161 offset:3072
	ds_read_b128 v[208:211], v161 offset:4096
	ds_read_b128 v[216:219], v161 offset:5120
	ds_read_b128 v[220:223], v161 offset:6144
	ds_read_b128 v[224:227], v161 offset:7168
	global_load_lds_dwordx4 v136, s[40:41]
	s_add_i32 m0, s39, 0xe000
	s_nop 0
	global_load_lds_dwordx4 v138, s[40:41]
	s_waitcnt vmcnt(8)
	s_waitcnt lgkmcnt(0)
	s_barrier
	s_setprio 1
	s_waitcnt lgkmcnt(0)
	v_mfma_f32_16x16x32_bf16 v[126:129], v[140:143], v[186:189], v[126:129]
	v_mfma_f32_16x16x32_bf16 v[122:125], v[162:165], v[186:189], v[122:125]
	v_mfma_f32_16x16x32_bf16 v[110:113], v[140:143], v[194:197], v[110:113]
	v_mfma_f32_16x16x32_bf16 v[106:109], v[162:165], v[194:197], v[106:109]
	v_mfma_f32_16x16x32_bf16 v[94:97], v[140:143], v[208:211], v[94:97]
	v_mfma_f32_16x16x32_bf16 v[90:93], v[162:165], v[208:211], v[90:93]
	v_mfma_f32_16x16x32_bf16 v[78:81], v[140:143], v[220:223], v[78:81]
	v_mfma_f32_16x16x32_bf16 v[74:77], v[162:165], v[220:223], v[74:77]
	v_mfma_f32_16x16x32_bf16 v[126:129], v[148:151], v[190:193], v[126:129]
	v_mfma_f32_16x16x32_bf16 v[122:125], v[166:169], v[190:193], v[122:125]
	v_mfma_f32_16x16x32_bf16 v[110:113], v[148:151], v[198:201], v[110:113]
	v_mfma_f32_16x16x32_bf16 v[106:109], v[166:169], v[198:201], v[106:109]
	v_mfma_f32_16x16x32_bf16 v[94:97], v[148:151], v[216:219], v[94:97]
	v_mfma_f32_16x16x32_bf16 v[90:93], v[166:169], v[216:219], v[90:93]
	v_mfma_f32_16x16x32_bf16 v[78:81], v[148:151], v[224:227], v[78:81]
	v_mfma_f32_16x16x32_bf16 v[74:77], v[166:169], v[224:227], v[74:77]
	v_mfma_f32_16x16x32_bf16 v[118:121], v[170:173], v[186:189], v[118:121]
	v_mfma_f32_16x16x32_bf16 v[114:117], v[178:181], v[186:189], v[114:117]
	v_mfma_f32_16x16x32_bf16 v[102:105], v[170:173], v[194:197], v[102:105]
	v_mfma_f32_16x16x32_bf16 v[98:101], v[178:181], v[194:197], v[98:101]
	v_mfma_f32_16x16x32_bf16 v[86:89], v[170:173], v[208:211], v[86:89]
	v_mfma_f32_16x16x32_bf16 v[82:85], v[178:181], v[208:211], v[82:85]
	v_mfma_f32_16x16x32_bf16 v[70:73], v[170:173], v[220:223], v[70:73]
	v_mfma_f32_16x16x32_bf16 v[66:69], v[178:181], v[220:223], v[66:69]
	v_mfma_f32_16x16x32_bf16 v[118:121], v[174:177], v[190:193], v[118:121]
	v_mfma_f32_16x16x32_bf16 v[114:117], v[182:185], v[190:193], v[114:117]
	v_mfma_f32_16x16x32_bf16 v[102:105], v[174:177], v[198:201], v[102:105]
	v_mfma_f32_16x16x32_bf16 v[98:101], v[182:185], v[198:201], v[98:101]
	v_mfma_f32_16x16x32_bf16 v[86:89], v[174:177], v[216:219], v[86:89]
	v_mfma_f32_16x16x32_bf16 v[82:85], v[182:185], v[216:219], v[82:85]
	v_mfma_f32_16x16x32_bf16 v[70:73], v[174:177], v[224:227], v[70:73]
	v_mfma_f32_16x16x32_bf16 v[66:69], v[182:185], v[224:227], v[66:69]
	s_setprio 0
	s_barrier
	s_add_i32 s87, s87, s53
	s_mov_b32 m0, s87
	ds_read_b128 v[186:189], v161 offset:16384
	ds_read_b128 v[190:193], v161 offset:17408
	ds_read_b128 v[194:197], v161 offset:18432
	ds_read_b128 v[198:201], v161 offset:19456
	ds_read_b128 v[208:211], v161 offset:20480
	ds_read_b128 v[216:219], v161 offset:21504
	ds_read_b128 v[220:223], v161 offset:22528
	ds_read_b128 v[224:227], v161 offset:23552
	global_load_lds_dwordx4 v32, s[42:43]
	s_add_i32 m0, s87, 0x2000
	s_add_u32 s88, s42, 0x40000
	s_addc_u32 s89, s43, 0
	s_add_i32 s87, s90, s53
	global_load_lds_dwordx4 v134, s[42:43]
	s_mov_b32 m0, s87
	v_lshl_add_u64 v[206:207], s[44:45], 0, v[132:133]
	global_load_lds_dwordx4 v32, s[88:89]
	s_add_i32 m0, s87, 0x2000
	s_nop 0
	global_load_lds_dwordx4 v134, s[88:89]
	v_lshl_add_u64 v[204:205], s[44:45], 0, v[130:131]
	s_mov_b32 m0, s39
	s_nop 0
	global_load_lds_dwordx4 v130, s[44:45]
	s_mov_b32 m0, s67
	s_nop 0
	global_load_lds_dwordx4 v132, s[44:45]
	s_waitcnt vmcnt(8)
	s_waitcnt lgkmcnt(0)
	s_barrier
	s_setprio 1
	s_waitcnt lgkmcnt(0)
	v_mfma_f32_16x16x32_bf16 v[62:65], v[140:143], v[186:189], v[62:65]
	v_mfma_f32_16x16x32_bf16 v[58:61], v[162:165], v[186:189], v[58:61]
	v_mfma_f32_16x16x32_bf16 v[46:49], v[140:143], v[194:197], v[46:49]
	v_mfma_f32_16x16x32_bf16 v[42:45], v[162:165], v[194:197], v[42:45]
	v_mfma_f32_16x16x32_bf16 v[28:31], v[140:143], v[208:211], v[28:31]
	v_mfma_f32_16x16x32_bf16 v[24:27], v[162:165], v[208:211], v[24:27]
	v_mfma_f32_16x16x32_bf16 v[12:15], v[140:143], v[220:223], v[12:15]
	v_mfma_f32_16x16x32_bf16 v[8:11], v[162:165], v[220:223], v[8:11]
	v_mfma_f32_16x16x32_bf16 v[62:65], v[148:151], v[190:193], v[62:65]
	v_mfma_f32_16x16x32_bf16 v[58:61], v[166:169], v[190:193], v[58:61]
	v_mfma_f32_16x16x32_bf16 v[46:49], v[148:151], v[198:201], v[46:49]
	v_mfma_f32_16x16x32_bf16 v[42:45], v[166:169], v[198:201], v[42:45]
	v_mfma_f32_16x16x32_bf16 v[28:31], v[148:151], v[216:219], v[28:31]
	v_mfma_f32_16x16x32_bf16 v[24:27], v[166:169], v[216:219], v[24:27]
	v_mfma_f32_16x16x32_bf16 v[12:15], v[148:151], v[224:227], v[12:15]
	v_mfma_f32_16x16x32_bf16 v[8:11], v[166:169], v[224:227], v[8:11]
	v_mfma_f32_16x16x32_bf16 v[54:57], v[170:173], v[186:189], v[54:57]
	v_mfma_f32_16x16x32_bf16 v[50:53], v[178:181], v[186:189], v[50:53]
	v_mfma_f32_16x16x32_bf16 v[38:41], v[170:173], v[194:197], v[38:41]
	v_mfma_f32_16x16x32_bf16 v[34:37], v[178:181], v[194:197], v[34:37]
	v_mfma_f32_16x16x32_bf16 v[20:23], v[170:173], v[208:211], v[20:23]
	v_mfma_f32_16x16x32_bf16 v[16:19], v[178:181], v[208:211], v[16:19]
	v_mfma_f32_16x16x32_bf16 v[4:7], v[170:173], v[220:223], v[4:7]
	v_mfma_f32_16x16x32_bf16 v[0:3], v[178:181], v[220:223], v[0:3]
	v_mfma_f32_16x16x32_bf16 v[54:57], v[174:177], v[190:193], v[54:57]
	v_mfma_f32_16x16x32_bf16 v[50:53], v[182:185], v[190:193], v[50:53]
	v_mfma_f32_16x16x32_bf16 v[38:41], v[174:177], v[198:201], v[38:41]
	v_mfma_f32_16x16x32_bf16 v[34:37], v[182:185], v[198:201], v[34:37]
	v_mfma_f32_16x16x32_bf16 v[20:23], v[174:177], v[216:219], v[20:23]
	v_mfma_f32_16x16x32_bf16 v[16:19], v[182:185], v[216:219], v[16:19]
	v_mfma_f32_16x16x32_bf16 v[4:7], v[174:177], v[224:227], v[4:7]
	v_mfma_f32_16x16x32_bf16 v[0:3], v[182:185], v[224:227], v[0:3]
	s_setprio 0
	s_barrier
; #define PG8_STAGE(bufoff, gbase, voff) do { _Pragma("unroll") for (int _i = 0; _i < 2; ++_i) \
;         __builtin_amdgcn_global_load_lds((const unsigned*)((const char*)(gbase) + (voff)[_i]), (PG8_LAS unsigned*)(lds + (bufoff) + ldsw + _i * 8192), 16, 0, 0); } while (0)
; #define PG8_LDA(dst, b, h) do { _Pragma("unroll") for (int m = 0; m < 4; ++m) _Pragma("unroll") for (int k = 0; k < 2; ++k) dst[m][k] = *(const PG8_LAS bf16x8*)(lds + PG8_SA(b, h) + aoff + m * 2048 + k * 1024); } while (0)
; #define PG8_LDB(dst, b, h) do { _Pragma("unroll") for (int n = 0; n < 2; ++n) _Pragma("unroll") for (int k = 0; k < 2; ++k) dst[n][k] = *(const PG8_LAS bf16x8*)(lds + PG8_SB(b, h) + boff + n * 2048 + k * 1024); } while (0)
; #define PG8_WAIT_V(n) asm volatile("s_waitcnt vmcnt(" #n ")" ::: "memory")
; #define PG8_WAIT_L(n) asm volatile("s_waitcnt lgkmcnt(" #n ")" ::: "memory")
; #define PG8_BAR __builtin_amdgcn_s_barrier()
; #define PG8_SCHED __builtin_amdgcn_sched_barrier(0)
; template <class Epi, bool ALIGN_EPI = true>
; __device__ __forceinline__ void gemm_phase(PG8_LAS unsigned char* lds, const Gemm g, const StaticOrder& S, const Epi& E) {
;     ...
;             PG8_LDB(B0, 1, 0); PG8_LDB(B1, 1, 1); PG8_SCHED; PG8_LDA(At, 1, 0); PG8_STAGE(PG8_SA(0, 1), a2 + hstepA, voffA);
;             PG8_WAIT_V(8); PG8_WAIT_L(0); PG8_BAR; PG8_MMA(0, 0, At, B0); PG8_MMA(0, 1, At, B1); PG8_BAR; PG8_SCHED;
.Lp3_2032:
	s_add_i32 s87, 0, 0x18000
	v_add_u32_e32 v154, s87, v159
	s_add_i32 s88, 0, 0x1c000
	ds_read_b128 v[140:143], v154
	ds_read_b128 v[148:151], v154 offset:1024
	ds_read_b128 v[162:165], v154 offset:2048
	ds_read_b128 v[166:169], v154 offset:3072
	v_add_u32_e32 v154, s88, v159
	ds_read_b128 v[170:173], v154
	ds_read_b128 v[174:177], v154 offset:1024
	ds_read_b128 v[178:181], v154 offset:2048
	ds_read_b128 v[182:185], v154 offset:3072
	s_add_u32 s44, s44, 0x40000
	s_addc_u32 s45, s45, 0
	s_mov_b32 m0, s70
	ds_read_b128 v[186:189], v161 offset:32768
	ds_read_b128 v[190:193], v161 offset:33792
	ds_read_b128 v[194:197], v161 offset:34816
	ds_read_b128 v[198:201], v161 offset:35840
	ds_read_b128 v[208:211], v161 offset:36864
	ds_read_b128 v[216:219], v161 offset:37888
	ds_read_b128 v[220:223], v161 offset:38912
	ds_read_b128 v[224:227], v161 offset:39936
	global_load_lds_dwordx4 v130, s[44:45]
	s_mov_b32 m0, s71
	s_nop 0
	global_load_lds_dwordx4 v132, s[44:45]
	s_waitcnt vmcnt(8)
	s_waitcnt lgkmcnt(0)
	s_barrier
	s_setprio 1
	s_waitcnt lgkmcnt(0)
	v_mfma_f32_16x16x32_bf16 v[126:129], v[140:143], v[186:189], v[126:129]
	v_mfma_f32_16x16x32_bf16 v[122:125], v[162:165], v[186:189], v[122:125]
	v_mfma_f32_16x16x32_bf16 v[110:113], v[140:143], v[194:197], v[110:113]
	v_mfma_f32_16x16x32_bf16 v[106:109], v[162:165], v[194:197], v[106:109]
	v_mfma_f32_16x16x32_bf16 v[94:97], v[140:143], v[208:211], v[94:97]
	v_mfma_f32_16x16x32_bf16 v[90:93], v[162:165], v[208:211], v[90:93]
	v_mfma_f32_16x16x32_bf16 v[78:81], v[140:143], v[220:223], v[78:81]
	v_mfma_f32_16x16x32_bf16 v[74:77], v[162:165], v[220:223], v[74:77]
	v_mfma_f32_16x16x32_bf16 v[126:129], v[148:151], v[190:193], v[126:129]
	v_mfma_f32_16x16x32_bf16 v[122:125], v[166:169], v[190:193], v[122:125]
	v_mfma_f32_16x16x32_bf16 v[110:113], v[148:151], v[198:201], v[110:113]
	v_mfma_f32_16x16x32_bf16 v[106:109], v[166:169], v[198:201], v[106:109]
	v_mfma_f32_16x16x32_bf16 v[94:97], v[148:151], v[216:219], v[94:97]
	v_mfma_f32_16x16x32_bf16 v[90:93], v[166:169], v[216:219], v[90:93]
	v_mfma_f32_16x16x32_bf16 v[78:81], v[148:151], v[224:227], v[78:81]
	v_mfma_f32_16x16x32_bf16 v[74:77], v[166:169], v[224:227], v[74:77]
	v_mfma_f32_16x16x32_bf16 v[118:121], v[170:173], v[186:189], v[118:121]
	v_mfma_f32_16x16x32_bf16 v[114:117], v[178:181], v[186:189], v[114:117]
	v_mfma_f32_16x16x32_bf16 v[102:105], v[170:173], v[194:197], v[102:105]
	v_mfma_f32_16x16x32_bf16 v[98:101], v[178:181], v[194:197], v[98:101]
	v_mfma_f32_16x16x32_bf16 v[86:89], v[170:173], v[208:211], v[86:89]
	v_mfma_f32_16x16x32_bf16 v[82:85], v[178:181], v[208:211], v[82:85]
	v_mfma_f32_16x16x32_bf16 v[70:73], v[170:173], v[220:223], v[70:73]
	v_mfma_f32_16x16x32_bf16 v[66:69], v[178:181], v[220:223], v[66:69]
	v_mfma_f32_16x16x32_bf16 v[118:121], v[174:177], v[190:193], v[118:121]
	v_mfma_f32_16x16x32_bf16 v[114:117], v[182:185], v[190:193], v[114:117]
	v_mfma_f32_16x16x32_bf16 v[102:105], v[174:177], v[198:201], v[102:105]
	v_mfma_f32_16x16x32_bf16 v[98:101], v[182:185], v[198:201], v[98:101]
	v_mfma_f32_16x16x32_bf16 v[86:89], v[174:177], v[216:219], v[86:89]
	v_mfma_f32_16x16x32_bf16 v[82:85], v[182:185], v[216:219], v[82:85]
	v_mfma_f32_16x16x32_bf16 v[70:73], v[174:177], v[224:227], v[70:73]
	v_mfma_f32_16x16x32_bf16 v[66:69], v[182:185], v[224:227], v[66:69]
	s_setprio 0
	s_barrier
; #define PG8_STAGE(bufoff, gbase, voff) do { _Pragma("unroll") for (int _i = 0; _i < 2; ++_i) \
;         __builtin_amdgcn_global_load_lds((const unsigned*)((const char*)(gbase) + (voff)[_i]), (PG8_LAS unsigned*)(lds + (bufoff) + ldsw + _i * 8192), 16, 0, 0); } while (0)
; #define PG8_LDA(dst, b, h) do { _Pragma("unroll") for (int m = 0; m < 4; ++m) _Pragma("unroll") for (int k = 0; k < 2; ++k) dst[m][k] = *(const PG8_LAS bf16x8*)(lds + PG8_SA(b, h) + aoff + m * 2048 + k * 1024); } while (0)
; #define PG8_WAIT_V(n) asm volatile("s_waitcnt vmcnt(" #n ")" ::: "memory")
; #define PG8_WAIT_L(n) asm volatile("s_waitcnt lgkmcnt(" #n ")" ::: "memory")
; #define PG8_BAR __builtin_amdgcn_s_barrier()
; #define PG8_SCHED __builtin_amdgcn_sched_barrier(0)
; template <class Epi, bool ALIGN_EPI = true>
; __device__ __forceinline__ void gemm_phase(PG8_LAS unsigned char* lds, const Gemm g, const StaticOrder& S, const Epi& E) {
;     ...
;         for (int t = 0; t < nt; t += 2) {
;             const bool last = (t == nt - 2);
;             const char* a1 = cA + (size_t)(t + 1) * kstep;
;             const char* a2 = last ? nA : cA + (size_t)(t + 2) * kstep; const char* b2 = last ? nB : cB + (size_t)(t + 2) * kstep;
;             const char* a3 = a2 + kstep; const char* b3 = b2 + kstep;
;     ...
;             PG8_LDA(At, 1, 1); PG8_STAGE(PG8_SB(1, 0), b3, voffB); PG8_STAGE(PG8_SB(1, 1), b3 + hstepB, voffB); PG8_STAGE(PG8_SA(1, 0), a3, voffA);
;             PG8_WAIT_V(8); PG8_WAIT_L(0); PG8_BAR; PG8_MMA(1, 0, At, B0); PG8_MMA(1, 1, At, B1); PG8_BAR; PG8_SCHED;
	s_add_i32 s44, s87, s53
	s_mov_b32 m0, s44
	ds_read_b128 v[186:189], v161 offset:49152
	ds_read_b128 v[190:193], v161 offset:50176
	ds_read_b128 v[194:197], v161 offset:51200
	ds_read_b128 v[198:201], v161 offset:52224
	ds_read_b128 v[208:211], v161 offset:53248
	ds_read_b128 v[216:219], v161 offset:54272
	ds_read_b128 v[220:223], v161 offset:55296
	ds_read_b128 v[224:227], v161 offset:56320
	s_add_u32 s98, s42, s60
	s_addc_u32 s99, s43, s61
	global_load_lds_dwordx4 v32, s[98:99]
	s_add_i32 m0, s44, 0x2000
	s_add_u32 s42, s42, 0x40080
	s_addc_u32 s43, s43, 0
	s_add_i32 s44, s88, s53
	s_add_u32 s98, s42, s60
	s_addc_u32 s99, s43, s61
	s_add_u32 s98, s98, 0xfffbff80
	s_addc_u32 s99, s99, -1
	global_load_lds_dwordx4 v134, s[98:99]
	s_mov_b32 m0, s44
	s_nop 0
	global_load_lds_dwordx4 v32, s[42:43]
	s_add_i32 m0, s44, 0x2000
	s_nop 0
	global_load_lds_dwordx4 v134, s[42:43]
	v_lshl_add_u64 v[144:145], v[204:205], 0, s[60:61]
	s_mov_b32 m0, s72
	s_nop 0
	global_load_lds_dwordx4 v[144:145], off
	v_lshl_add_u64 v[144:145], v[206:207], 0, s[60:61]
	s_mov_b32 m0, s73
	s_nop 0
	global_load_lds_dwordx4 v[144:145], off
	s_add_i32 s86, s86, 2
	s_add_u32 s40, s40, 0x100
	s_addc_u32 s41, s41, 0
	s_add_u32 s83, s83, 0x100
	s_addc_u32 s85, s85, 0
	s_add_u32 s42, s40, 0xfffc0080
	s_addc_u32 s43, s41, -1
	s_add_i32 s87, 0, 0x10000
	s_cmp_eq_u32 s86, 12
	s_cselect_b32 s45, s29, s43
	s_cselect_b32 s44, s37, s42
	v_add_u32_e32 v144, s87, v159
	s_cselect_b32 s43, s27, s85
	s_cselect_b32 s42, s82, s83
	s_add_i32 s90, 0, 0x14000
	s_cmp_gt_u32 s86, 13
	s_waitcnt vmcnt(8)
	s_waitcnt lgkmcnt(0)
	s_barrier
	s_setprio 1
	s_waitcnt lgkmcnt(0)
	v_mfma_f32_16x16x32_bf16 v[62:65], v[140:143], v[186:189], v[62:65]
	v_mfma_f32_16x16x32_bf16 v[58:61], v[162:165], v[186:189], v[58:61]
	v_mfma_f32_16x16x32_bf16 v[46:49], v[140:143], v[194:197], v[46:49]
	v_mfma_f32_16x16x32_bf16 v[42:45], v[162:165], v[194:197], v[42:45]
	v_mfma_f32_16x16x32_bf16 v[28:31], v[140:143], v[208:211], v[28:31]
	v_mfma_f32_16x16x32_bf16 v[24:27], v[162:165], v[208:211], v[24:27]
	v_mfma_f32_16x16x32_bf16 v[12:15], v[140:143], v[220:223], v[12:15]
	v_mfma_f32_16x16x32_bf16 v[8:11], v[162:165], v[220:223], v[8:11]
	v_mfma_f32_16x16x32_bf16 v[62:65], v[148:151], v[190:193], v[62:65]
	v_mfma_f32_16x16x32_bf16 v[58:61], v[166:169], v[190:193], v[58:61]
	v_mfma_f32_16x16x32_bf16 v[46:49], v[148:151], v[198:201], v[46:49]
	v_mfma_f32_16x16x32_bf16 v[42:45], v[166:169], v[198:201], v[42:45]
	v_mfma_f32_16x16x32_bf16 v[28:31], v[148:151], v[216:219], v[28:31]
	v_mfma_f32_16x16x32_bf16 v[24:27], v[166:169], v[216:219], v[24:27]
	v_mfma_f32_16x16x32_bf16 v[12:15], v[148:151], v[224:227], v[12:15]
	v_mfma_f32_16x16x32_bf16 v[8:11], v[166:169], v[224:227], v[8:11]
	v_mfma_f32_16x16x32_bf16 v[54:57], v[170:173], v[186:189], v[54:57]
	v_mfma_f32_16x16x32_bf16 v[50:53], v[178:181], v[186:189], v[50:53]
	v_mfma_f32_16x16x32_bf16 v[38:41], v[170:173], v[194:197], v[38:41]
	v_mfma_f32_16x16x32_bf16 v[34:37], v[178:181], v[194:197], v[34:37]
	v_mfma_f32_16x16x32_bf16 v[20:23], v[170:173], v[208:211], v[20:23]
	v_mfma_f32_16x16x32_bf16 v[16:19], v[178:181], v[208:211], v[16:19]
	v_mfma_f32_16x16x32_bf16 v[4:7], v[170:173], v[220:223], v[4:7]
	v_mfma_f32_16x16x32_bf16 v[0:3], v[178:181], v[220:223], v[0:3]
	v_mfma_f32_16x16x32_bf16 v[54:57], v[174:177], v[190:193], v[54:57]
	v_mfma_f32_16x16x32_bf16 v[50:53], v[182:185], v[190:193], v[50:53]
	v_mfma_f32_16x16x32_bf16 v[38:41], v[174:177], v[198:201], v[38:41]
	v_mfma_f32_16x16x32_bf16 v[34:37], v[182:185], v[198:201], v[34:37]
	v_mfma_f32_16x16x32_bf16 v[20:23], v[174:177], v[216:219], v[20:23]
	v_mfma_f32_16x16x32_bf16 v[16:19], v[182:185], v[216:219], v[16:19]
	v_mfma_f32_16x16x32_bf16 v[4:7], v[174:177], v[224:227], v[4:7]
	v_mfma_f32_16x16x32_bf16 v[0:3], v[182:185], v[224:227], v[0:3]
	s_setprio 0
	s_barrier
	s_cbranch_scc0 .Lrot_2032
	s_and_b64 vcc, exec, s[14:15]
	s_cbranch_vccz .LBB0_2035
	s_barrier

; #define PG8_STAGE(bufoff, gbase, voff) do { _Pragma("unroll") for (int _i = 0; _i < 2; ++_i) \
;         __builtin_amdgcn_global_load_lds((const unsigned*)((const char*)(gbase) + (voff)[_i]), (PG8_LAS unsigned*)(lds + (bufoff) + ldsw + _i * 8192), 16, 0, 0); } while (0)
; #define PG8_LDA(dst, b, h) do { _Pragma("unroll") for (int m = 0; m < 4; ++m) _Pragma("unroll") for (int k = 0; k < 2; ++k) dst[m][k] = *(const PG8_LAS bf16x8*)(lds + PG8_SA(b, h) + aoff + m * 2048 + k * 1024); } while (0)
; #define PG8_LDB(dst, b, h) do { _Pragma("unroll") for (int n = 0; n < 2; ++n) _Pragma("unroll") for (int k = 0; k < 2; ++k) dst[n][k] = *(const PG8_LAS bf16x8*)(lds + PG8_SB(b, h) + boff + n * 2048 + k * 1024); } while (0)
; #define PG8_WAIT_V(n) asm volatile("s_waitcnt vmcnt(" #n ")" ::: "memory")
; #define PG8_WAIT_L(n) asm volatile("s_waitcnt lgkmcnt(" #n ")" ::: "memory")
; #define PG8_BAR __builtin_amdgcn_s_barrier()
; #define PG8_SCHED __builtin_amdgcn_sched_barrier(0)
; template <class Epi, bool ALIGN_EPI = true>
; __device__ __forceinline__ void gemm_phase(PG8_LAS unsigned char* lds, const Gemm g, const StaticOrder& S, const Epi& E) {
;     ...
;         for (int t = 0; t < nt; t += 2) {
;             const bool last = (t == nt - 2);
;             const char* a1 = cA + (size_t)(t + 1) * kstep;
;             const char* a2 = last ? nA : cA + (size_t)(t + 2) * kstep; const char* b2 = last ? nB : cB + (size_t)(t + 2) * kstep;
;             const char* a3 = a2 + kstep; const char* b3 = b2 + kstep;
;             PG8_LDB(B0, 0, 0); PG8_LDB(B1, 0, 1); PG8_SCHED; PG8_LDA(At, 0, 0); PG8_STAGE(PG8_SA(1, 1), a1 + hstepA, voffA);
;             PG8_WAIT_V(8); PG8_WAIT_L(0); PG8_BAR; PG8_MMA(0, 0, At, B0); PG8_MMA(0, 1, At, B1); PG8_BAR; PG8_SCHED;
;             PG8_LDA(At, 0, 1); PG8_STAGE(PG8_SB(0, 0), b2, voffB); PG8_STAGE(PG8_SB(0, 1), b2 + hstepB, voffB); PG8_STAGE(PG8_SA(0, 0), a2, voffA);
;             PG8_WAIT_V(8); PG8_WAIT_L(0); PG8_BAR; PG8_MMA(1, 0, At, B0); PG8_MMA(1, 1, At, B1); PG8_BAR; PG8_SCHED;
.LBB0_2132:
	s_add_u32 s43, s48, 0xfff00080
	s_addc_u32 s50, s49, -1
	s_add_i32 s93, 0, 0x10000
	s_cmp_eq_u32 s41, 60
	s_cselect_b32 s53, s45, s50
	s_cselect_b32 s52, s44, s43
	v_add_u32_e32 v32, s93, v165
	s_cselect_b32 s51, s47, s9
	s_cselect_b32 s50, s46, s7
	s_add_i32 s43, 0, 0x14000
	ds_read_b128 v[142:145], v32
	ds_read_b128 v[148:151], v32 offset:1024
	ds_read_b128 v[158:161], v32 offset:2048
	ds_read_b128 v[168:171], v32 offset:3072
	v_add_u32_e32 v32, s43, v165
	ds_read_b128 v[172:175], v32
	ds_read_b128 v[176:179], v32 offset:1024
	ds_read_b128 v[180:183], v32 offset:2048
	ds_read_b128 v[184:187], v32 offset:3072
	s_add_i32 m0, s75, 0xc000
	ds_read_b128 v[188:191], v167
	ds_read_b128 v[192:195], v167 offset:1024
	ds_read_b128 v[196:199], v167 offset:2048
	ds_read_b128 v[208:211], v167 offset:3072
	ds_read_b128 v[216:219], v167 offset:4096
	ds_read_b128 v[220:223], v167 offset:5120
	ds_read_b128 v[224:227], v167 offset:6144
	ds_read_b128 v[228:231], v167 offset:7168
	global_load_lds_dwordx4 v138, s[48:49]
	s_add_i32 m0, s75, 0xe000
	s_nop 0
	global_load_lds_dwordx4 v140, s[48:49]
	s_waitcnt vmcnt(8)
	s_waitcnt lgkmcnt(0)
	s_barrier
	s_setprio 1
	s_waitcnt lgkmcnt(0)
	v_mfma_f32_16x16x32_bf16 v[126:129], v[142:145], v[188:191], 0
	v_mfma_f32_16x16x32_bf16 v[122:125], v[158:161], v[188:191], 0
	v_mfma_f32_16x16x32_bf16 v[110:113], v[142:145], v[196:199], 0
	v_mfma_f32_16x16x32_bf16 v[106:109], v[158:161], v[196:199], 0
	v_mfma_f32_16x16x32_bf16 v[94:97], v[142:145], v[216:219], 0
	v_mfma_f32_16x16x32_bf16 v[90:93], v[158:161], v[216:219], 0
	v_mfma_f32_16x16x32_bf16 v[78:81], v[142:145], v[224:227], 0
	v_mfma_f32_16x16x32_bf16 v[74:77], v[158:161], v[224:227], 0
	v_mfma_f32_16x16x32_bf16 v[126:129], v[148:151], v[192:195], v[126:129]
	v_mfma_f32_16x16x32_bf16 v[122:125], v[168:171], v[192:195], v[122:125]
	v_mfma_f32_16x16x32_bf16 v[110:113], v[148:151], v[208:211], v[110:113]
	v_mfma_f32_16x16x32_bf16 v[106:109], v[168:171], v[208:211], v[106:109]
	v_mfma_f32_16x16x32_bf16 v[94:97], v[148:151], v[220:223], v[94:97]
	v_mfma_f32_16x16x32_bf16 v[90:93], v[168:171], v[220:223], v[90:93]
	v_mfma_f32_16x16x32_bf16 v[78:81], v[148:151], v[228:231], v[78:81]
	v_mfma_f32_16x16x32_bf16 v[74:77], v[168:171], v[228:231], v[74:77]
	v_mfma_f32_16x16x32_bf16 v[118:121], v[172:175], v[188:191], 0
	v_mfma_f32_16x16x32_bf16 v[114:117], v[180:183], v[188:191], 0
	v_mfma_f32_16x16x32_bf16 v[102:105], v[172:175], v[196:199], 0
	v_mfma_f32_16x16x32_bf16 v[98:101], v[180:183], v[196:199], 0
	v_mfma_f32_16x16x32_bf16 v[86:89], v[172:175], v[216:219], 0
	v_mfma_f32_16x16x32_bf16 v[82:85], v[180:183], v[216:219], 0
	v_mfma_f32_16x16x32_bf16 v[70:73], v[172:175], v[224:227], 0
	v_mfma_f32_16x16x32_bf16 v[66:69], v[180:183], v[224:227], 0
	v_mfma_f32_16x16x32_bf16 v[118:121], v[176:179], v[192:195], v[118:121]
	v_mfma_f32_16x16x32_bf16 v[114:117], v[184:187], v[192:195], v[114:117]
	v_mfma_f32_16x16x32_bf16 v[102:105], v[176:179], v[208:211], v[102:105]
	v_mfma_f32_16x16x32_bf16 v[98:101], v[184:187], v[208:211], v[98:101]
	v_mfma_f32_16x16x32_bf16 v[86:89], v[176:179], v[220:223], v[86:89]
	v_mfma_f32_16x16x32_bf16 v[82:85], v[184:187], v[220:223], v[82:85]
	v_mfma_f32_16x16x32_bf16 v[70:73], v[176:179], v[228:231], v[70:73]
	v_mfma_f32_16x16x32_bf16 v[66:69], v[184:187], v[228:231], v[66:69]
	s_setprio 0
	s_barrier
	s_add_i32 s93, s93, s74
	s_mov_b32 m0, s93
	ds_read_b128 v[188:191], v167 offset:16384
	ds_read_b128 v[192:195], v167 offset:17408
	ds_read_b128 v[196:199], v167 offset:18432
	ds_read_b128 v[208:211], v167 offset:19456
	ds_read_b128 v[216:219], v167 offset:20480
	ds_read_b128 v[220:223], v167 offset:21504
	ds_read_b128 v[224:227], v167 offset:22528
	ds_read_b128 v[228:231], v167 offset:23552
	global_load_lds_dwordx4 v132, s[50:51]
	s_add_i32 m0, s93, 0x2000
	s_add_u32 s94, s50, 0x100000
	s_addc_u32 s95, s51, 0
	s_add_i32 s43, s43, s74
	global_load_lds_dwordx4 v136, s[50:51]
	s_mov_b32 m0, s43
	s_nop 0
	global_load_lds_dwordx4 v132, s[94:95]
	s_add_i32 m0, s43, 0x2000
	s_nop 0
	global_load_lds_dwordx4 v136, s[94:95]
	s_mov_b32 m0, s75
	s_nop 0
	global_load_lds_dwordx4 v130, s[52:53]
	s_mov_b32 m0, s76
	s_nop 0
	global_load_lds_dwordx4 v134, s[52:53]
	s_waitcnt vmcnt(8)
	s_waitcnt lgkmcnt(0)
	s_barrier
	s_setprio 1
	s_waitcnt lgkmcnt(0)
	v_mfma_f32_16x16x32_bf16 v[62:65], v[142:145], v[188:191], 0
	v_mfma_f32_16x16x32_bf16 v[58:61], v[158:161], v[188:191], 0
	v_mfma_f32_16x16x32_bf16 v[46:49], v[142:145], v[196:199], 0
	v_mfma_f32_16x16x32_bf16 v[42:45], v[158:161], v[196:199], 0
	v_mfma_f32_16x16x32_bf16 v[28:31], v[142:145], v[216:219], 0
	v_mfma_f32_16x16x32_bf16 v[24:27], v[158:161], v[216:219], 0
	v_mfma_f32_16x16x32_bf16 v[12:15], v[142:145], v[224:227], 0
	v_mfma_f32_16x16x32_bf16 v[8:11], v[158:161], v[224:227], 0
	v_mfma_f32_16x16x32_bf16 v[62:65], v[148:151], v[192:195], v[62:65]
	v_mfma_f32_16x16x32_bf16 v[58:61], v[168:171], v[192:195], v[58:61]
	v_mfma_f32_16x16x32_bf16 v[46:49], v[148:151], v[208:211], v[46:49]
	v_mfma_f32_16x16x32_bf16 v[42:45], v[168:171], v[208:211], v[42:45]
	v_mfma_f32_16x16x32_bf16 v[28:31], v[148:151], v[220:223], v[28:31]
	v_mfma_f32_16x16x32_bf16 v[24:27], v[168:171], v[220:223], v[24:27]
	v_mfma_f32_16x16x32_bf16 v[12:15], v[148:151], v[228:231], v[12:15]
	v_mfma_f32_16x16x32_bf16 v[8:11], v[168:171], v[228:231], v[8:11]
	v_mfma_f32_16x16x32_bf16 v[54:57], v[172:175], v[188:191], 0
	v_mfma_f32_16x16x32_bf16 v[50:53], v[180:183], v[188:191], 0
	v_mfma_f32_16x16x32_bf16 v[38:41], v[172:175], v[196:199], 0
	v_mfma_f32_16x16x32_bf16 v[34:37], v[180:183], v[196:199], 0
	v_mfma_f32_16x16x32_bf16 v[20:23], v[172:175], v[216:219], 0
	v_mfma_f32_16x16x32_bf16 v[16:19], v[180:183], v[216:219], 0
	v_mfma_f32_16x16x32_bf16 v[4:7], v[172:175], v[224:227], 0
	v_mfma_f32_16x16x32_bf16 v[0:3], v[180:183], v[224:227], 0
	v_mfma_f32_16x16x32_bf16 v[54:57], v[176:179], v[192:195], v[54:57]
	v_mfma_f32_16x16x32_bf16 v[50:53], v[184:187], v[192:195], v[50:53]
	v_mfma_f32_16x16x32_bf16 v[38:41], v[176:179], v[208:211], v[38:41]
	v_mfma_f32_16x16x32_bf16 v[34:37], v[184:187], v[208:211], v[34:37]
	v_mfma_f32_16x16x32_bf16 v[20:23], v[176:179], v[220:223], v[20:23]
	v_mfma_f32_16x16x32_bf16 v[16:19], v[184:187], v[220:223], v[16:19]
	v_mfma_f32_16x16x32_bf16 v[4:7], v[176:179], v[228:231], v[4:7]
	v_mfma_f32_16x16x32_bf16 v[0:3], v[184:187], v[228:231], v[0:3]
	s_setprio 0
	s_barrier
	s_branch .Lp3_2132
; #define PG8_STAGE(bufoff, gbase, voff) do { _Pragma("unroll") for (int _i = 0; _i < 2; ++_i) \
;         __builtin_amdgcn_global_load_lds((const unsigned*)((const char*)(gbase) + (voff)[_i]), (PG8_LAS unsigned*)(lds + (bufoff) + ldsw + _i * 8192), 16, 0, 0); } while (0)
; #define PG8_LDA(dst, b, h) do { _Pragma("unroll") for (int m = 0; m < 4; ++m) _Pragma("unroll") for (int k = 0; k < 2; ++k) dst[m][k] = *(const PG8_LAS bf16x8*)(lds + PG8_SA(b, h) + aoff + m * 2048 + k * 1024); } while (0)
; #define PG8_LDB(dst, b, h) do { _Pragma("unroll") for (int n = 0; n < 2; ++n) _Pragma("unroll") for (int k = 0; k < 2; ++k) dst[n][k] = *(const PG8_LAS bf16x8*)(lds + PG8_SB(b, h) + boff + n * 2048 + k * 1024); } while (0)
; #define PG8_WAIT_V(n) asm volatile("s_waitcnt vmcnt(" #n ")" ::: "memory")
; #define PG8_WAIT_L(n) asm volatile("s_waitcnt lgkmcnt(" #n ")" ::: "memory")
; #define PG8_BAR __builtin_amdgcn_s_barrier()
; #define PG8_SCHED __builtin_amdgcn_sched_barrier(0)
; template <class Epi, bool ALIGN_EPI = true>
; __device__ __forceinline__ void gemm_phase(PG8_LAS unsigned char* lds, const Gemm g, const StaticOrder& S, const Epi& E) {
;     ...
;         for (int t = 0; t < nt; t += 2) {
;             const bool last = (t == nt - 2);
;             const char* a1 = cA + (size_t)(t + 1) * kstep;
;             const char* a2 = last ? nA : cA + (size_t)(t + 2) * kstep; const char* b2 = last ? nB : cB + (size_t)(t + 2) * kstep;
;             const char* a3 = a2 + kstep; const char* b3 = b2 + kstep;
;             PG8_LDB(B0, 0, 0); PG8_LDB(B1, 0, 1); PG8_SCHED; PG8_LDA(At, 0, 0); PG8_STAGE(PG8_SA(1, 1), a1 + hstepA, voffA);
;             PG8_WAIT_V(8); PG8_WAIT_L(0); PG8_BAR; PG8_MMA(0, 0, At, B0); PG8_MMA(0, 1, At, B1); PG8_BAR; PG8_SCHED;
;             PG8_LDA(At, 0, 1); PG8_STAGE(PG8_SB(0, 0), b2, voffB); PG8_STAGE(PG8_SB(0, 1), b2 + hstepB, voffB); PG8_STAGE(PG8_SA(0, 0), a2, voffA);
;             PG8_WAIT_V(8); PG8_WAIT_L(0); PG8_BAR; PG8_MMA(1, 0, At, B0); PG8_MMA(1, 1, At, B1); PG8_BAR; PG8_SCHED;
.Lrot_2132:
	ds_read_b128 v[142:145], v32
	ds_read_b128 v[148:151], v32 offset:1024
	ds_read_b128 v[158:161], v32 offset:2048
	ds_read_b128 v[168:171], v32 offset:3072
	v_add_u32_e32 v32, s43, v165
	ds_read_b128 v[172:175], v32
	ds_read_b128 v[176:179], v32 offset:1024
	ds_read_b128 v[180:183], v32 offset:2048
	ds_read_b128 v[184:187], v32 offset:3072
	s_add_i32 m0, s75, 0xc000
	ds_read_b128 v[188:191], v167
	ds_read_b128 v[192:195], v167 offset:1024
	ds_read_b128 v[196:199], v167 offset:2048
	ds_read_b128 v[208:211], v167 offset:3072
	ds_read_b128 v[216:219], v167 offset:4096
	ds_read_b128 v[220:223], v167 offset:5120
	ds_read_b128 v[224:227], v167 offset:6144
	ds_read_b128 v[228:231], v167 offset:7168
	global_load_lds_dwordx4 v138, s[48:49]
	s_add_i32 m0, s75, 0xe000
	s_nop 0
	global_load_lds_dwordx4 v140, s[48:49]
	s_waitcnt vmcnt(8)
	s_waitcnt lgkmcnt(0)
	s_barrier
	s_setprio 1
	s_waitcnt lgkmcnt(0)
	v_mfma_f32_16x16x32_bf16 v[126:129], v[142:145], v[188:191], v[126:129]
	v_mfma_f32_16x16x32_bf16 v[122:125], v[158:161], v[188:191], v[122:125]
	v_mfma_f32_16x16x32_bf16 v[110:113], v[142:145], v[196:199], v[110:113]
	v_mfma_f32_16x16x32_bf16 v[106:109], v[158:161], v[196:199], v[106:109]
	v_mfma_f32_16x16x32_bf16 v[94:97], v[142:145], v[216:219], v[94:97]
	v_mfma_f32_16x16x32_bf16 v[90:93], v[158:161], v[216:219], v[90:93]
	v_mfma_f32_16x16x32_bf16 v[78:81], v[142:145], v[224:227], v[78:81]
	v_mfma_f32_16x16x32_bf16 v[74:77], v[158:161], v[224:227], v[74:77]
	v_mfma_f32_16x16x32_bf16 v[126:129], v[148:151], v[192:195], v[126:129]
	v_mfma_f32_16x16x32_bf16 v[122:125], v[168:171], v[192:195], v[122:125]
	v_mfma_f32_16x16x32_bf16 v[110:113], v[148:151], v[208:211], v[110:113]
	v_mfma_f32_16x16x32_bf16 v[106:109], v[168:171], v[208:211], v[106:109]
	v_mfma_f32_16x16x32_bf16 v[94:97], v[148:151], v[220:223], v[94:97]
	v_mfma_f32_16x16x32_bf16 v[90:93], v[168:171], v[220:223], v[90:93]
	v_mfma_f32_16x16x32_bf16 v[78:81], v[148:151], v[228:231], v[78:81]
	v_mfma_f32_16x16x32_bf16 v[74:77], v[168:171], v[228:231], v[74:77]
	v_mfma_f32_16x16x32_bf16 v[118:121], v[172:175], v[188:191], v[118:121]
	v_mfma_f32_16x16x32_bf16 v[114:117], v[180:183], v[188:191], v[114:117]
	v_mfma_f32_16x16x32_bf16 v[102:105], v[172:175], v[196:199], v[102:105]
	v_mfma_f32_16x16x32_bf16 v[98:101], v[180:183], v[196:199], v[98:101]
	v_mfma_f32_16x16x32_bf16 v[86:89], v[172:175], v[216:219], v[86:89]
	v_mfma_f32_16x16x32_bf16 v[82:85], v[180:183], v[216:219], v[82:85]
	v_mfma_f32_16x16x32_bf16 v[70:73], v[172:175], v[224:227], v[70:73]
	v_mfma_f32_16x16x32_bf16 v[66:69], v[180:183], v[224:227], v[66:69]
	v_mfma_f32_16x16x32_bf16 v[118:121], v[176:179], v[192:195], v[118:121]
	v_mfma_f32_16x16x32_bf16 v[114:117], v[184:187], v[192:195], v[114:117]
	v_mfma_f32_16x16x32_bf16 v[102:105], v[176:179], v[208:211], v[102:105]
	v_mfma_f32_16x16x32_bf16 v[98:101], v[184:187], v[208:211], v[98:101]
	v_mfma_f32_16x16x32_bf16 v[86:89], v[176:179], v[220:223], v[86:89]
	v_mfma_f32_16x16x32_bf16 v[82:85], v[184:187], v[220:223], v[82:85]
	v_mfma_f32_16x16x32_bf16 v[70:73], v[176:179], v[228:231], v[70:73]
	v_mfma_f32_16x16x32_bf16 v[66:69], v[184:187], v[228:231], v[66:69]
	s_setprio 0
	s_barrier
	s_add_i32 s93, s93, s74
	s_mov_b32 m0, s93
	ds_read_b128 v[188:191], v167 offset:16384
	ds_read_b128 v[192:195], v167 offset:17408
	ds_read_b128 v[196:199], v167 offset:18432
	ds_read_b128 v[208:211], v167 offset:19456
	ds_read_b128 v[216:219], v167 offset:20480
	ds_read_b128 v[220:223], v167 offset:21504
	ds_read_b128 v[224:227], v167 offset:22528
	ds_read_b128 v[228:231], v167 offset:23552
	global_load_lds_dwordx4 v132, s[50:51]
	s_add_i32 m0, s93, 0x2000
	s_add_u32 s94, s50, 0x100000
	s_addc_u32 s95, s51, 0
	s_add_i32 s43, s43, s74
	global_load_lds_dwordx4 v136, s[50:51]
	s_mov_b32 m0, s43
	s_nop 0
	global_load_lds_dwordx4 v132, s[94:95]
	s_add_i32 m0, s43, 0x2000
	s_nop 0
	global_load_lds_dwordx4 v136, s[94:95]
	s_mov_b32 m0, s75
	s_nop 0
	global_load_lds_dwordx4 v130, s[52:53]
	s_mov_b32 m0, s76
	s_nop 0
	global_load_lds_dwordx4 v134, s[52:53]
	s_waitcnt vmcnt(8)
	s_waitcnt lgkmcnt(0)
	s_barrier
	s_setprio 1
	s_waitcnt lgkmcnt(0)
	v_mfma_f32_16x16x32_bf16 v[62:65], v[142:145], v[188:191], v[62:65]
	v_mfma_f32_16x16x32_bf16 v[58:61], v[158:161], v[188:191], v[58:61]
	v_mfma_f32_16x16x32_bf16 v[46:49], v[142:145], v[196:199], v[46:49]
	v_mfma_f32_16x16x32_bf16 v[42:45], v[158:161], v[196:199], v[42:45]
	v_mfma_f32_16x16x32_bf16 v[28:31], v[142:145], v[216:219], v[28:31]
	v_mfma_f32_16x16x32_bf16 v[24:27], v[158:161], v[216:219], v[24:27]
	v_mfma_f32_16x16x32_bf16 v[12:15], v[142:145], v[224:227], v[12:15]
	v_mfma_f32_16x16x32_bf16 v[8:11], v[158:161], v[224:227], v[8:11]
	v_mfma_f32_16x16x32_bf16 v[62:65], v[148:151], v[192:195], v[62:65]
	v_mfma_f32_16x16x32_bf16 v[58:61], v[168:171], v[192:195], v[58:61]
	v_mfma_f32_16x16x32_bf16 v[46:49], v[148:151], v[208:211], v[46:49]
	v_mfma_f32_16x16x32_bf16 v[42:45], v[168:171], v[208:211], v[42:45]
	v_mfma_f32_16x16x32_bf16 v[28:31], v[148:151], v[220:223], v[28:31]
	v_mfma_f32_16x16x32_bf16 v[24:27], v[168:171], v[220:223], v[24:27]
	v_mfma_f32_16x16x32_bf16 v[12:15], v[148:151], v[228:231], v[12:15]
	v_mfma_f32_16x16x32_bf16 v[8:11], v[168:171], v[228:231], v[8:11]
	v_mfma_f32_16x16x32_bf16 v[54:57], v[172:175], v[188:191], v[54:57]
	v_mfma_f32_16x16x32_bf16 v[50:53], v[180:183], v[188:191], v[50:53]
	v_mfma_f32_16x16x32_bf16 v[38:41], v[172:175], v[196:199], v[38:41]
	v_mfma_f32_16x16x32_bf16 v[34:37], v[180:183], v[196:199], v[34:37]
	v_mfma_f32_16x16x32_bf16 v[20:23], v[172:175], v[216:219], v[20:23]
	v_mfma_f32_16x16x32_bf16 v[16:19], v[180:183], v[216:219], v[16:19]
	v_mfma_f32_16x16x32_bf16 v[4:7], v[172:175], v[224:227], v[4:7]
	v_mfma_f32_16x16x32_bf16 v[0:3], v[180:183], v[224:227], v[0:3]
	v_mfma_f32_16x16x32_bf16 v[54:57], v[176:179], v[192:195], v[54:57]
	v_mfma_f32_16x16x32_bf16 v[50:53], v[184:187], v[192:195], v[50:53]
	v_mfma_f32_16x16x32_bf16 v[38:41], v[176:179], v[208:211], v[38:41]
	v_mfma_f32_16x16x32_bf16 v[34:37], v[184:187], v[208:211], v[34:37]
	v_mfma_f32_16x16x32_bf16 v[20:23], v[176:179], v[220:223], v[20:23]
	v_mfma_f32_16x16x32_bf16 v[16:19], v[184:187], v[220:223], v[16:19]
	v_mfma_f32_16x16x32_bf16 v[4:7], v[176:179], v[228:231], v[4:7]
	v_mfma_f32_16x16x32_bf16 v[0:3], v[184:187], v[228:231], v[0:3]
	s_setprio 0
	s_barrier
; #define PG8_STAGE(bufoff, gbase, voff) do { _Pragma("unroll") for (int _i = 0; _i < 2; ++_i) \
;         __builtin_amdgcn_global_load_lds((const unsigned*)((const char*)(gbase) + (voff)[_i]), (PG8_LAS unsigned*)(lds + (bufoff) + ldsw + _i * 8192), 16, 0, 0); } while (0)
; #define PG8_LDA(dst, b, h) do { _Pragma("unroll") for (int m = 0; m < 4; ++m) _Pragma("unroll") for (int k = 0; k < 2; ++k) dst[m][k] = *(const PG8_LAS bf16x8*)(lds + PG8_SA(b, h) + aoff + m * 2048 + k * 1024); } while (0)
; #define PG8_LDB(dst, b, h) do { _Pragma("unroll") for (int n = 0; n < 2; ++n) _Pragma("unroll") for (int k = 0; k < 2; ++k) dst[n][k] = *(const PG8_LAS bf16x8*)(lds + PG8_SB(b, h) + boff + n * 2048 + k * 1024); } while (0)
; #define PG8_WAIT_V(n) asm volatile("s_waitcnt vmcnt(" #n ")" ::: "memory")
; #define PG8_WAIT_L(n) asm volatile("s_waitcnt lgkmcnt(" #n ")" ::: "memory")
; #define PG8_BAR __builtin_amdgcn_s_barrier()
; #define PG8_SCHED __builtin_amdgcn_sched_barrier(0)
; template <class Epi, bool ALIGN_EPI = true>
; __device__ __forceinline__ void gemm_phase(PG8_LAS unsigned char* lds, const Gemm g, const StaticOrder& S, const Epi& E) {
;     ...
;             PG8_LDB(B0, 1, 0); PG8_LDB(B1, 1, 1); PG8_SCHED; PG8_LDA(At, 1, 0); PG8_STAGE(PG8_SA(0, 1), a2 + hstepA, voffA);
;             PG8_WAIT_V(8); PG8_WAIT_L(0); PG8_BAR; PG8_MMA(0, 0, At, B0); PG8_MMA(0, 1, At, B1); PG8_BAR; PG8_SCHED;
.Lp3_2132:
	s_add_i32 s43, 0, 0x18000
	v_add_u32_e32 v32, s43, v165
	s_add_i32 s93, 0, 0x1c000
	ds_read_b128 v[142:145], v32
	ds_read_b128 v[148:151], v32 offset:1024
	ds_read_b128 v[158:161], v32 offset:2048
	ds_read_b128 v[168:171], v32 offset:3072
	v_add_u32_e32 v32, s93, v165
	ds_read_b128 v[172:175], v32
	ds_read_b128 v[176:179], v32 offset:1024
	ds_read_b128 v[180:183], v32 offset:2048
	ds_read_b128 v[184:187], v32 offset:3072
	s_add_u32 s52, s52, 0x100000
	s_addc_u32 s53, s53, 0
	s_mov_b32 m0, s77
	ds_read_b128 v[188:191], v167 offset:32768
	ds_read_b128 v[192:195], v167 offset:33792
	ds_read_b128 v[196:199], v167 offset:34816
	ds_read_b128 v[208:211], v167 offset:35840
	ds_read_b128 v[216:219], v167 offset:36864
	ds_read_b128 v[220:223], v167 offset:37888
	ds_read_b128 v[224:227], v167 offset:38912
	ds_read_b128 v[228:231], v167 offset:39936
	global_load_lds_dwordx4 v130, s[52:53]
	s_mov_b32 m0, s82
	s_nop 0
	global_load_lds_dwordx4 v134, s[52:53]
	s_waitcnt vmcnt(8)
	s_waitcnt lgkmcnt(0)
	s_barrier
	s_setprio 1
	s_waitcnt lgkmcnt(0)
	v_mfma_f32_16x16x32_bf16 v[126:129], v[142:145], v[188:191], v[126:129]
	v_mfma_f32_16x16x32_bf16 v[122:125], v[158:161], v[188:191], v[122:125]
	v_mfma_f32_16x16x32_bf16 v[110:113], v[142:145], v[196:199], v[110:113]
	v_mfma_f32_16x16x32_bf16 v[106:109], v[158:161], v[196:199], v[106:109]
	v_mfma_f32_16x16x32_bf16 v[94:97], v[142:145], v[216:219], v[94:97]
	v_mfma_f32_16x16x32_bf16 v[90:93], v[158:161], v[216:219], v[90:93]
	v_mfma_f32_16x16x32_bf16 v[78:81], v[142:145], v[224:227], v[78:81]
	v_mfma_f32_16x16x32_bf16 v[74:77], v[158:161], v[224:227], v[74:77]
	v_mfma_f32_16x16x32_bf16 v[126:129], v[148:151], v[192:195], v[126:129]
	v_mfma_f32_16x16x32_bf16 v[122:125], v[168:171], v[192:195], v[122:125]
	v_mfma_f32_16x16x32_bf16 v[110:113], v[148:151], v[208:211], v[110:113]
	v_mfma_f32_16x16x32_bf16 v[106:109], v[168:171], v[208:211], v[106:109]
	v_mfma_f32_16x16x32_bf16 v[94:97], v[148:151], v[220:223], v[94:97]
	v_mfma_f32_16x16x32_bf16 v[90:93], v[168:171], v[220:223], v[90:93]
	v_mfma_f32_16x16x32_bf16 v[78:81], v[148:151], v[228:231], v[78:81]
	v_mfma_f32_16x16x32_bf16 v[74:77], v[168:171], v[228:231], v[74:77]
	v_mfma_f32_16x16x32_bf16 v[118:121], v[172:175], v[188:191], v[118:121]
	v_mfma_f32_16x16x32_bf16 v[114:117], v[180:183], v[188:191], v[114:117]
	v_mfma_f32_16x16x32_bf16 v[102:105], v[172:175], v[196:199], v[102:105]
	v_mfma_f32_16x16x32_bf16 v[98:101], v[180:183], v[196:199], v[98:101]
	v_mfma_f32_16x16x32_bf16 v[86:89], v[172:175], v[216:219], v[86:89]
	v_mfma_f32_16x16x32_bf16 v[82:85], v[180:183], v[216:219], v[82:85]
	v_mfma_f32_16x16x32_bf16 v[70:73], v[172:175], v[224:227], v[70:73]
	v_mfma_f32_16x16x32_bf16 v[66:69], v[180:183], v[224:227], v[66:69]
	v_mfma_f32_16x16x32_bf16 v[118:121], v[176:179], v[192:195], v[118:121]
	v_mfma_f32_16x16x32_bf16 v[114:117], v[184:187], v[192:195], v[114:117]
	v_mfma_f32_16x16x32_bf16 v[102:105], v[176:179], v[208:211], v[102:105]
	v_mfma_f32_16x16x32_bf16 v[98:101], v[184:187], v[208:211], v[98:101]
	v_mfma_f32_16x16x32_bf16 v[86:89], v[176:179], v[220:223], v[86:89]
	v_mfma_f32_16x16x32_bf16 v[82:85], v[184:187], v[220:223], v[82:85]
	v_mfma_f32_16x16x32_bf16 v[70:73], v[176:179], v[228:231], v[70:73]
	v_mfma_f32_16x16x32_bf16 v[66:69], v[184:187], v[228:231], v[66:69]
	s_setprio 0
	s_barrier
; #define PG8_STAGE(bufoff, gbase, voff) do { _Pragma("unroll") for (int _i = 0; _i < 2; ++_i) \
;         __builtin_amdgcn_global_load_lds((const unsigned*)((const char*)(gbase) + (voff)[_i]), (PG8_LAS unsigned*)(lds + (bufoff) + ldsw + _i * 8192), 16, 0, 0); } while (0)
; #define PG8_LDA(dst, b, h) do { _Pragma("unroll") for (int m = 0; m < 4; ++m) _Pragma("unroll") for (int k = 0; k < 2; ++k) dst[m][k] = *(const PG8_LAS bf16x8*)(lds + PG8_SA(b, h) + aoff + m * 2048 + k * 1024); } while (0)
; #define PG8_WAIT_V(n) asm volatile("s_waitcnt vmcnt(" #n ")" ::: "memory")
; #define PG8_WAIT_L(n) asm volatile("s_waitcnt lgkmcnt(" #n ")" ::: "memory")
; #define PG8_BAR __builtin_amdgcn_s_barrier()
; #define PG8_SCHED __builtin_amdgcn_sched_barrier(0)
; template <class Epi, bool ALIGN_EPI = true>
; __device__ __forceinline__ void gemm_phase(PG8_LAS unsigned char* lds, const Gemm g, const StaticOrder& S, const Epi& E) {
;     ...
;         for (int t = 0; t < nt; t += 2) {
;             const bool last = (t == nt - 2);
;             const char* a1 = cA + (size_t)(t + 1) * kstep;
;             const char* a2 = last ? nA : cA + (size_t)(t + 2) * kstep; const char* b2 = last ? nB : cB + (size_t)(t + 2) * kstep;
;             const char* a3 = a2 + kstep; const char* b3 = b2 + kstep;
;     ...
;             PG8_LDA(At, 1, 1); PG8_STAGE(PG8_SB(1, 0), b3, voffB); PG8_STAGE(PG8_SB(1, 1), b3 + hstepB, voffB); PG8_STAGE(PG8_SA(1, 0), a3, voffA);
;             PG8_WAIT_V(8); PG8_WAIT_L(0); PG8_BAR; PG8_MMA(1, 0, At, B0); PG8_MMA(1, 1, At, B1); PG8_BAR; PG8_SCHED;
	s_add_i32 s43, s43, s74
	s_mov_b32 m0, s43
	ds_read_b128 v[188:191], v167 offset:49152
	ds_read_b128 v[192:195], v167 offset:50176
	ds_read_b128 v[196:199], v167 offset:51200
	ds_read_b128 v[208:211], v167 offset:52224
	ds_read_b128 v[216:219], v167 offset:53248
	ds_read_b128 v[220:223], v167 offset:54272
	ds_read_b128 v[224:227], v167 offset:55296
	ds_read_b128 v[228:231], v167 offset:56320
	s_add_u32 s98, s50, s60
	s_addc_u32 s99, s51, s61
	global_load_lds_dwordx4 v132, s[98:99]
	s_add_i32 m0, s43, 0x2000
	s_add_u32 s50, s50, 0x100080
	s_addc_u32 s51, s51, 0
	s_add_i32 s43, s93, s74
	s_add_u32 s98, s50, s60
	s_addc_u32 s99, s51, s61
	s_add_u32 s98, s98, 0xffefff80
	s_addc_u32 s99, s99, -1
	global_load_lds_dwordx4 v136, s[98:99]
	s_mov_b32 m0, s43
	s_nop 0
	global_load_lds_dwordx4 v132, s[50:51]
	s_add_i32 m0, s43, 0x2000
	s_nop 0
	global_load_lds_dwordx4 v136, s[50:51]
	s_mov_b32 m0, s83
	s_nop 0
	s_add_u32 s98, s52, s60
	s_addc_u32 s99, s53, s61
	s_add_u32 s98, s98, 0xfff00000
	s_addc_u32 s99, s99, -1
	global_load_lds_dwordx4 v130, s[98:99]
	s_mov_b32 m0, s85
	s_nop 0
	s_add_u32 s98, s52, s60
	s_addc_u32 s99, s53, s61
	s_add_u32 s98, s98, 0xfff00000
	s_addc_u32 s99, s99, -1
	global_load_lds_dwordx4 v134, s[98:99]
	s_add_i32 s41, s41, 2
	s_add_u32 s48, s48, 0x100
	s_addc_u32 s49, s49, 0
	s_add_u32 s7, s7, 0x100
	s_addc_u32 s9, s9, 0
	s_add_u32 s43, s48, 0xfff00080
	s_addc_u32 s50, s49, -1
	s_add_i32 s93, 0, 0x10000
	s_cmp_eq_u32 s41, 60
	s_cselect_b32 s53, s45, s50
	s_cselect_b32 s52, s44, s43
	v_add_u32_e32 v32, s93, v165
	s_cselect_b32 s51, s47, s9
	s_cselect_b32 s50, s46, s7
	s_add_i32 s43, 0, 0x14000
	s_cmp_gt_u32 s41, 61
	s_waitcnt vmcnt(8)
	s_waitcnt lgkmcnt(0)
	s_barrier
	s_setprio 1
	s_waitcnt lgkmcnt(0)
	v_mfma_f32_16x16x32_bf16 v[62:65], v[142:145], v[188:191], v[62:65]
	v_mfma_f32_16x16x32_bf16 v[58:61], v[158:161], v[188:191], v[58:61]
	v_mfma_f32_16x16x32_bf16 v[46:49], v[142:145], v[196:199], v[46:49]
	v_mfma_f32_16x16x32_bf16 v[42:45], v[158:161], v[196:199], v[42:45]
	v_mfma_f32_16x16x32_bf16 v[28:31], v[142:145], v[216:219], v[28:31]
	v_mfma_f32_16x16x32_bf16 v[24:27], v[158:161], v[216:219], v[24:27]
	v_mfma_f32_16x16x32_bf16 v[12:15], v[142:145], v[224:227], v[12:15]
	v_mfma_f32_16x16x32_bf16 v[8:11], v[158:161], v[224:227], v[8:11]
	v_mfma_f32_16x16x32_bf16 v[62:65], v[148:151], v[192:195], v[62:65]
	v_mfma_f32_16x16x32_bf16 v[58:61], v[168:171], v[192:195], v[58:61]
	v_mfma_f32_16x16x32_bf16 v[46:49], v[148:151], v[208:211], v[46:49]
	v_mfma_f32_16x16x32_bf16 v[42:45], v[168:171], v[208:211], v[42:45]
	v_mfma_f32_16x16x32_bf16 v[28:31], v[148:151], v[220:223], v[28:31]
	v_mfma_f32_16x16x32_bf16 v[24:27], v[168:171], v[220:223], v[24:27]
	v_mfma_f32_16x16x32_bf16 v[12:15], v[148:151], v[228:231], v[12:15]
	v_mfma_f32_16x16x32_bf16 v[8:11], v[168:171], v[228:231], v[8:11]
	v_mfma_f32_16x16x32_bf16 v[54:57], v[172:175], v[188:191], v[54:57]
	v_mfma_f32_16x16x32_bf16 v[50:53], v[180:183], v[188:191], v[50:53]
	v_mfma_f32_16x16x32_bf16 v[38:41], v[172:175], v[196:199], v[38:41]
	v_mfma_f32_16x16x32_bf16 v[34:37], v[180:183], v[196:199], v[34:37]
	v_mfma_f32_16x16x32_bf16 v[20:23], v[172:175], v[216:219], v[20:23]
	v_mfma_f32_16x16x32_bf16 v[16:19], v[180:183], v[216:219], v[16:19]
	v_mfma_f32_16x16x32_bf16 v[4:7], v[172:175], v[224:227], v[4:7]
	v_mfma_f32_16x16x32_bf16 v[0:3], v[180:183], v[224:227], v[0:3]
	v_mfma_f32_16x16x32_bf16 v[54:57], v[176:179], v[192:195], v[54:57]
	v_mfma_f32_16x16x32_bf16 v[50:53], v[184:187], v[192:195], v[50:53]
	v_mfma_f32_16x16x32_bf16 v[38:41], v[176:179], v[208:211], v[38:41]
	v_mfma_f32_16x16x32_bf16 v[34:37], v[184:187], v[208:211], v[34:37]
	v_mfma_f32_16x16x32_bf16 v[20:23], v[176:179], v[220:223], v[20:23]
	v_mfma_f32_16x16x32_bf16 v[16:19], v[184:187], v[220:223], v[16:19]
	v_mfma_f32_16x16x32_bf16 v[4:7], v[176:179], v[228:231], v[4:7]
	v_mfma_f32_16x16x32_bf16 v[0:3], v[184:187], v[228:231], v[0:3]
	s_setprio 0
	s_barrier
	s_cbranch_scc0 .Lrot_2132
	s_and_b64 vcc, exec, s[38:39]
	s_cbranch_vccz .LBB0_2135
	s_barrier
